# fused up-GEMM epilogue reads scale-shift, bias and conv weights from LDS tables prefetched by LDS-DMA for the next unit (double-buffered)
# speedup vs baseline: 1.0160x; 1.0015x over previous
.LBB0_818:
	s_add_u32 s33, s70, 0xa00000
	s_mov_b64 s[2:3], s[82:83]
	s_addc_u32 s82, s71, 0
	s_cmpk_lt_i32 s84, 0x2c0
	s_cselect_b64 s[4:5], -1, 0
	s_ashr_i32 s85, s84, 31
	s_lshr_b32 s0, s85, 29
	s_add_i32 s0, s84, s0
	s_ashr_i32 s1, s0, 3
	s_and_b32 s0, s0, -8
	s_sub_i32 s0, s84, s0
	s_cmp_lt_i32 s0, 0
	v_writelane_b32 v254, s1, 61
	s_cselect_b64 s[6:7], -1, 0
	v_writelane_b32 v254, s6, 62
	s_cmp_gt_i32 s0, -1
	s_mov_b32 s18, s2
	v_writelane_b32 v254, s7, 63
	v_writelane_b32 v254, s0, 51
	s_cselect_b64 s[0:1], -1, 0
	s_ashr_i32 s19, s2, 31
	v_writelane_b32 v255, s0, 0
	s_cmpk_eq_i32 s2, 0x100
	v_cmp_eq_u32_e64 s[2:3], 0, v230
	v_writelane_b32 v255, s1, 1
	s_cselect_b64 s[0:1], -1, 0
	s_cmpk_gt_u32 s84, 0xbf
	s_cselect_b64 s[6:7], -1, 0
	s_and_b64 s[8:9], s[6:7], s[0:1]
	s_lshl_b32 s1, s84, 3
	s_add_i32 s83, s1, 0xfffffa00
	s_cmp_gt_i32 s72, 7
	v_writelane_b32 v254, s2, 59
	s_cselect_b64 s[6:7], -1, 0
	s_cmp_lt_i32 s73, 8
	v_cndmask_b32_e64 v0, 0, 1, s[4:5]
	v_writelane_b32 v254, s3, 60
	s_cselect_b64 s[12:13], -1, 0
	v_cmp_ne_u32_e64 s[2:3], 1, v0
	s_or_b64 s[6:7], s[6:7], s[12:13]
	s_and_b64 vcc, exec, s[6:7]
	v_writelane_b32 v255, s2, 2
	s_nop 1
	v_writelane_b32 v255, s3, 3
	s_cbranch_vccnz .LBB0_899
	v_readlane_b32 s2, v255, 2
	v_mov_b32_e32 v14, v230
	v_readlane_b32 s3, v255, 3
	s_and_b64 vcc, exec, s[2:3]
	v_readfirstlane_b32 s5, v14
	s_cbranch_vccnz .LBB0_834
	v_lshlrev_b32_e32 v0, 4, v14
	s_waitcnt lgkmcnt(0)
	v_add_u32_e32 v1, 0x2000, v0
	v_ashrrev_i32_e32 v2, 31, v1
	v_lshrrev_b32_e32 v2, 22, v2
	v_add_u32_e32 v2, v1, v2
	v_ashrrev_i32_e32 v8, 10, v2
	v_mul_i32_i24_e32 v2, 0x400, v8
	v_sub_u32_e32 v1, v1, v2
	v_lshrrev_b32_e32 v2, 4, v1
	v_bitop3_b32 v1, v2, v1, 32 bitop3:0x6c
	v_ashrrev_i32_e32 v2, 31, v1
	v_lshrrev_b32_e32 v2, 26, v2
	v_add_u32_e32 v2, v1, v2
	v_lshlrev_b32_e32 v3, 3, v8
	v_ashrrev_i32_e32 v9, 6, v2
	v_and_b32_e32 v3, -16, v3
	v_add_u32_e32 v3, v9, v3
	v_and_b32_e32 v4, 3, v9
	s_mov_b32 s4, 0x1fffe0
	v_lshrrev_b32_e32 v5, 2, v3
	v_lshlrev_b32_e32 v6, 1, v3
	v_and_b32_e32 v2, 0xc0, v2
	v_and_or_b32 v4, v3, s4, v4
	v_and_b32_e32 v5, 4, v5
	v_and_b32_e32 v6, 24, v6
	v_sub_u32_e32 v1, v1, v2
	v_mov_b32_e32 v2, 1
	v_or3_b32 v4, v4, v5, v6
	v_lshlrev_b32_e32 v5, 5, v8
	v_ashrrev_i16_sdwa v1, v2, sext(v1) dst_sel:DWORD dst_unused:UNUSED_PAD src0_sel:DWORD src1_sel:BYTE_0
	v_and_b32_e32 v5, 32, v5
	v_bfe_i32 v10, v1, 0, 16
	v_add_lshl_u32 v1, v5, v10, 1
	v_lshl_add_u32 v144, v4, 11, v1
	v_lshl_add_u32 v146, v3, 11, v1
	v_lshrrev_b32_e32 v248, 11, v146
	v_and_b32_e32 v249, 0x7ff, v146
	v_and_b32_e32 v250, 15, v248
	v_lshlrev_b32_e32 v250, 2, v250
	v_bfe_u32 v251, v248, 4, 2
	v_and_or_b32 v248, v248, 64, v250
	v_or_b32_e32 v248, v248, v251
	v_lshl_or_b32 v146, v248, 11, v249
	v_bfe_i32 v1, v14, 27, 1
	v_lshrrev_b32_e32 v1, 22, v1
	v_add_u32_e32 v1, v0, v1
	v_and_b32_e32 v1, 0xfffffc00, v1
	v_sub_u32_e32 v0, v0, v1
	v_lshrrev_b32_e32 v1, 4, v0
	v_ashrrev_i32_e32 v3, 31, v14
	v_bitop3_b32 v0, v1, v0, 32 bitop3:0x6c
	v_lshrrev_b32_e32 v3, 26, v3
	v_ashrrev_i32_e32 v1, 31, v0
	v_add_u32_e32 v3, v14, v3
	s_add_u32 s0, s70, 0x3b00000
	v_lshrrev_b32_e32 v1, 26, v1
	v_ashrrev_i32_e32 v12, 6, v3
	s_addc_u32 s20, s71, 0
	s_ashr_i32 s6, s5, 6
	v_add_u32_e32 v1, v0, v1
	v_lshlrev_b32_e32 v3, 3, v12
	v_readlane_b32 s2, v254, 62
	s_ashr_i32 s7, s5, 8
	s_lshl_b32 s21, s6, 10
	v_ashrrev_i32_e32 v11, 6, v1
	v_and_b32_e32 v3, -16, v3
	v_readlane_b32 s3, v254, 63
	v_add_u32_e32 v3, v11, v3
	v_and_b32_e32 v4, 3, v11
	s_movk_i32 s30, 0x59
	s_and_b64 s[12:13], s[2:3], exec
	v_and_or_b32 v4, v3, s4, v4
	s_cselect_b32 s4, s30, 0x58
	v_readlane_b32 s2, v254, 51
	s_mul_i32 s4, s4, s2
	v_readlane_b32 s2, v254, 61
	s_add_i32 s4, s4, s2
	s_mul_hi_i32 s12, s4, 0x2e8ba2e9
	s_lshr_b32 s13, s12, 31
	s_ashr_i32 s12, s12, 5
	s_add_i32 s12, s12, s13
	s_lshl_b32 s13, s12, 3
	s_mulk_i32 s12, 0xb0
	s_sub_i32 s12, s4, s12
	s_bfe_u32 s4, s12, 0x3001c
	s_add_i32 s14, s12, s4
	s_sext_i32_i16 s4, s14
	s_and_b32 s14, s14, 0xfff8
	s_sub_i32 s12, s12, s14
	s_sext_i32_i16 s12, s12
	v_lshrrev_b32_e32 v5, 2, v3
	v_lshlrev_b32_e32 v6, 1, v3
	v_and_b32_e32 v1, 0xc0, v1
	s_lshr_b32 s4, s4, 3
	s_add_i32 s88, s13, s12
	v_and_b32_e32 v5, 4, v5
	v_and_b32_e32 v6, 24, v6
	v_sub_u32_e32 v0, v0, v1
	s_ashr_i32 s89, s88, 31
	s_bfe_i64 s[14:15], s[4:5], 0x100000
	v_or3_b32 v4, v4, v5, v6
	v_lshlrev_b32_e32 v5, 5, v12
	v_ashrrev_i16_sdwa v0, v2, sext(v0) dst_sel:DWORD dst_unused:UNUSED_PAD src0_sel:DWORD src1_sel:BYTE_0
	s_lshl_b64 s[12:13], s[88:89], 19
	s_lshl_b64 s[14:15], s[14:15], 18
	v_and_b32_e32 v5, 32, v5
	v_bfe_i32 v13, v0, 0, 16
	s_add_u32 s92, s33, s14
	v_add_lshl_u32 v0, v5, v13, 1
	s_addc_u32 s93, s82, s15
	s_add_i32 s31, s21, 0
	v_lshl_add_u32 v148, v4, 11, v0
	s_add_i32 m0, s31, 0x10000
	v_lshl_add_u32 v150, v3, 11, v0
	v_lshrrev_b32_e32 v248, 11, v150
	v_and_b32_e32 v249, 0x7ff, v150
	v_and_b32_e32 v250, 15, v248
	v_lshlrev_b32_e32 v250, 2, v250
	v_bfe_u32 v251, v248, 4, 2
	v_and_or_b32 v248, v248, 64, v250
	v_or_b32_e32 v248, v248, v251
	v_lshl_or_b32 v150, v248, 11, v249
	global_load_lds_dwordx4 v148, s[92:93]
	s_add_i32 m0, s31, 0x12000
	s_add_u32 s14, s92, 0x580000
	global_load_lds_dwordx4 v144, s[92:93]
	s_addc_u32 s15, s93, 0
	s_add_i32 m0, s31, 0x14000
	v_mov_b32_e32 v149, 0
	global_load_lds_dwordx4 v148, s[14:15]
	s_add_i32 m0, s31, 0x16000
	s_add_u32 s90, s0, s12
	s_addc_u32 s91, s20, s13
	s_add_i32 s52, s31, 0x2000
	global_load_lds_dwordx4 v144, s[14:15]
	s_mov_b32 m0, s31
	s_add_u32 s12, s90, 0x40000
	global_load_lds_dwordx4 v150, s[90:91]
	s_mov_b32 m0, s52
	s_addc_u32 s13, s91, 0
	s_add_i32 s53, s31, 0x4000
	global_load_lds_dwordx4 v146, s[90:91]
	s_mov_b32 m0, s53
	s_add_i32 s58, s31, 0x6000
	global_load_lds_dwordx4 v150, s[12:13]
	s_mov_b32 m0, s58
	v_mov_b32_e32 v145, v149
	global_load_lds_dwordx4 v146, s[12:13]
	v_mov_b32_e32 v151, v149
	v_mov_b32_e32 v147, v149
	s_cmp_eq_u32 s7, 1
	s_mov_b32 s59, 0
	s_mov_b32 s101, 0
	v_lshl_add_u64 v[6:7], s[92:93], 0, v[148:149]
	v_lshl_add_u64 v[4:5], s[92:93], 0, v[144:145]
	v_lshl_add_u64 v[0:1], s[90:91], 0, v[150:151]
	s_cselect_b64 s[12:13], -1, 0
	s_cmp_lg_u32 s7, 1
	v_lshl_add_u64 v[2:3], s[90:91], 0, v[146:147]
	s_cbranch_scc1 .LBB0_822
	s_barrier

.LBB0_831:
	s_and_b32 s57, s101, 1
	s_mulk_i32 s57, 0x1800
	s_add_i32 s57, s57, 0x22c00
	s_bitcmp1_b32 s101, 1
	s_cbranch_scc1 .LepB_fast
	v_readfirstlane_b32 s67, v230
	s_cmp_lt_u32 s67, 64
	s_cbranch_scc0 .LepB_nfs
	s_add_i32 s4, s88, -32
	s_ashr_i32 s4, s4, 2
	s_add_i32 s4, s4, 1
	s_cmp_gt_i32 s88, 31
	s_cselect_b32 s4, s4, 0
	s_mul_hi_i32 s5, s4, 0x5800
	s_mulk_i32 s4, 0x5800
	v_readlane_b32 s67, v254, 49
	v_readlane_b32 s95, v254, 50
	s_nop 0
	s_add_u32 s4, s67, s4
	s_addc_u32 s5, s95, s5
	v_readlane_b32 s2, v254, 5
	v_readlane_b32 s3, v254, 6
	v_readlane_b32 s28, v254, 7
	v_readlane_b32 s29, v254, 8
	s_nop 0
	v_and_b32_e32 v238, 63, v230
	v_lshrrev_b32_e32 v239, 5, v238
	v_and_b32_e32 v240, 31, v238
	v_lshlrev_b32_e32 v240, 4, v240
	s_lshl_b32 s67, s66, 9
	v_add_u32_e32 v240, s67, v240
	v_mul_u32_u24_e32 v241, 0x2c00, v239
	v_mul_u32_u24_e32 v242, 0x5800, v239
	v_add_u32_e32 v241, v241, v240
	v_add_u32_e32 v242, v242, v240
	v_lshlrev_b32_e32 v243, 4, v238
	s_lshl_b32 s67, s88, 10
	v_add_u32_e32 v243, s67, v243
	s_mov_b32 m0, s57
	s_nop 0
	global_load_lds_dwordx4 v243, s[10:11]
	s_add_i32 m0, s57, 1024
	s_nop 0
	global_load_lds_dwordx4 v241, s[4:5]
	s_add_i32 m0, s57, 2048
	s_nop 0
	global_load_lds_dwordx4 v242, s[2:3]
	v_add_u32_e32 v243, 0x2c00, v242
	s_add_i32 m0, s57, 3072
	s_nop 0
	global_load_lds_dwordx4 v243, s[2:3]
	v_add_u32_e32 v243, 0xb000, v241
	s_add_i32 m0, s57, 4096
	s_nop 0
	global_load_lds_dwordx4 v243, s[2:3]
	s_add_i32 m0, s57, 5120
	s_nop 0
	global_load_lds_dwordx4 v241, s[28:29]

.LepB_fast:
	s_and_b32 s32, s12, 1
	v_and_b32_e32 v237, 15, v170
	v_and_b32_e32 v236, 64, v170
	v_lshl_add_u32 v236, v237, 2, v236
	v_mul_u32_u24_e32 v168, 0x1600, v236
	v_lshl_add_u32 v168, v172, 1, v168
	v_lshl_add_u32 v236, v236, 2, s57
	v_lshl_add_u32 v177, v172, 2, s57
	ds_read_b128 v[210:213], v236
	ds_read_b128 v[214:217], v236 offset:512
	ds_read_b128 v[202:205], v177 offset:1024
	ds_read_b128 v[206:209], v177 offset:1040
	ds_read_b128 v[218:221], v177 offset:1536
	ds_read_b128 v[222:225], v177 offset:1552
	ds_read_b128 v[116:119], v177 offset:2048
	ds_read_b128 v[124:127], v177 offset:2560
	ds_read_b128 v[128:131], v177 offset:4096
	ds_read_b128 v[132:135], v177 offset:5120
	ds_read_b128 v[160:163], v177 offset:3072
	ds_read_b128 v[164:167], v177 offset:3584
	ds_read_b128 v[178:181], v177 offset:4608
	ds_read_b128 v[182:185], v177 offset:5632
	s_mul_i32 s4, s88, 0x160000
	s_lshl_b32 s67, s66, 8
	s_add_i32 s4, s4, s67
	s_add_i32 s4, s4, 0x9300000
	s_add_u32 s4, s4, s70
	s_addc_u32 s5, s71, 0
	s_mov_b32 s67, 0x20800
	v_lshl_add_u32 v169, v172, 2, s67
	v_cmp_eq_u32_e64 s[2:3], 0, v237
	v_cmp_eq_u32_e64 s[28:29], 15, v237
	v_and_b32_e32 v231, 8, v237
	v_lshlrev_b32_e32 v231, 9, v231
	s_lshl_b32 s67, s32, 10
	v_add3_u32 v231, v231, v169, s67
	s_waitcnt lgkmcnt(12)
	v_fmamk_f32 v210, v210, 0x3a800000, v176
	v_fmamk_f32 v211, v211, 0x3a800000, v176
	v_fmamk_f32 v212, v212, 0x3a800000, v176
	v_fmamk_f32 v213, v213, 0x3a800000, v176
	v_fmamk_f32 v214, v214, 0x3a800000, v176
	v_fmamk_f32 v215, v215, 0x3a800000, v176
	v_fmamk_f32 v216, v216, 0x3a800000, v176
	v_fmamk_f32 v217, v217, 0x3a800000, v176
	s_mov_b32 s67, 0x800000
	v_mul_f32_e32 v226, 0x4b800000, v210
	v_mul_f32_e32 v227, 0x4b800000, v211
	v_mul_f32_e32 v228, 0x4b800000, v212
	v_mul_f32_e32 v229, 0x4b800000, v213
	v_mul_f32_e32 v232, 0x4b800000, v214
	v_mul_f32_e32 v233, 0x4b800000, v215
	v_mul_f32_e32 v234, 0x4b800000, v216
	v_mul_f32_e32 v235, 0x4b800000, v217
	v_cmp_gt_f32_e32 vcc, s67, v210
	s_nop 1
	v_cndmask_b32_e32 v210, v210, v226, vcc
	v_rsq_f32_e32 v210, v210
	s_nop 0
	v_mul_f32_e32 v226, 0x45800000, v210
	v_cndmask_b32_e32 v210, v210, v226, vcc
	v_cmp_gt_f32_e32 vcc, s67, v211
	s_nop 1
	v_cndmask_b32_e32 v211, v211, v227, vcc
	v_rsq_f32_e32 v211, v211
	s_nop 0
	v_mul_f32_e32 v227, 0x45800000, v211
	v_cndmask_b32_e32 v211, v211, v227, vcc
	v_cmp_gt_f32_e32 vcc, s67, v212
	s_nop 1
	v_cndmask_b32_e32 v212, v212, v228, vcc
	v_rsq_f32_e32 v212, v212
	s_nop 0
	v_mul_f32_e32 v228, 0x45800000, v212
	v_cndmask_b32_e32 v212, v212, v228, vcc
	v_cmp_gt_f32_e32 vcc, s67, v213
	s_nop 1
	v_cndmask_b32_e32 v213, v213, v229, vcc
	v_rsq_f32_e32 v213, v213
	s_nop 0
	v_mul_f32_e32 v229, 0x45800000, v213
	v_cndmask_b32_e32 v213, v213, v229, vcc
	v_cmp_gt_f32_e32 vcc, s67, v214
	s_nop 1
	v_cndmask_b32_e32 v214, v214, v232, vcc
	v_rsq_f32_e32 v214, v214
	s_nop 0
	v_mul_f32_e32 v232, 0x45800000, v214
	v_cndmask_b32_e32 v214, v214, v232, vcc
	v_cmp_gt_f32_e32 vcc, s67, v215
	s_nop 1
	v_cndmask_b32_e32 v215, v215, v233, vcc
	v_rsq_f32_e32 v215, v215
	s_nop 0
	v_mul_f32_e32 v233, 0x45800000, v215
	v_cndmask_b32_e32 v215, v215, v233, vcc
	v_cmp_gt_f32_e32 vcc, s67, v216
	s_nop 1
	v_cndmask_b32_e32 v216, v216, v234, vcc
	v_rsq_f32_e32 v216, v216
	s_nop 0
	v_mul_f32_e32 v234, 0x45800000, v216
	v_cndmask_b32_e32 v216, v216, v234, vcc
	v_cmp_gt_f32_e32 vcc, s67, v217
	s_nop 1
	v_cndmask_b32_e32 v217, v217, v235, vcc
	v_rsq_f32_e32 v217, v217
	s_nop 0
	v_mul_f32_e32 v235, 0x45800000, v217
	v_cndmask_b32_e32 v217, v217, v235, vcc
	s_waitcnt lgkmcnt(8)
	v_fma_f32 v140, v140, v210, v202
	v_fma_f32 v141, v141, v210, v203
	v_fma_f32 v142, v142, v210, v204
	v_fma_f32 v143, v143, v210, v205
	v_fma_f32 v136, v136, v210, v206
	v_fma_f32 v137, v137, v210, v207
	v_fma_f32 v138, v138, v210, v208
	v_fma_f32 v139, v139, v210, v209
	v_fma_f32 v120, v120, v210, v218
	v_fma_f32 v121, v121, v210, v219
	v_fma_f32 v122, v122, v210, v220
	v_fma_f32 v123, v123, v210, v221
	v_fma_f32 v112, v112, v210, v222
	v_fma_f32 v113, v113, v210, v223
	v_fma_f32 v114, v114, v210, v224
	v_fma_f32 v115, v115, v210, v225
	v_fma_f32 v108, v108, v211, v202
	v_fma_f32 v109, v109, v211, v203
	v_fma_f32 v110, v110, v211, v204
	v_fma_f32 v111, v111, v211, v205
	v_fma_f32 v104, v104, v211, v206
	v_fma_f32 v105, v105, v211, v207
	v_fma_f32 v106, v106, v211, v208
	v_fma_f32 v107, v107, v211, v209
	v_fma_f32 v100, v100, v211, v218
	v_fma_f32 v101, v101, v211, v219
	v_fma_f32 v102, v102, v211, v220
	v_fma_f32 v103, v103, v211, v221
	v_fma_f32 v96, v96, v211, v222
	v_fma_f32 v97, v97, v211, v223
	v_fma_f32 v98, v98, v211, v224
	v_fma_f32 v99, v99, v211, v225
	v_fma_f32 v92, v92, v212, v202
	v_fma_f32 v93, v93, v212, v203
	v_fma_f32 v94, v94, v212, v204
	v_fma_f32 v95, v95, v212, v205
	v_fma_f32 v88, v88, v212, v206
	v_fma_f32 v89, v89, v212, v207
	v_fma_f32 v90, v90, v212, v208
	v_fma_f32 v91, v91, v212, v209
	v_fma_f32 v84, v84, v212, v218
	v_fma_f32 v85, v85, v212, v219
	v_fma_f32 v86, v86, v212, v220
	v_fma_f32 v87, v87, v212, v221
	v_fma_f32 v80, v80, v212, v222
	v_fma_f32 v81, v81, v212, v223
	v_fma_f32 v82, v82, v212, v224
	v_fma_f32 v83, v83, v212, v225
	v_fma_f32 v76, v76, v213, v202
	v_fma_f32 v77, v77, v213, v203
	v_fma_f32 v78, v78, v213, v204
	v_fma_f32 v79, v79, v213, v205
	v_fma_f32 v72, v72, v213, v206
	v_fma_f32 v73, v73, v213, v207
	v_fma_f32 v74, v74, v213, v208
	v_fma_f32 v75, v75, v213, v209
	v_fma_f32 v68, v68, v213, v218
	v_fma_f32 v69, v69, v213, v219
	v_fma_f32 v70, v70, v213, v220
	v_fma_f32 v71, v71, v213, v221
	v_fma_f32 v64, v64, v213, v222
	v_fma_f32 v65, v65, v213, v223
	v_fma_f32 v66, v66, v213, v224
	v_fma_f32 v67, v67, v213, v225
	v_fma_f32 v60, v60, v214, v202
	v_fma_f32 v61, v61, v214, v203
	v_fma_f32 v62, v62, v214, v204
	v_fma_f32 v63, v63, v214, v205
	v_fma_f32 v56, v56, v214, v206
	v_fma_f32 v57, v57, v214, v207
	v_fma_f32 v58, v58, v214, v208
	v_fma_f32 v59, v59, v214, v209
	v_fma_f32 v52, v52, v214, v218
	v_fma_f32 v53, v53, v214, v219
	v_fma_f32 v54, v54, v214, v220
	v_fma_f32 v55, v55, v214, v221
	v_fma_f32 v48, v48, v214, v222
	v_fma_f32 v49, v49, v214, v223
	v_fma_f32 v50, v50, v214, v224
	v_fma_f32 v51, v51, v214, v225
	v_fma_f32 v44, v44, v215, v202
	v_fma_f32 v45, v45, v215, v203
	v_fma_f32 v46, v46, v215, v204
	v_fma_f32 v47, v47, v215, v205
	v_fma_f32 v40, v40, v215, v206
	v_fma_f32 v41, v41, v215, v207
	v_fma_f32 v42, v42, v215, v208
	v_fma_f32 v43, v43, v215, v209
	v_fma_f32 v36, v36, v215, v218
	v_fma_f32 v37, v37, v215, v219
	v_fma_f32 v38, v38, v215, v220
	v_fma_f32 v39, v39, v215, v221
	v_fma_f32 v32, v32, v215, v222
	v_fma_f32 v33, v33, v215, v223
	v_fma_f32 v34, v34, v215, v224
	v_fma_f32 v35, v35, v215, v225
	v_fma_f32 v28, v28, v216, v202
	v_fma_f32 v29, v29, v216, v203
	v_fma_f32 v30, v30, v216, v204
	v_fma_f32 v31, v31, v216, v205
	v_fma_f32 v24, v24, v216, v206
	v_fma_f32 v25, v25, v216, v207
	v_fma_f32 v26, v26, v216, v208
	v_fma_f32 v27, v27, v216, v209
	v_fma_f32 v20, v20, v216, v218
	v_fma_f32 v21, v21, v216, v219
	v_fma_f32 v22, v22, v216, v220
	v_fma_f32 v23, v23, v216, v221
	v_fma_f32 v16, v16, v216, v222
	v_fma_f32 v17, v17, v216, v223
	v_fma_f32 v18, v18, v216, v224
	v_fma_f32 v19, v19, v216, v225
	v_fma_f32 v12, v12, v217, v202
	v_fma_f32 v13, v13, v217, v203
	v_fma_f32 v14, v14, v217, v204
	v_fma_f32 v15, v15, v217, v205
	v_fma_f32 v8, v8, v217, v206
	v_fma_f32 v9, v9, v217, v207
	v_fma_f32 v10, v10, v217, v208
	v_fma_f32 v11, v11, v217, v209
	v_fma_f32 v4, v4, v217, v218
	v_fma_f32 v5, v5, v217, v219
	v_fma_f32 v6, v6, v217, v220
	v_fma_f32 v7, v7, v217, v221
	v_fma_f32 v0, v0, v217, v222
	v_fma_f32 v1, v1, v217, v223
	v_fma_f32 v2, v2, v217, v224
	v_fma_f32 v3, v3, v217, v225
	v_mov_b32_e32 v214, 0
	v_mov_b32_e32 v215, 0
	v_mov_b32_e32 v216, 0
	v_mov_b32_e32 v217, 0
	s_lshl_b32 s100, s32, 12
	s_sub_i32 s100, 0x2000, s100
	s_mul_i32 s98, s32, 0x1400
	s_add_i32 s98, s98, 0xc00
	s_lshl_b32 s67, s32, 10
	s_add_i32 s99, s67, 5120
	s_add_i32 s94, s67, 1024
	s_mov_b64 exec, s[2:3]
	v_add_u32_e32 v250, s100, v169
	ds_write_b128 v250, v[140:143] offset:0
	ds_write_b128 v250, v[136:139] offset:16
	ds_write_b128 v250, v[120:123] offset:512
	ds_write_b128 v250, v[112:115] offset:528
	v_add_u32_e32 v250, s99, v169
	ds_write_b128 v250, v[60:63] offset:0
	ds_write_b128 v250, v[56:59] offset:16
	ds_write_b128 v250, v[52:55] offset:512
	ds_write_b128 v250, v[48:51] offset:528
	ds_write_b128 v169, v[214:217] offset:0
	ds_write_b128 v169, v[214:217] offset:16
	ds_write_b128 v169, v[214:217] offset:512
	ds_write_b128 v169, v[214:217] offset:528
	s_mov_b64 exec, s[28:29]
	v_add_u32_e32 v251, s94, v169
	ds_write_b128 v251, v[76:79] offset:0
	ds_write_b128 v251, v[72:75] offset:16
	ds_write_b128 v251, v[68:71] offset:512
	ds_write_b128 v251, v[64:67] offset:528
	v_add_u32_e32 v251, s98, v169
	ds_write_b128 v251, v[12:15] offset:0
	ds_write_b128 v251, v[8:11] offset:16
	ds_write_b128 v251, v[4:7] offset:512
	ds_write_b128 v251, v[0:3] offset:528
	ds_write_b128 v169, v[214:217] offset:7168
	ds_write_b128 v169, v[214:217] offset:7184
	ds_write_b128 v169, v[214:217] offset:7680
	ds_write_b128 v169, v[214:217] offset:7696
	s_mov_b64 exec, -1
	s_waitcnt lgkmcnt(0)
	s_barrier
	ds_read_b128 v[186:189], v231 offset:0
	ds_read_b128 v[190:193], v231 offset:512
	ds_read_b128 v[194:197], v231 offset:2048
	ds_read_b128 v[198:201], v231 offset:2560
	s_nop 0
	v_cndmask_b32_e64 v218, 0, v116, s[2:3]
	v_cndmask_b32_e64 v222, 0, v128, s[28:29]
	v_cndmask_b32_e64 v219, 0, v117, s[2:3]
	v_cndmask_b32_e64 v223, 0, v129, s[28:29]
	v_cndmask_b32_e64 v220, 0, v118, s[2:3]
	v_cndmask_b32_e64 v224, 0, v130, s[28:29]
	v_cndmask_b32_e64 v221, 0, v119, s[2:3]
	v_cndmask_b32_e64 v225, 0, v131, s[28:29]
	v_cndmask_b32_e64 v226, 0, v160, s[2:3]
	v_cndmask_b32_e64 v232, 0, v178, s[28:29]
	v_cndmask_b32_e64 v227, 0, v161, s[2:3]
	v_cndmask_b32_e64 v233, 0, v179, s[28:29]
	v_cndmask_b32_e64 v228, 0, v162, s[2:3]
	v_cndmask_b32_e64 v234, 0, v180, s[28:29]
	v_cndmask_b32_e64 v229, 0, v163, s[2:3]
	v_cndmask_b32_e64 v235, 0, v181, s[28:29]
	s_waitcnt lgkmcnt(0)
	s_nop 1
	v_fma_f32 v202, v124, v140, v132
	v_fma_f32 v203, v125, v141, v133
	v_fma_f32 v204, v126, v142, v134
	v_fma_f32 v205, v127, v143, v135
	v_fmac_f32_dpp v202, v76, v116 row_shr:1 row_mask:0xf bank_mask:0xf
	v_fmac_f32_dpp v203, v77, v117 row_shr:1 row_mask:0xf bank_mask:0xf
	v_fmac_f32_dpp v204, v78, v118 row_shr:1 row_mask:0xf bank_mask:0xf
	v_fmac_f32_dpp v205, v79, v119 row_shr:1 row_mask:0xf bank_mask:0xf
	v_fmac_f32_e32 v202, v186, v218
	v_fmac_f32_e32 v203, v187, v219
	v_fmac_f32_e32 v204, v188, v220
	v_fmac_f32_e32 v205, v189, v221
	v_fmac_f32_e32 v202, v108, v128
	v_fmac_f32_e32 v203, v109, v129
	v_fmac_f32_e32 v204, v110, v130
	v_fmac_f32_e32 v205, v111, v131
	v_fma_f32 v206, v164, v120, v182
	v_fma_f32 v207, v165, v121, v183
	v_fma_f32 v208, v166, v122, v184
	v_fma_f32 v209, v167, v123, v185
	v_fmac_f32_dpp v206, v68, v160 row_shr:1 row_mask:0xf bank_mask:0xf
	v_fmac_f32_dpp v207, v69, v161 row_shr:1 row_mask:0xf bank_mask:0xf
	v_fmac_f32_dpp v208, v70, v162 row_shr:1 row_mask:0xf bank_mask:0xf
	v_fmac_f32_dpp v209, v71, v163 row_shr:1 row_mask:0xf bank_mask:0xf
	v_fmac_f32_e32 v206, v190, v226
	v_fmac_f32_e32 v207, v191, v227
	v_fmac_f32_e32 v208, v192, v228
	v_fmac_f32_e32 v209, v193, v229
	v_fmac_f32_e32 v206, v100, v178
	v_fmac_f32_e32 v207, v101, v179
	v_fmac_f32_e32 v208, v102, v180
	v_fmac_f32_e32 v209, v103, v181
	v_mul_f32_e32 v210, 0xbfb8aa3b, v202
	v_mul_f32_e32 v211, 0xbfb8aa3b, v203
	v_mul_f32_e32 v212, 0xbfb8aa3b, v204
	v_mul_f32_e32 v213, 0xbfb8aa3b, v205
	v_exp_f32_e32 v210, v210
	v_exp_f32_e32 v211, v211
	v_exp_f32_e32 v212, v212
	v_exp_f32_e32 v213, v213
	v_add_f32_e32 v210, 1.0, v210
	v_add_f32_e32 v211, 1.0, v211
	v_add_f32_e32 v212, 1.0, v212
	v_add_f32_e32 v213, 1.0, v213
	v_rcp_f32_e32 v210, v210
	v_rcp_f32_e32 v211, v211
	v_rcp_f32_e32 v212, v212
	v_rcp_f32_e32 v213, v213
	v_mul_f32_e32 v202, v202, v210
	v_mul_f32_e32 v203, v203, v211
	v_mul_f32_e32 v204, v204, v212
	v_mul_f32_e32 v205, v205, v213
	v_mul_f32_e32 v202, v202, v206
	v_mul_f32_e32 v203, v203, v207
	v_mul_f32_e32 v204, v204, v208
	v_mul_f32_e32 v205, v205, v209
	v_cvt_pk_bf16_f32 v236, v202, v203
	v_cvt_pk_bf16_f32 v237, v204, v205
	v_fma_f32 v202, v124, v108, v132
	v_fma_f32 v203, v125, v109, v133
	v_fma_f32 v204, v126, v110, v134
	v_fma_f32 v205, v127, v111, v135
	v_fmac_f32_e32 v202, v140, v116
	v_fmac_f32_e32 v203, v141, v117
	v_fmac_f32_e32 v204, v142, v118
	v_fmac_f32_e32 v205, v143, v119
	v_fmac_f32_e32 v202, v92, v128
	v_fmac_f32_e32 v203, v93, v129
	v_fmac_f32_e32 v204, v94, v130
	v_fmac_f32_e32 v205, v95, v131
	v_fma_f32 v206, v164, v100, v182
	v_fma_f32 v207, v165, v101, v183
	v_fma_f32 v208, v166, v102, v184
	v_fma_f32 v209, v167, v103, v185
	v_fmac_f32_e32 v206, v120, v160
	v_fmac_f32_e32 v207, v121, v161
	v_fmac_f32_e32 v208, v122, v162
	v_fmac_f32_e32 v209, v123, v163
	v_fmac_f32_e32 v206, v84, v178
	v_fmac_f32_e32 v207, v85, v179
	v_fmac_f32_e32 v208, v86, v180
	v_fmac_f32_e32 v209, v87, v181
	v_mul_f32_e32 v210, 0xbfb8aa3b, v202
	v_mul_f32_e32 v211, 0xbfb8aa3b, v203
	v_mul_f32_e32 v212, 0xbfb8aa3b, v204
	v_mul_f32_e32 v213, 0xbfb8aa3b, v205
	v_exp_f32_e32 v210, v210
	v_exp_f32_e32 v211, v211
	v_exp_f32_e32 v212, v212
	v_exp_f32_e32 v213, v213
	v_add_f32_e32 v210, 1.0, v210
	v_add_f32_e32 v211, 1.0, v211
	v_add_f32_e32 v212, 1.0, v212
	v_add_f32_e32 v213, 1.0, v213
	v_rcp_f32_e32 v210, v210
	v_rcp_f32_e32 v211, v211
	v_rcp_f32_e32 v212, v212
	v_rcp_f32_e32 v213, v213
	v_mul_f32_e32 v202, v202, v210
	v_mul_f32_e32 v203, v203, v211
	v_mul_f32_e32 v204, v204, v212
	v_mul_f32_e32 v205, v205, v213
	v_mul_f32_e32 v202, v202, v206
	v_mul_f32_e32 v203, v203, v207
	v_mul_f32_e32 v204, v204, v208
	v_mul_f32_e32 v205, v205, v209
	v_cvt_pk_bf16_f32 v238, v202, v203
	v_cvt_pk_bf16_f32 v239, v204, v205
	v_fma_f32 v202, v124, v92, v132
	v_fma_f32 v203, v125, v93, v133
	v_fma_f32 v204, v126, v94, v134
	v_fma_f32 v205, v127, v95, v135
	v_fmac_f32_e32 v202, v108, v116
	v_fmac_f32_e32 v203, v109, v117
	v_fmac_f32_e32 v204, v110, v118
	v_fmac_f32_e32 v205, v111, v119
	v_fmac_f32_e32 v202, v76, v128
	v_fmac_f32_e32 v203, v77, v129
	v_fmac_f32_e32 v204, v78, v130
	v_fmac_f32_e32 v205, v79, v131
	v_fma_f32 v206, v164, v84, v182
	v_fma_f32 v207, v165, v85, v183
	v_fma_f32 v208, v166, v86, v184
	v_fma_f32 v209, v167, v87, v185
	v_fmac_f32_e32 v206, v100, v160
	v_fmac_f32_e32 v207, v101, v161
	v_fmac_f32_e32 v208, v102, v162
	v_fmac_f32_e32 v209, v103, v163
	v_fmac_f32_e32 v206, v68, v178
	v_fmac_f32_e32 v207, v69, v179
	v_fmac_f32_e32 v208, v70, v180
	v_fmac_f32_e32 v209, v71, v181
	v_mul_f32_e32 v210, 0xbfb8aa3b, v202
	v_mul_f32_e32 v211, 0xbfb8aa3b, v203
	v_mul_f32_e32 v212, 0xbfb8aa3b, v204
	v_mul_f32_e32 v213, 0xbfb8aa3b, v205
	v_exp_f32_e32 v210, v210
	v_exp_f32_e32 v211, v211
	v_exp_f32_e32 v212, v212
	v_exp_f32_e32 v213, v213
	v_add_f32_e32 v210, 1.0, v210
	v_add_f32_e32 v211, 1.0, v211
	v_add_f32_e32 v212, 1.0, v212
	v_add_f32_e32 v213, 1.0, v213
	v_rcp_f32_e32 v210, v210
	v_rcp_f32_e32 v211, v211
	v_rcp_f32_e32 v212, v212
	v_rcp_f32_e32 v213, v213
	v_mul_f32_e32 v202, v202, v210
	v_mul_f32_e32 v203, v203, v211
	v_mul_f32_e32 v204, v204, v212
	v_mul_f32_e32 v205, v205, v213
	v_mul_f32_e32 v202, v202, v206
	v_mul_f32_e32 v203, v203, v207
	v_mul_f32_e32 v204, v204, v208
	v_mul_f32_e32 v205, v205, v209
	v_cvt_pk_bf16_f32 v240, v202, v203
	v_cvt_pk_bf16_f32 v241, v204, v205
	v_fma_f32 v202, v124, v76, v132
	v_fma_f32 v203, v125, v77, v133
	v_fma_f32 v204, v126, v78, v134
	v_fma_f32 v205, v127, v79, v135
	v_fmac_f32_e32 v202, v92, v116
	v_fmac_f32_e32 v203, v93, v117
	v_fmac_f32_e32 v204, v94, v118
	v_fmac_f32_e32 v205, v95, v119
	v_fmac_f32_dpp v202, v140, v128 row_shl:1 row_mask:0xf bank_mask:0xf
	v_fmac_f32_dpp v203, v141, v129 row_shl:1 row_mask:0xf bank_mask:0xf
	v_fmac_f32_dpp v204, v142, v130 row_shl:1 row_mask:0xf bank_mask:0xf
	v_fmac_f32_dpp v205, v143, v131 row_shl:1 row_mask:0xf bank_mask:0xf
	v_fmac_f32_e32 v202, v186, v222
	v_fmac_f32_e32 v203, v187, v223
	v_fmac_f32_e32 v204, v188, v224
	v_fmac_f32_e32 v205, v189, v225
	v_fma_f32 v206, v164, v68, v182
	v_fma_f32 v207, v165, v69, v183
	v_fma_f32 v208, v166, v70, v184
	v_fma_f32 v209, v167, v71, v185
	v_fmac_f32_e32 v206, v84, v160
	v_fmac_f32_e32 v207, v85, v161
	v_fmac_f32_e32 v208, v86, v162
	v_fmac_f32_e32 v209, v87, v163
	v_fmac_f32_dpp v206, v120, v178 row_shl:1 row_mask:0xf bank_mask:0xf
	v_fmac_f32_dpp v207, v121, v179 row_shl:1 row_mask:0xf bank_mask:0xf
	v_fmac_f32_dpp v208, v122, v180 row_shl:1 row_mask:0xf bank_mask:0xf
	v_fmac_f32_dpp v209, v123, v181 row_shl:1 row_mask:0xf bank_mask:0xf
	v_fmac_f32_e32 v206, v190, v232
	v_fmac_f32_e32 v207, v191, v233
	v_fmac_f32_e32 v208, v192, v234
	v_fmac_f32_e32 v209, v193, v235
	v_mul_f32_e32 v210, 0xbfb8aa3b, v202
	v_mul_f32_e32 v211, 0xbfb8aa3b, v203
	v_mul_f32_e32 v212, 0xbfb8aa3b, v204
	v_mul_f32_e32 v213, 0xbfb8aa3b, v205
	v_exp_f32_e32 v210, v210
	v_exp_f32_e32 v211, v211
	v_exp_f32_e32 v212, v212
	v_exp_f32_e32 v213, v213
	v_add_f32_e32 v210, 1.0, v210
	v_add_f32_e32 v211, 1.0, v211
	v_add_f32_e32 v212, 1.0, v212
	v_add_f32_e32 v213, 1.0, v213
	v_rcp_f32_e32 v210, v210
	v_rcp_f32_e32 v211, v211
	v_rcp_f32_e32 v212, v212
	v_rcp_f32_e32 v213, v213
	v_mul_f32_e32 v202, v202, v210
	v_mul_f32_e32 v203, v203, v211
	v_mul_f32_e32 v204, v204, v212
	v_mul_f32_e32 v205, v205, v213
	v_mul_f32_e32 v202, v202, v206
	v_mul_f32_e32 v203, v203, v207
	v_mul_f32_e32 v204, v204, v208
	v_mul_f32_e32 v205, v205, v209
	v_cvt_pk_bf16_f32 v242, v202, v203
	v_cvt_pk_bf16_f32 v243, v204, v205
	v_fma_f32 v202, v124, v60, v132
	v_fma_f32 v203, v125, v61, v133
	v_fma_f32 v204, v126, v62, v134
	v_fma_f32 v205, v127, v63, v135
	v_fmac_f32_dpp v202, v12, v116 row_shr:1 row_mask:0xf bank_mask:0xf
	v_fmac_f32_dpp v203, v13, v117 row_shr:1 row_mask:0xf bank_mask:0xf
	v_fmac_f32_dpp v204, v14, v118 row_shr:1 row_mask:0xf bank_mask:0xf
	v_fmac_f32_dpp v205, v15, v119 row_shr:1 row_mask:0xf bank_mask:0xf
	v_fmac_f32_e32 v202, v194, v218
	v_fmac_f32_e32 v203, v195, v219
	v_fmac_f32_e32 v204, v196, v220
	v_fmac_f32_e32 v205, v197, v221
	v_fmac_f32_e32 v202, v44, v128
	v_fmac_f32_e32 v203, v45, v129
	v_fmac_f32_e32 v204, v46, v130
	v_fmac_f32_e32 v205, v47, v131
	v_fma_f32 v206, v164, v52, v182
	v_fma_f32 v207, v165, v53, v183
	v_fma_f32 v208, v166, v54, v184
	v_fma_f32 v209, v167, v55, v185
	v_fmac_f32_dpp v206, v4, v160 row_shr:1 row_mask:0xf bank_mask:0xf
	v_fmac_f32_dpp v207, v5, v161 row_shr:1 row_mask:0xf bank_mask:0xf
	v_fmac_f32_dpp v208, v6, v162 row_shr:1 row_mask:0xf bank_mask:0xf
	v_fmac_f32_dpp v209, v7, v163 row_shr:1 row_mask:0xf bank_mask:0xf
	v_fmac_f32_e32 v206, v198, v226
	v_fmac_f32_e32 v207, v199, v227
	v_fmac_f32_e32 v208, v200, v228
	v_fmac_f32_e32 v209, v201, v229
	v_fmac_f32_e32 v206, v36, v178
	v_fmac_f32_e32 v207, v37, v179
	v_fmac_f32_e32 v208, v38, v180
	v_fmac_f32_e32 v209, v39, v181
	v_mul_f32_e32 v210, 0xbfb8aa3b, v202
	v_mul_f32_e32 v211, 0xbfb8aa3b, v203
	v_mul_f32_e32 v212, 0xbfb8aa3b, v204
	v_mul_f32_e32 v213, 0xbfb8aa3b, v205
	v_exp_f32_e32 v210, v210
	v_exp_f32_e32 v211, v211
	v_exp_f32_e32 v212, v212
	v_exp_f32_e32 v213, v213
	v_add_f32_e32 v210, 1.0, v210
	v_add_f32_e32 v211, 1.0, v211
	v_add_f32_e32 v212, 1.0, v212
	v_add_f32_e32 v213, 1.0, v213
	v_rcp_f32_e32 v210, v210
	v_rcp_f32_e32 v211, v211
	v_rcp_f32_e32 v212, v212
	v_rcp_f32_e32 v213, v213
	v_mul_f32_e32 v202, v202, v210
	v_mul_f32_e32 v203, v203, v211
	v_mul_f32_e32 v204, v204, v212
	v_mul_f32_e32 v205, v205, v213
	v_mul_f32_e32 v202, v202, v206
	v_mul_f32_e32 v203, v203, v207
	v_mul_f32_e32 v204, v204, v208
	v_mul_f32_e32 v205, v205, v209
	v_cvt_pk_bf16_f32 v244, v202, v203
	v_cvt_pk_bf16_f32 v245, v204, v205
	v_fma_f32 v202, v124, v44, v132
	v_fma_f32 v203, v125, v45, v133
	v_fma_f32 v204, v126, v46, v134
	v_fma_f32 v205, v127, v47, v135
	v_fmac_f32_e32 v202, v60, v116
	v_fmac_f32_e32 v203, v61, v117
	v_fmac_f32_e32 v204, v62, v118
	v_fmac_f32_e32 v205, v63, v119
	v_fmac_f32_e32 v202, v28, v128
	v_fmac_f32_e32 v203, v29, v129
	v_fmac_f32_e32 v204, v30, v130
	v_fmac_f32_e32 v205, v31, v131
	v_fma_f32 v206, v164, v36, v182
	v_fma_f32 v207, v165, v37, v183
	v_fma_f32 v208, v166, v38, v184
	v_fma_f32 v209, v167, v39, v185
	v_fmac_f32_e32 v206, v52, v160
	v_fmac_f32_e32 v207, v53, v161
	v_fmac_f32_e32 v208, v54, v162
	v_fmac_f32_e32 v209, v55, v163
	v_fmac_f32_e32 v206, v20, v178
	v_fmac_f32_e32 v207, v21, v179
	v_fmac_f32_e32 v208, v22, v180
	v_fmac_f32_e32 v209, v23, v181
	v_mul_f32_e32 v210, 0xbfb8aa3b, v202
	v_mul_f32_e32 v211, 0xbfb8aa3b, v203
	v_mul_f32_e32 v212, 0xbfb8aa3b, v204
	v_mul_f32_e32 v213, 0xbfb8aa3b, v205
	v_exp_f32_e32 v210, v210
	v_exp_f32_e32 v211, v211
	v_exp_f32_e32 v212, v212
	v_exp_f32_e32 v213, v213
	v_add_f32_e32 v210, 1.0, v210
	v_add_f32_e32 v211, 1.0, v211
	v_add_f32_e32 v212, 1.0, v212
	v_add_f32_e32 v213, 1.0, v213
	v_rcp_f32_e32 v210, v210
	v_rcp_f32_e32 v211, v211
	v_rcp_f32_e32 v212, v212
	v_rcp_f32_e32 v213, v213
	v_mul_f32_e32 v202, v202, v210
	v_mul_f32_e32 v203, v203, v211
	v_mul_f32_e32 v204, v204, v212
	v_mul_f32_e32 v205, v205, v213
	v_mul_f32_e32 v202, v202, v206
	v_mul_f32_e32 v203, v203, v207
	v_mul_f32_e32 v204, v204, v208
	v_mul_f32_e32 v205, v205, v209
	v_cvt_pk_bf16_f32 v246, v202, v203
	v_cvt_pk_bf16_f32 v247, v204, v205
	v_fma_f32 v202, v124, v28, v132
	v_fma_f32 v203, v125, v29, v133
	v_fma_f32 v204, v126, v30, v134
	v_fma_f32 v205, v127, v31, v135
	v_fmac_f32_e32 v202, v44, v116
	v_fmac_f32_e32 v203, v45, v117
	v_fmac_f32_e32 v204, v46, v118
	v_fmac_f32_e32 v205, v47, v119
	v_fmac_f32_e32 v202, v12, v128
	v_fmac_f32_e32 v203, v13, v129
	v_fmac_f32_e32 v204, v14, v130
	v_fmac_f32_e32 v205, v15, v131
	v_fma_f32 v206, v164, v20, v182
	v_fma_f32 v207, v165, v21, v183
	v_fma_f32 v208, v166, v22, v184
	v_fma_f32 v209, v167, v23, v185
	v_fmac_f32_e32 v206, v36, v160
	v_fmac_f32_e32 v207, v37, v161
	v_fmac_f32_e32 v208, v38, v162
	v_fmac_f32_e32 v209, v39, v163
	v_fmac_f32_e32 v206, v4, v178
	v_fmac_f32_e32 v207, v5, v179
	v_fmac_f32_e32 v208, v6, v180
	v_fmac_f32_e32 v209, v7, v181
	v_mul_f32_e32 v210, 0xbfb8aa3b, v202
	v_mul_f32_e32 v211, 0xbfb8aa3b, v203
	v_mul_f32_e32 v212, 0xbfb8aa3b, v204
	v_mul_f32_e32 v213, 0xbfb8aa3b, v205
	v_exp_f32_e32 v210, v210
	v_exp_f32_e32 v211, v211
	v_exp_f32_e32 v212, v212
	v_exp_f32_e32 v213, v213
	v_add_f32_e32 v210, 1.0, v210
	v_add_f32_e32 v211, 1.0, v211
	v_add_f32_e32 v212, 1.0, v212
	v_add_f32_e32 v213, 1.0, v213
	v_rcp_f32_e32 v210, v210
	v_rcp_f32_e32 v211, v211
	v_rcp_f32_e32 v212, v212
	v_rcp_f32_e32 v213, v213
	v_mul_f32_e32 v202, v202, v210
	v_mul_f32_e32 v203, v203, v211
	v_mul_f32_e32 v204, v204, v212
	v_mul_f32_e32 v205, v205, v213
	v_mul_f32_e32 v202, v202, v206
	v_mul_f32_e32 v203, v203, v207
	v_mul_f32_e32 v204, v204, v208
	v_mul_f32_e32 v205, v205, v209
	v_cvt_pk_bf16_f32 v248, v202, v203
	v_cvt_pk_bf16_f32 v249, v204, v205
	v_fma_f32 v202, v124, v12, v132
	v_fma_f32 v203, v125, v13, v133
	v_fma_f32 v204, v126, v14, v134
	v_fma_f32 v205, v127, v15, v135
	v_fmac_f32_e32 v202, v28, v116
	v_fmac_f32_e32 v203, v29, v117
	v_fmac_f32_e32 v204, v30, v118
	v_fmac_f32_e32 v205, v31, v119
	v_fmac_f32_dpp v202, v60, v128 row_shl:1 row_mask:0xf bank_mask:0xf
	v_fmac_f32_dpp v203, v61, v129 row_shl:1 row_mask:0xf bank_mask:0xf
	v_fmac_f32_dpp v204, v62, v130 row_shl:1 row_mask:0xf bank_mask:0xf
	v_fmac_f32_dpp v205, v63, v131 row_shl:1 row_mask:0xf bank_mask:0xf
	v_fmac_f32_e32 v202, v194, v222
	v_fmac_f32_e32 v203, v195, v223
	v_fmac_f32_e32 v204, v196, v224
	v_fmac_f32_e32 v205, v197, v225
	v_fma_f32 v206, v164, v4, v182
	v_fma_f32 v207, v165, v5, v183
	v_fma_f32 v208, v166, v6, v184
	v_fma_f32 v209, v167, v7, v185
	v_fmac_f32_e32 v206, v20, v160
	v_fmac_f32_e32 v207, v21, v161
	v_fmac_f32_e32 v208, v22, v162
	v_fmac_f32_e32 v209, v23, v163
	v_fmac_f32_dpp v206, v52, v178 row_shl:1 row_mask:0xf bank_mask:0xf
	v_fmac_f32_dpp v207, v53, v179 row_shl:1 row_mask:0xf bank_mask:0xf
	v_fmac_f32_dpp v208, v54, v180 row_shl:1 row_mask:0xf bank_mask:0xf
	v_fmac_f32_dpp v209, v55, v181 row_shl:1 row_mask:0xf bank_mask:0xf
	v_fmac_f32_e32 v206, v198, v232
	v_fmac_f32_e32 v207, v199, v233
	v_fmac_f32_e32 v208, v200, v234
	v_fmac_f32_e32 v209, v201, v235
	v_mul_f32_e32 v210, 0xbfb8aa3b, v202
	v_mul_f32_e32 v211, 0xbfb8aa3b, v203
	v_mul_f32_e32 v212, 0xbfb8aa3b, v204
	v_mul_f32_e32 v213, 0xbfb8aa3b, v205
	v_exp_f32_e32 v210, v210
	v_exp_f32_e32 v211, v211
	v_exp_f32_e32 v212, v212
	v_exp_f32_e32 v213, v213
	v_add_f32_e32 v210, 1.0, v210
	v_add_f32_e32 v211, 1.0, v211
	v_add_f32_e32 v212, 1.0, v212
	v_add_f32_e32 v213, 1.0, v213
	v_rcp_f32_e32 v210, v210
	v_rcp_f32_e32 v211, v211
	v_rcp_f32_e32 v212, v212
	v_rcp_f32_e32 v213, v213
	v_mul_f32_e32 v202, v202, v210
	v_mul_f32_e32 v203, v203, v211
	v_mul_f32_e32 v204, v204, v212
	v_mul_f32_e32 v205, v205, v213
	v_mul_f32_e32 v202, v202, v206
	v_mul_f32_e32 v203, v203, v207
	v_mul_f32_e32 v204, v204, v208
	v_mul_f32_e32 v205, v205, v209
	v_cvt_pk_bf16_f32 v250, v202, v203
	v_cvt_pk_bf16_f32 v251, v204, v205
	ds_read_b128 v[116:119], v177 offset:2064
	ds_read_b128 v[124:127], v177 offset:2576
	ds_read_b128 v[128:131], v177 offset:4112
	ds_read_b128 v[132:135], v177 offset:5136
	ds_read_b128 v[160:163], v177 offset:3088
	ds_read_b128 v[164:167], v177 offset:3600
	ds_read_b128 v[178:181], v177 offset:4624
	ds_read_b128 v[182:185], v177 offset:5648
	v_mov_b32_e32 v140, v236
	v_mov_b32_e32 v141, v237
	v_mov_b32_e32 v108, v238
	v_mov_b32_e32 v109, v239
	v_mov_b32_e32 v92, v240
	v_mov_b32_e32 v93, v241
	v_mov_b32_e32 v76, v242
	v_mov_b32_e32 v77, v243
	v_mov_b32_e32 v60, v244
	v_mov_b32_e32 v61, v245
	v_mov_b32_e32 v44, v246
	v_mov_b32_e32 v45, v247
	v_mov_b32_e32 v28, v248
	v_mov_b32_e32 v29, v249
	v_mov_b32_e32 v12, v250
	v_mov_b32_e32 v13, v251
	ds_read_b128 v[186:189], v231 offset:16
	ds_read_b128 v[190:193], v231 offset:528
	ds_read_b128 v[194:197], v231 offset:2064
	ds_read_b128 v[198:201], v231 offset:2576
	s_waitcnt lgkmcnt(4)
	v_cndmask_b32_e64 v218, 0, v116, s[2:3]
	v_cndmask_b32_e64 v222, 0, v128, s[28:29]
	v_cndmask_b32_e64 v219, 0, v117, s[2:3]
	v_cndmask_b32_e64 v223, 0, v129, s[28:29]
	v_cndmask_b32_e64 v220, 0, v118, s[2:3]
	v_cndmask_b32_e64 v224, 0, v130, s[28:29]
	v_cndmask_b32_e64 v221, 0, v119, s[2:3]
	v_cndmask_b32_e64 v225, 0, v131, s[28:29]
	v_cndmask_b32_e64 v226, 0, v160, s[2:3]
	v_cndmask_b32_e64 v232, 0, v178, s[28:29]
	v_cndmask_b32_e64 v227, 0, v161, s[2:3]
	v_cndmask_b32_e64 v233, 0, v179, s[28:29]
	v_cndmask_b32_e64 v228, 0, v162, s[2:3]
	v_cndmask_b32_e64 v234, 0, v180, s[28:29]
	v_cndmask_b32_e64 v229, 0, v163, s[2:3]
	v_cndmask_b32_e64 v235, 0, v181, s[28:29]
	s_waitcnt lgkmcnt(0)
	s_nop 1
	v_fma_f32 v202, v124, v136, v132
	v_fma_f32 v203, v125, v137, v133
	v_fma_f32 v204, v126, v138, v134
	v_fma_f32 v205, v127, v139, v135
	v_fmac_f32_dpp v202, v72, v116 row_shr:1 row_mask:0xf bank_mask:0xf
	v_fmac_f32_dpp v203, v73, v117 row_shr:1 row_mask:0xf bank_mask:0xf
	v_fmac_f32_dpp v204, v74, v118 row_shr:1 row_mask:0xf bank_mask:0xf
	v_fmac_f32_dpp v205, v75, v119 row_shr:1 row_mask:0xf bank_mask:0xf
	v_fmac_f32_e32 v202, v186, v218
	v_fmac_f32_e32 v203, v187, v219
	v_fmac_f32_e32 v204, v188, v220
	v_fmac_f32_e32 v205, v189, v221
	v_fmac_f32_e32 v202, v104, v128
	v_fmac_f32_e32 v203, v105, v129
	v_fmac_f32_e32 v204, v106, v130
	v_fmac_f32_e32 v205, v107, v131
	v_fma_f32 v206, v164, v112, v182
	v_fma_f32 v207, v165, v113, v183
	v_fma_f32 v208, v166, v114, v184
	v_fma_f32 v209, v167, v115, v185
	v_fmac_f32_dpp v206, v64, v160 row_shr:1 row_mask:0xf bank_mask:0xf
	v_fmac_f32_dpp v207, v65, v161 row_shr:1 row_mask:0xf bank_mask:0xf
	v_fmac_f32_dpp v208, v66, v162 row_shr:1 row_mask:0xf bank_mask:0xf
	v_fmac_f32_dpp v209, v67, v163 row_shr:1 row_mask:0xf bank_mask:0xf
	v_fmac_f32_e32 v206, v190, v226
	v_fmac_f32_e32 v207, v191, v227
	v_fmac_f32_e32 v208, v192, v228
	v_fmac_f32_e32 v209, v193, v229
	v_fmac_f32_e32 v206, v96, v178
	v_fmac_f32_e32 v207, v97, v179
	v_fmac_f32_e32 v208, v98, v180
	v_fmac_f32_e32 v209, v99, v181
	v_mul_f32_e32 v210, 0xbfb8aa3b, v202
	v_mul_f32_e32 v211, 0xbfb8aa3b, v203
	v_mul_f32_e32 v212, 0xbfb8aa3b, v204
	v_mul_f32_e32 v213, 0xbfb8aa3b, v205
	v_exp_f32_e32 v210, v210
	v_exp_f32_e32 v211, v211
	v_exp_f32_e32 v212, v212
	v_exp_f32_e32 v213, v213
	v_add_f32_e32 v210, 1.0, v210
	v_add_f32_e32 v211, 1.0, v211
	v_add_f32_e32 v212, 1.0, v212
	v_add_f32_e32 v213, 1.0, v213
	v_rcp_f32_e32 v210, v210
	v_rcp_f32_e32 v211, v211
	v_rcp_f32_e32 v212, v212
	v_rcp_f32_e32 v213, v213
	v_mul_f32_e32 v202, v202, v210
	v_mul_f32_e32 v203, v203, v211
	v_mul_f32_e32 v204, v204, v212
	v_mul_f32_e32 v205, v205, v213
	v_mul_f32_e32 v202, v202, v206
	v_mul_f32_e32 v203, v203, v207
	v_mul_f32_e32 v204, v204, v208
	v_mul_f32_e32 v205, v205, v209
	v_cvt_pk_bf16_f32 v142, v202, v203
	v_cvt_pk_bf16_f32 v143, v204, v205
	v_fma_f32 v202, v124, v104, v132
	v_fma_f32 v203, v125, v105, v133
	v_fma_f32 v204, v126, v106, v134
	v_fma_f32 v205, v127, v107, v135
	v_fmac_f32_e32 v202, v136, v116
	v_fmac_f32_e32 v203, v137, v117
	v_fmac_f32_e32 v204, v138, v118
	v_fmac_f32_e32 v205, v139, v119
	v_fmac_f32_e32 v202, v88, v128
	v_fmac_f32_e32 v203, v89, v129
	v_fmac_f32_e32 v204, v90, v130
	v_fmac_f32_e32 v205, v91, v131
	v_fma_f32 v206, v164, v96, v182
	v_fma_f32 v207, v165, v97, v183
	v_fma_f32 v208, v166, v98, v184
	v_fma_f32 v209, v167, v99, v185
	v_fmac_f32_e32 v206, v112, v160
	v_fmac_f32_e32 v207, v113, v161
	v_fmac_f32_e32 v208, v114, v162
	v_fmac_f32_e32 v209, v115, v163
	v_fmac_f32_e32 v206, v80, v178
	v_fmac_f32_e32 v207, v81, v179
	v_fmac_f32_e32 v208, v82, v180
	v_fmac_f32_e32 v209, v83, v181
	v_mul_f32_e32 v210, 0xbfb8aa3b, v202
	v_mul_f32_e32 v211, 0xbfb8aa3b, v203
	v_mul_f32_e32 v212, 0xbfb8aa3b, v204
	v_mul_f32_e32 v213, 0xbfb8aa3b, v205
	v_exp_f32_e32 v210, v210
	v_exp_f32_e32 v211, v211
	v_exp_f32_e32 v212, v212
	v_exp_f32_e32 v213, v213
	v_add_f32_e32 v210, 1.0, v210
	v_add_f32_e32 v211, 1.0, v211
	v_add_f32_e32 v212, 1.0, v212
	v_add_f32_e32 v213, 1.0, v213
	v_rcp_f32_e32 v210, v210
	v_rcp_f32_e32 v211, v211
	v_rcp_f32_e32 v212, v212
	v_rcp_f32_e32 v213, v213
	v_mul_f32_e32 v202, v202, v210
	v_mul_f32_e32 v203, v203, v211
	v_mul_f32_e32 v204, v204, v212
	v_mul_f32_e32 v205, v205, v213
	v_mul_f32_e32 v202, v202, v206
	v_mul_f32_e32 v203, v203, v207
	v_mul_f32_e32 v204, v204, v208
	v_mul_f32_e32 v205, v205, v209
	v_cvt_pk_bf16_f32 v110, v202, v203
	v_cvt_pk_bf16_f32 v111, v204, v205
	v_fma_f32 v202, v124, v88, v132
	v_fma_f32 v203, v125, v89, v133
	v_fma_f32 v204, v126, v90, v134
	v_fma_f32 v205, v127, v91, v135
	v_fmac_f32_e32 v202, v104, v116
	v_fmac_f32_e32 v203, v105, v117
	v_fmac_f32_e32 v204, v106, v118
	v_fmac_f32_e32 v205, v107, v119
	v_fmac_f32_e32 v202, v72, v128
	v_fmac_f32_e32 v203, v73, v129
	v_fmac_f32_e32 v204, v74, v130
	v_fmac_f32_e32 v205, v75, v131
	v_fma_f32 v206, v164, v80, v182
	v_fma_f32 v207, v165, v81, v183
	v_fma_f32 v208, v166, v82, v184
	v_fma_f32 v209, v167, v83, v185
	v_fmac_f32_e32 v206, v96, v160
	v_fmac_f32_e32 v207, v97, v161
	v_fmac_f32_e32 v208, v98, v162
	v_fmac_f32_e32 v209, v99, v163
	v_fmac_f32_e32 v206, v64, v178
	v_fmac_f32_e32 v207, v65, v179
	v_fmac_f32_e32 v208, v66, v180
	v_fmac_f32_e32 v209, v67, v181
	v_mul_f32_e32 v210, 0xbfb8aa3b, v202
	v_mul_f32_e32 v211, 0xbfb8aa3b, v203
	v_mul_f32_e32 v212, 0xbfb8aa3b, v204
	v_mul_f32_e32 v213, 0xbfb8aa3b, v205
	v_exp_f32_e32 v210, v210
	v_exp_f32_e32 v211, v211
	v_exp_f32_e32 v212, v212
	v_exp_f32_e32 v213, v213
	v_add_f32_e32 v210, 1.0, v210
	v_add_f32_e32 v211, 1.0, v211
	v_add_f32_e32 v212, 1.0, v212
	v_add_f32_e32 v213, 1.0, v213
	v_rcp_f32_e32 v210, v210
	v_rcp_f32_e32 v211, v211
	v_rcp_f32_e32 v212, v212
	v_rcp_f32_e32 v213, v213
	v_mul_f32_e32 v202, v202, v210
	v_mul_f32_e32 v203, v203, v211
	v_mul_f32_e32 v204, v204, v212
	v_mul_f32_e32 v205, v205, v213
	v_mul_f32_e32 v202, v202, v206
	v_mul_f32_e32 v203, v203, v207
	v_mul_f32_e32 v204, v204, v208
	v_mul_f32_e32 v205, v205, v209
	v_cvt_pk_bf16_f32 v94, v202, v203
	v_cvt_pk_bf16_f32 v95, v204, v205
	v_fma_f32 v202, v124, v72, v132
	v_fma_f32 v203, v125, v73, v133
	v_fma_f32 v204, v126, v74, v134
	v_fma_f32 v205, v127, v75, v135
	v_fmac_f32_e32 v202, v88, v116
	v_fmac_f32_e32 v203, v89, v117
	v_fmac_f32_e32 v204, v90, v118
	v_fmac_f32_e32 v205, v91, v119
	v_fmac_f32_dpp v202, v136, v128 row_shl:1 row_mask:0xf bank_mask:0xf
	v_fmac_f32_dpp v203, v137, v129 row_shl:1 row_mask:0xf bank_mask:0xf
	v_fmac_f32_dpp v204, v138, v130 row_shl:1 row_mask:0xf bank_mask:0xf
	v_fmac_f32_dpp v205, v139, v131 row_shl:1 row_mask:0xf bank_mask:0xf
	v_fmac_f32_e32 v202, v186, v222
	v_fmac_f32_e32 v203, v187, v223
	v_fmac_f32_e32 v204, v188, v224
	v_fmac_f32_e32 v205, v189, v225
	v_fma_f32 v206, v164, v64, v182
	v_fma_f32 v207, v165, v65, v183
	v_fma_f32 v208, v166, v66, v184
	v_fma_f32 v209, v167, v67, v185
	v_fmac_f32_e32 v206, v80, v160
	v_fmac_f32_e32 v207, v81, v161
	v_fmac_f32_e32 v208, v82, v162
	v_fmac_f32_e32 v209, v83, v163
	v_fmac_f32_dpp v206, v112, v178 row_shl:1 row_mask:0xf bank_mask:0xf
	v_fmac_f32_dpp v207, v113, v179 row_shl:1 row_mask:0xf bank_mask:0xf
	v_fmac_f32_dpp v208, v114, v180 row_shl:1 row_mask:0xf bank_mask:0xf
	v_fmac_f32_dpp v209, v115, v181 row_shl:1 row_mask:0xf bank_mask:0xf
	v_fmac_f32_e32 v206, v190, v232
	v_fmac_f32_e32 v207, v191, v233
	v_fmac_f32_e32 v208, v192, v234
	v_fmac_f32_e32 v209, v193, v235
	v_mul_f32_e32 v210, 0xbfb8aa3b, v202
	v_mul_f32_e32 v211, 0xbfb8aa3b, v203
	v_mul_f32_e32 v212, 0xbfb8aa3b, v204
	v_mul_f32_e32 v213, 0xbfb8aa3b, v205
	v_exp_f32_e32 v210, v210
	v_exp_f32_e32 v211, v211
	v_exp_f32_e32 v212, v212
	v_exp_f32_e32 v213, v213
	v_add_f32_e32 v210, 1.0, v210
	v_add_f32_e32 v211, 1.0, v211
	v_add_f32_e32 v212, 1.0, v212
	v_add_f32_e32 v213, 1.0, v213
	v_rcp_f32_e32 v210, v210
	v_rcp_f32_e32 v211, v211
	v_rcp_f32_e32 v212, v212
	v_rcp_f32_e32 v213, v213
	v_mul_f32_e32 v202, v202, v210
	v_mul_f32_e32 v203, v203, v211
	v_mul_f32_e32 v204, v204, v212
	v_mul_f32_e32 v205, v205, v213
	v_mul_f32_e32 v202, v202, v206
	v_mul_f32_e32 v203, v203, v207
	v_mul_f32_e32 v204, v204, v208
	v_mul_f32_e32 v205, v205, v209
	v_cvt_pk_bf16_f32 v78, v202, v203
	v_cvt_pk_bf16_f32 v79, v204, v205
	v_fma_f32 v202, v124, v56, v132
	v_fma_f32 v203, v125, v57, v133
	v_fma_f32 v204, v126, v58, v134
	v_fma_f32 v205, v127, v59, v135
	v_fmac_f32_dpp v202, v8, v116 row_shr:1 row_mask:0xf bank_mask:0xf
	v_fmac_f32_dpp v203, v9, v117 row_shr:1 row_mask:0xf bank_mask:0xf
	v_fmac_f32_dpp v204, v10, v118 row_shr:1 row_mask:0xf bank_mask:0xf
	v_fmac_f32_dpp v205, v11, v119 row_shr:1 row_mask:0xf bank_mask:0xf
	v_fmac_f32_e32 v202, v194, v218
	v_fmac_f32_e32 v203, v195, v219
	v_fmac_f32_e32 v204, v196, v220
	v_fmac_f32_e32 v205, v197, v221
	v_fmac_f32_e32 v202, v40, v128
	v_fmac_f32_e32 v203, v41, v129
	v_fmac_f32_e32 v204, v42, v130
	v_fmac_f32_e32 v205, v43, v131
	v_fma_f32 v206, v164, v48, v182
	v_fma_f32 v207, v165, v49, v183
	v_fma_f32 v208, v166, v50, v184
	v_fma_f32 v209, v167, v51, v185
	v_fmac_f32_dpp v206, v0, v160 row_shr:1 row_mask:0xf bank_mask:0xf
	v_fmac_f32_dpp v207, v1, v161 row_shr:1 row_mask:0xf bank_mask:0xf
	v_fmac_f32_dpp v208, v2, v162 row_shr:1 row_mask:0xf bank_mask:0xf
	v_fmac_f32_dpp v209, v3, v163 row_shr:1 row_mask:0xf bank_mask:0xf
	v_fmac_f32_e32 v206, v198, v226
	v_fmac_f32_e32 v207, v199, v227
	v_fmac_f32_e32 v208, v200, v228
	v_fmac_f32_e32 v209, v201, v229
	v_fmac_f32_e32 v206, v32, v178
	v_fmac_f32_e32 v207, v33, v179
	v_fmac_f32_e32 v208, v34, v180
	v_fmac_f32_e32 v209, v35, v181
	v_mul_f32_e32 v210, 0xbfb8aa3b, v202
	v_mul_f32_e32 v211, 0xbfb8aa3b, v203
	v_mul_f32_e32 v212, 0xbfb8aa3b, v204
	v_mul_f32_e32 v213, 0xbfb8aa3b, v205
	v_exp_f32_e32 v210, v210
	v_exp_f32_e32 v211, v211
	v_exp_f32_e32 v212, v212
	v_exp_f32_e32 v213, v213
	v_add_f32_e32 v210, 1.0, v210
	v_add_f32_e32 v211, 1.0, v211
	v_add_f32_e32 v212, 1.0, v212
	v_add_f32_e32 v213, 1.0, v213
	v_rcp_f32_e32 v210, v210
	v_rcp_f32_e32 v211, v211
	v_rcp_f32_e32 v212, v212
	v_rcp_f32_e32 v213, v213
	v_mul_f32_e32 v202, v202, v210
	v_mul_f32_e32 v203, v203, v211
	v_mul_f32_e32 v204, v204, v212
	v_mul_f32_e32 v205, v205, v213
	v_mul_f32_e32 v202, v202, v206
	v_mul_f32_e32 v203, v203, v207
	v_mul_f32_e32 v204, v204, v208
	v_mul_f32_e32 v205, v205, v209
	v_cvt_pk_bf16_f32 v62, v202, v203
	v_cvt_pk_bf16_f32 v63, v204, v205
	v_fma_f32 v202, v124, v40, v132
	v_fma_f32 v203, v125, v41, v133
	v_fma_f32 v204, v126, v42, v134
	v_fma_f32 v205, v127, v43, v135
	v_fmac_f32_e32 v202, v56, v116
	v_fmac_f32_e32 v203, v57, v117
	v_fmac_f32_e32 v204, v58, v118
	v_fmac_f32_e32 v205, v59, v119
	v_fmac_f32_e32 v202, v24, v128
	v_fmac_f32_e32 v203, v25, v129
	v_fmac_f32_e32 v204, v26, v130
	v_fmac_f32_e32 v205, v27, v131
	v_fma_f32 v206, v164, v32, v182
	v_fma_f32 v207, v165, v33, v183
	v_fma_f32 v208, v166, v34, v184
	v_fma_f32 v209, v167, v35, v185
	v_fmac_f32_e32 v206, v48, v160
	v_fmac_f32_e32 v207, v49, v161
	v_fmac_f32_e32 v208, v50, v162
	v_fmac_f32_e32 v209, v51, v163
	v_fmac_f32_e32 v206, v16, v178
	v_fmac_f32_e32 v207, v17, v179
	v_fmac_f32_e32 v208, v18, v180
	v_fmac_f32_e32 v209, v19, v181
	v_mul_f32_e32 v210, 0xbfb8aa3b, v202
	v_mul_f32_e32 v211, 0xbfb8aa3b, v203
	v_mul_f32_e32 v212, 0xbfb8aa3b, v204
	v_mul_f32_e32 v213, 0xbfb8aa3b, v205
	v_exp_f32_e32 v210, v210
	v_exp_f32_e32 v211, v211
	v_exp_f32_e32 v212, v212
	v_exp_f32_e32 v213, v213
	v_add_f32_e32 v210, 1.0, v210
	v_add_f32_e32 v211, 1.0, v211
	v_add_f32_e32 v212, 1.0, v212
	v_add_f32_e32 v213, 1.0, v213
	v_rcp_f32_e32 v210, v210
	v_rcp_f32_e32 v211, v211
	v_rcp_f32_e32 v212, v212
	v_rcp_f32_e32 v213, v213
	v_mul_f32_e32 v202, v202, v210
	v_mul_f32_e32 v203, v203, v211
	v_mul_f32_e32 v204, v204, v212
	v_mul_f32_e32 v205, v205, v213
	v_mul_f32_e32 v202, v202, v206
	v_mul_f32_e32 v203, v203, v207
	v_mul_f32_e32 v204, v204, v208
	v_mul_f32_e32 v205, v205, v209
	v_cvt_pk_bf16_f32 v46, v202, v203
	v_cvt_pk_bf16_f32 v47, v204, v205
	v_fma_f32 v202, v124, v24, v132
	v_fma_f32 v203, v125, v25, v133
	v_fma_f32 v204, v126, v26, v134
	v_fma_f32 v205, v127, v27, v135
	v_fmac_f32_e32 v202, v40, v116
	v_fmac_f32_e32 v203, v41, v117
	v_fmac_f32_e32 v204, v42, v118
	v_fmac_f32_e32 v205, v43, v119
	v_fmac_f32_e32 v202, v8, v128
	v_fmac_f32_e32 v203, v9, v129
	v_fmac_f32_e32 v204, v10, v130
	v_fmac_f32_e32 v205, v11, v131
	v_fma_f32 v206, v164, v16, v182
	v_fma_f32 v207, v165, v17, v183
	v_fma_f32 v208, v166, v18, v184
	v_fma_f32 v209, v167, v19, v185
	v_fmac_f32_e32 v206, v32, v160
	v_fmac_f32_e32 v207, v33, v161
	v_fmac_f32_e32 v208, v34, v162
	v_fmac_f32_e32 v209, v35, v163
	v_fmac_f32_e32 v206, v0, v178
	v_fmac_f32_e32 v207, v1, v179
	v_fmac_f32_e32 v208, v2, v180
	v_fmac_f32_e32 v209, v3, v181
	v_mul_f32_e32 v210, 0xbfb8aa3b, v202
	v_mul_f32_e32 v211, 0xbfb8aa3b, v203
	v_mul_f32_e32 v212, 0xbfb8aa3b, v204
	v_mul_f32_e32 v213, 0xbfb8aa3b, v205
	v_exp_f32_e32 v210, v210
	v_exp_f32_e32 v211, v211
	v_exp_f32_e32 v212, v212
	v_exp_f32_e32 v213, v213
	v_add_f32_e32 v210, 1.0, v210
	v_add_f32_e32 v211, 1.0, v211
	v_add_f32_e32 v212, 1.0, v212
	v_add_f32_e32 v213, 1.0, v213
	v_rcp_f32_e32 v210, v210
	v_rcp_f32_e32 v211, v211
	v_rcp_f32_e32 v212, v212
	v_rcp_f32_e32 v213, v213
	v_mul_f32_e32 v202, v202, v210
	v_mul_f32_e32 v203, v203, v211
	v_mul_f32_e32 v204, v204, v212
	v_mul_f32_e32 v205, v205, v213
	v_mul_f32_e32 v202, v202, v206
	v_mul_f32_e32 v203, v203, v207
	v_mul_f32_e32 v204, v204, v208
	v_mul_f32_e32 v205, v205, v209
	v_cvt_pk_bf16_f32 v30, v202, v203
	v_cvt_pk_bf16_f32 v31, v204, v205
	v_fma_f32 v202, v124, v8, v132
	v_fma_f32 v203, v125, v9, v133
	v_fma_f32 v204, v126, v10, v134
	v_fma_f32 v205, v127, v11, v135
	v_fmac_f32_e32 v202, v24, v116
	v_fmac_f32_e32 v203, v25, v117
	v_fmac_f32_e32 v204, v26, v118
	v_fmac_f32_e32 v205, v27, v119
	v_fmac_f32_dpp v202, v56, v128 row_shl:1 row_mask:0xf bank_mask:0xf
	v_fmac_f32_dpp v203, v57, v129 row_shl:1 row_mask:0xf bank_mask:0xf
	v_fmac_f32_dpp v204, v58, v130 row_shl:1 row_mask:0xf bank_mask:0xf
	v_fmac_f32_dpp v205, v59, v131 row_shl:1 row_mask:0xf bank_mask:0xf
	v_fmac_f32_e32 v202, v194, v222
	v_fmac_f32_e32 v203, v195, v223
	v_fmac_f32_e32 v204, v196, v224
	v_fmac_f32_e32 v205, v197, v225
	v_fma_f32 v206, v164, v0, v182
	v_fma_f32 v207, v165, v1, v183
	v_fma_f32 v208, v166, v2, v184
	v_fma_f32 v209, v167, v3, v185
	v_fmac_f32_e32 v206, v16, v160
	v_fmac_f32_e32 v207, v17, v161
	v_fmac_f32_e32 v208, v18, v162
	v_fmac_f32_e32 v209, v19, v163
	v_fmac_f32_dpp v206, v48, v178 row_shl:1 row_mask:0xf bank_mask:0xf
	v_fmac_f32_dpp v207, v49, v179 row_shl:1 row_mask:0xf bank_mask:0xf
	v_fmac_f32_dpp v208, v50, v180 row_shl:1 row_mask:0xf bank_mask:0xf
	v_fmac_f32_dpp v209, v51, v181 row_shl:1 row_mask:0xf bank_mask:0xf
	v_fmac_f32_e32 v206, v198, v232
	v_fmac_f32_e32 v207, v199, v233
	v_fmac_f32_e32 v208, v200, v234
	v_fmac_f32_e32 v209, v201, v235
	v_mul_f32_e32 v210, 0xbfb8aa3b, v202
	v_mul_f32_e32 v211, 0xbfb8aa3b, v203
	v_mul_f32_e32 v212, 0xbfb8aa3b, v204
	v_mul_f32_e32 v213, 0xbfb8aa3b, v205
	v_exp_f32_e32 v210, v210
	v_exp_f32_e32 v211, v211
	v_exp_f32_e32 v212, v212
	v_exp_f32_e32 v213, v213
	v_add_f32_e32 v210, 1.0, v210
	v_add_f32_e32 v211, 1.0, v211
	v_add_f32_e32 v212, 1.0, v212
	v_add_f32_e32 v213, 1.0, v213
	v_rcp_f32_e32 v210, v210
	v_rcp_f32_e32 v211, v211
	v_rcp_f32_e32 v212, v212
	v_rcp_f32_e32 v213, v213
	v_mul_f32_e32 v202, v202, v210
	v_mul_f32_e32 v203, v203, v211
	v_mul_f32_e32 v204, v204, v212
	v_mul_f32_e32 v205, v205, v213
	v_mul_f32_e32 v202, v202, v206
	v_mul_f32_e32 v203, v203, v207
	v_mul_f32_e32 v204, v204, v208
	v_mul_f32_e32 v205, v205, v209
	v_cvt_pk_bf16_f32 v14, v202, v203
	v_cvt_pk_bf16_f32 v15, v204, v205
	global_store_dwordx4 v168, v[140:143], s[4:5]
	v_add_u32_e32 v250, 0x1600, v168
	global_store_dwordx4 v250, v[108:111], s[4:5]
	s_nop 0
	v_add_u32_e32 v250, 0x2c00, v168
	global_store_dwordx4 v250, v[92:95], s[4:5]
	s_nop 0
	v_add_u32_e32 v250, 0x4200, v168
	global_store_dwordx4 v250, v[76:79], s[4:5]
	s_nop 0
	v_add_u32_e32 v250, 0xb0000, v168
	global_store_dwordx4 v250, v[60:63], s[4:5]
	s_nop 0
	v_add_u32_e32 v250, 0xb1600, v168
	global_store_dwordx4 v250, v[44:47], s[4:5]
	s_nop 0
	v_add_u32_e32 v250, 0xb2c00, v168
	global_store_dwordx4 v250, v[28:31], s[4:5]
	s_nop 0
	v_add_u32_e32 v250, 0xb4200, v168
	global_store_dwordx4 v250, v[12:15], s[4:5]
	s_nop 0
	s_and_b64 s[2:3], s[6:7], exec
	s_cbranch_scc0 .LepB_nonext
	s_xor_b32 s101, s101, 1
	s_or_b32 s101, s101, 2
	s_and_b32 s57, s101, 1
	s_mulk_i32 s57, 0x1800
	s_add_i32 s57, s57, 0x22c00
	v_readfirstlane_b32 s67, v230
	s_cmp_lt_u32 s67, 64
	s_cbranch_scc0 .LepB_nfe
	s_add_i32 s4, s56, -32
	s_ashr_i32 s4, s4, 2
	s_add_i32 s4, s4, 1
	s_cmp_gt_i32 s56, 31
	s_cselect_b32 s4, s4, 0
	s_mul_hi_i32 s5, s4, 0x5800
	s_mulk_i32 s4, 0x5800
	v_readlane_b32 s67, v254, 49
	v_readlane_b32 s95, v254, 50
	s_nop 0
	s_add_u32 s4, s67, s4
	s_addc_u32 s5, s95, s5
	v_readlane_b32 s2, v254, 5
	v_readlane_b32 s3, v254, 6
	v_readlane_b32 s28, v254, 7
	v_readlane_b32 s29, v254, 8
	s_nop 0
	v_and_b32_e32 v238, 63, v230
	v_lshrrev_b32_e32 v239, 5, v238
	v_and_b32_e32 v240, 31, v238
	v_lshlrev_b32_e32 v240, 4, v240
	s_lshl_b32 s67, s54, 9
	v_add_u32_e32 v240, s67, v240
	v_mul_u32_u24_e32 v241, 0x2c00, v239
	v_mul_u32_u24_e32 v242, 0x5800, v239
	v_add_u32_e32 v241, v241, v240
	v_add_u32_e32 v242, v242, v240
	v_lshlrev_b32_e32 v243, 4, v238
	s_lshl_b32 s67, s56, 10
	v_add_u32_e32 v243, s67, v243
	s_mov_b32 m0, s57
	s_nop 0
	global_load_lds_dwordx4 v243, s[10:11]
	s_add_i32 m0, s57, 1024
	s_nop 0
	global_load_lds_dwordx4 v241, s[4:5]
	s_add_i32 m0, s57, 2048
	s_nop 0
	global_load_lds_dwordx4 v242, s[2:3]
	v_add_u32_e32 v243, 0x2c00, v242
	s_add_i32 m0, s57, 3072
	s_nop 0
	global_load_lds_dwordx4 v243, s[2:3]
	v_add_u32_e32 v243, 0xb000, v241
	s_add_i32 m0, s57, 4096
	s_nop 0
	global_load_lds_dwordx4 v243, s[2:3]
	s_add_i32 m0, s57, 5120
	s_nop 0
	global_load_lds_dwordx4 v241, s[28:29]
.LepB_nfe:
.LepB_nonext:
	s_andn2_b64 vcc, exec, s[6:7]
	s_mov_b64 s[4:5], -1
	s_cbranch_vccnz .LBB0_824
	s_andn2_b64 vcc, exec, s[12:13]
	s_cbranch_vccnz .LBB0_823
	s_barrier
	s_branch .LBB0_823

.LBB0_957:
	s_cmp_gt_i32 s72, 9
	s_cselect_b64 s[4:5], -1, 0
	s_cmp_lt_i32 s73, 10
	s_cselect_b64 s[6:7], -1, 0
	s_or_b64 s[4:5], s[4:5], s[6:7]
	s_and_b64 vcc, exec, s[4:5]
	s_cbranch_vccnz .LBB0_1038
	v_readlane_b32 s2, v255, 2
	v_mov_b32_e32 v14, v230
	v_readlane_b32 s3, v255, 3
	s_and_b64 vcc, exec, s[2:3]
	v_readfirstlane_b32 s5, v14
	s_cbranch_vccnz .LBB0_973
	v_lshlrev_b32_e32 v0, 4, v14
	s_waitcnt lgkmcnt(0)
	v_add_u32_e32 v1, 0x2000, v0
	v_ashrrev_i32_e32 v2, 31, v1
	v_lshrrev_b32_e32 v2, 22, v2
	v_add_u32_e32 v2, v1, v2
	v_ashrrev_i32_e32 v8, 10, v2
	v_mul_i32_i24_e32 v2, 0x400, v8
	v_sub_u32_e32 v1, v1, v2
	v_lshrrev_b32_e32 v2, 4, v1
	v_bitop3_b32 v1, v2, v1, 32 bitop3:0x6c
	v_ashrrev_i32_e32 v2, 31, v1
	v_lshrrev_b32_e32 v2, 26, v2
	v_add_u32_e32 v2, v1, v2
	v_lshlrev_b32_e32 v3, 3, v8
	v_ashrrev_i32_e32 v9, 6, v2
	v_and_b32_e32 v3, -16, v3
	v_add_u32_e32 v3, v9, v3
	v_and_b32_e32 v4, 3, v9
	s_mov_b32 s4, 0x1fffe0
	v_lshrrev_b32_e32 v5, 2, v3
	v_lshlrev_b32_e32 v6, 1, v3
	v_and_b32_e32 v2, 0xc0, v2
	v_and_or_b32 v4, v3, s4, v4
	v_and_b32_e32 v5, 4, v5
	v_and_b32_e32 v6, 24, v6
	v_sub_u32_e32 v1, v1, v2
	v_mov_b32_e32 v2, 1
	v_or3_b32 v4, v4, v5, v6
	v_lshlrev_b32_e32 v5, 5, v8
	v_ashrrev_i16_sdwa v1, v2, sext(v1) dst_sel:DWORD dst_unused:UNUSED_PAD src0_sel:DWORD src1_sel:BYTE_0
	v_and_b32_e32 v5, 32, v5
	v_bfe_i32 v10, v1, 0, 16
	v_add_lshl_u32 v1, v5, v10, 1
	v_lshl_add_u32 v144, v4, 11, v1
	v_lshl_add_u32 v146, v3, 11, v1
	v_lshrrev_b32_e32 v248, 11, v146
	v_and_b32_e32 v249, 0x7ff, v146
	v_and_b32_e32 v250, 15, v248
	v_lshlrev_b32_e32 v250, 2, v250
	v_bfe_u32 v251, v248, 4, 2
	v_and_or_b32 v248, v248, 64, v250
	v_or_b32_e32 v248, v248, v251
	v_lshl_or_b32 v146, v248, 11, v249
	v_bfe_i32 v1, v14, 27, 1
	v_lshrrev_b32_e32 v1, 22, v1
	v_add_u32_e32 v1, v0, v1
	v_and_b32_e32 v1, 0xfffffc00, v1
	v_sub_u32_e32 v0, v0, v1
	v_lshrrev_b32_e32 v1, 4, v0
	v_ashrrev_i32_e32 v3, 31, v14
	v_bitop3_b32 v0, v1, v0, 32 bitop3:0x6c
	v_lshrrev_b32_e32 v3, 26, v3
	v_ashrrev_i32_e32 v1, 31, v0
	v_add_u32_e32 v3, v14, v3
	s_add_u32 s0, s70, 0x4b00000
	v_lshrrev_b32_e32 v1, 26, v1
	v_ashrrev_i32_e32 v12, 6, v3
	s_addc_u32 s20, s71, 0
	s_ashr_i32 s6, s5, 6
	v_add_u32_e32 v1, v0, v1
	v_lshlrev_b32_e32 v3, 3, v12
	v_readlane_b32 s2, v254, 62
	s_ashr_i32 s7, s5, 8
	s_lshl_b32 s21, s6, 10
	v_ashrrev_i32_e32 v11, 6, v1
	v_and_b32_e32 v3, -16, v3
	v_readlane_b32 s3, v254, 63
	v_add_u32_e32 v3, v11, v3
	v_and_b32_e32 v4, 3, v11
	s_movk_i32 s30, 0x59
	s_and_b64 s[10:11], s[2:3], exec
	v_and_or_b32 v4, v3, s4, v4
	s_cselect_b32 s4, s30, 0x58
	v_readlane_b32 s2, v254, 51
	s_mul_i32 s4, s4, s2
	v_readlane_b32 s2, v254, 61
	s_add_i32 s4, s4, s2
	s_mul_hi_i32 s10, s4, 0x2e8ba2e9
	s_lshr_b32 s11, s10, 31
	s_ashr_i32 s10, s10, 5
	s_add_i32 s10, s10, s11
	s_lshl_b32 s11, s10, 3
	s_mulk_i32 s10, 0xb0
	s_sub_i32 s10, s4, s10
	s_bfe_u32 s4, s10, 0x3001c
	s_add_i32 s12, s10, s4
	s_sext_i32_i16 s4, s12
	s_and_b32 s12, s12, 0xfff8
	s_sub_i32 s10, s10, s12
	s_sext_i32_i16 s10, s10
	v_lshrrev_b32_e32 v5, 2, v3
	v_lshlrev_b32_e32 v6, 1, v3
	v_and_b32_e32 v1, 0xc0, v1
	s_lshr_b32 s4, s4, 3
	s_add_i32 s88, s11, s10
	v_and_b32_e32 v5, 4, v5
	v_and_b32_e32 v6, 24, v6
	v_sub_u32_e32 v0, v0, v1
	s_ashr_i32 s89, s88, 31
	s_bfe_i64 s[12:13], s[4:5], 0x100000
	v_or3_b32 v4, v4, v5, v6
	v_lshlrev_b32_e32 v5, 5, v12
	v_ashrrev_i16_sdwa v0, v2, sext(v0) dst_sel:DWORD dst_unused:UNUSED_PAD src0_sel:DWORD src1_sel:BYTE_0
	s_lshl_b64 s[10:11], s[88:89], 19
	s_lshl_b64 s[12:13], s[12:13], 18
	v_and_b32_e32 v5, 32, v5
	v_bfe_i32 v13, v0, 0, 16
	s_add_u32 s92, s33, s12
	v_add_lshl_u32 v0, v5, v13, 1
	s_addc_u32 s93, s82, s13
	s_add_i32 s31, s21, 0
	v_lshl_add_u32 v148, v4, 11, v0
	s_add_i32 m0, s31, 0x10000
	v_lshl_add_u32 v150, v3, 11, v0
	v_lshrrev_b32_e32 v248, 11, v150
	v_and_b32_e32 v249, 0x7ff, v150
	v_and_b32_e32 v250, 15, v248
	v_lshlrev_b32_e32 v250, 2, v250
	v_bfe_u32 v251, v248, 4, 2
	v_and_or_b32 v248, v248, 64, v250
	v_or_b32_e32 v248, v248, v251
	v_lshl_or_b32 v150, v248, 11, v249
	global_load_lds_dwordx4 v148, s[92:93]
	s_add_i32 m0, s31, 0x12000
	s_add_u32 s12, s92, 0x580000
	global_load_lds_dwordx4 v144, s[92:93]
	s_addc_u32 s13, s93, 0
	s_add_i32 m0, s31, 0x14000
	v_mov_b32_e32 v149, 0
	global_load_lds_dwordx4 v148, s[12:13]
	s_add_i32 m0, s31, 0x16000
	s_add_u32 s90, s0, s10
	s_addc_u32 s91, s20, s11
	s_add_i32 s52, s31, 0x2000
	global_load_lds_dwordx4 v144, s[12:13]
	s_mov_b32 m0, s31
	s_add_u32 s10, s90, 0x40000
	global_load_lds_dwordx4 v150, s[90:91]
	s_mov_b32 m0, s52
	s_addc_u32 s11, s91, 0
	s_add_i32 s53, s31, 0x4000
	global_load_lds_dwordx4 v146, s[90:91]
	s_mov_b32 m0, s53
	s_add_i32 s58, s31, 0x6000
	global_load_lds_dwordx4 v150, s[10:11]
	s_mov_b32 m0, s58
	v_mov_b32_e32 v145, v149
	global_load_lds_dwordx4 v146, s[10:11]
	v_mov_b32_e32 v151, v149
	v_mov_b32_e32 v147, v149
	s_cmp_eq_u32 s7, 1
	s_mov_b32 s59, 0
	s_mov_b32 s101, 0
	v_lshl_add_u64 v[6:7], s[92:93], 0, v[148:149]
	v_lshl_add_u64 v[4:5], s[92:93], 0, v[144:145]
	v_lshl_add_u64 v[0:1], s[90:91], 0, v[150:151]
	s_cselect_b64 s[10:11], -1, 0
	s_cmp_lg_u32 s7, 1
	v_lshl_add_u64 v[2:3], s[90:91], 0, v[146:147]
	s_cbranch_scc1 .LBB0_961
	s_barrier

.LBB0_970:
	s_and_b32 s55, s101, 1
	s_mulk_i32 s55, 0x1800
	s_add_i32 s55, s55, 0x22c00
	s_bitcmp1_b32 s101, 1
	s_cbranch_scc1 .LepD_fast
	v_readfirstlane_b32 s57, v230
	s_cmp_lt_u32 s57, 64
	s_cbranch_scc0 .LepD_nfs
	s_add_i32 s4, s88, 0
	s_ashr_i32 s4, s4, 2
	s_add_i32 s4, s4, 1
	s_cmp_gt_i32 s88, -1
	s_cselect_b32 s4, s4, 0
	s_mul_hi_i32 s5, s4, 0x5800
	s_mulk_i32 s4, 0x5800
	v_readlane_b32 s57, v254, 49
	v_readlane_b32 s99, v254, 50
	s_nop 0
	s_add_u32 s4, s57, s4
	s_addc_u32 s5, s99, s5
	v_readlane_b32 s2, v254, 5
	v_readlane_b32 s3, v254, 6
	v_readlane_b32 s28, v254, 7
	v_readlane_b32 s29, v254, 8
	s_nop 0
	v_and_b32_e32 v238, 63, v230
	v_lshrrev_b32_e32 v239, 5, v238
	v_and_b32_e32 v240, 31, v238
	v_lshlrev_b32_e32 v240, 4, v240
	s_lshl_b32 s57, s66, 9
	v_add_u32_e32 v240, s57, v240
	v_mul_u32_u24_e32 v241, 0x2c00, v239
	v_mul_u32_u24_e32 v242, 0x5800, v239
	v_add_u32_e32 v241, v241, v240
	v_add_u32_e32 v242, v242, v240
	v_lshlrev_b32_e32 v243, 4, v238
	s_lshl_b32 s57, s88, 10
	v_add_u32_e32 v243, s57, v243
	s_mov_b32 m0, s55
	s_nop 0
	global_load_lds_dwordx4 v243, s[12:13]
	s_add_i32 m0, s55, 1024
	s_nop 0
	global_load_lds_dwordx4 v241, s[4:5]
	s_add_i32 m0, s55, 2048
	s_nop 0
	global_load_lds_dwordx4 v242, s[2:3]
	v_add_u32_e32 v243, 0x2c00, v242
	s_add_i32 m0, s55, 3072
	s_nop 0
	global_load_lds_dwordx4 v243, s[2:3]
	v_add_u32_e32 v243, 0xb000, v241
	s_add_i32 m0, s55, 4096
	s_nop 0
	global_load_lds_dwordx4 v243, s[2:3]
	s_add_i32 m0, s55, 5120
	s_nop 0
	global_load_lds_dwordx4 v241, s[28:29]

.LepD_fast:
	s_and_b32 s32, s10, 1
	v_and_b32_e32 v237, 15, v170
	v_and_b32_e32 v236, 64, v170
	v_lshl_add_u32 v236, v237, 2, v236
	v_mul_u32_u24_e32 v168, 0x1600, v236
	v_lshl_add_u32 v168, v172, 1, v168
	v_lshl_add_u32 v236, v236, 2, s55
	v_lshl_add_u32 v177, v172, 2, s55
	ds_read_b128 v[210:213], v236
	ds_read_b128 v[214:217], v236 offset:512
	ds_read_b128 v[202:205], v177 offset:1024
	ds_read_b128 v[206:209], v177 offset:1040
	ds_read_b128 v[218:221], v177 offset:1536
	ds_read_b128 v[222:225], v177 offset:1552
	ds_read_b128 v[116:119], v177 offset:2048
	ds_read_b128 v[124:127], v177 offset:2560
	ds_read_b128 v[128:131], v177 offset:4096
	ds_read_b128 v[132:135], v177 offset:5120
	ds_read_b128 v[160:163], v177 offset:3072
	ds_read_b128 v[164:167], v177 offset:3584
	ds_read_b128 v[178:181], v177 offset:4608
	ds_read_b128 v[182:185], v177 offset:5632
	s_mul_i32 s4, s88, 0x160000
	s_lshl_b32 s57, s66, 8
	s_add_i32 s4, s4, s57
	s_add_i32 s4, s4, 0xbf00000
	s_add_u32 s4, s4, s70
	s_addc_u32 s5, s71, 0
	s_mov_b32 s57, 0x20800
	v_lshl_add_u32 v169, v172, 2, s57
	v_cmp_eq_u32_e64 s[2:3], 0, v237
	v_cmp_eq_u32_e64 s[28:29], 15, v237
	v_and_b32_e32 v231, 8, v237
	v_lshlrev_b32_e32 v231, 9, v231
	s_lshl_b32 s57, s32, 10
	v_add3_u32 v231, v231, v169, s57
	s_waitcnt lgkmcnt(12)
	v_fmamk_f32 v210, v210, 0x3a800000, v176
	v_fmamk_f32 v211, v211, 0x3a800000, v176
	v_fmamk_f32 v212, v212, 0x3a800000, v176
	v_fmamk_f32 v213, v213, 0x3a800000, v176
	v_fmamk_f32 v214, v214, 0x3a800000, v176
	v_fmamk_f32 v215, v215, 0x3a800000, v176
	v_fmamk_f32 v216, v216, 0x3a800000, v176
	v_fmamk_f32 v217, v217, 0x3a800000, v176
	s_mov_b32 s57, 0x800000
	v_mul_f32_e32 v226, 0x4b800000, v210
	v_mul_f32_e32 v227, 0x4b800000, v211
	v_mul_f32_e32 v228, 0x4b800000, v212
	v_mul_f32_e32 v229, 0x4b800000, v213
	v_mul_f32_e32 v232, 0x4b800000, v214
	v_mul_f32_e32 v233, 0x4b800000, v215
	v_mul_f32_e32 v234, 0x4b800000, v216
	v_mul_f32_e32 v235, 0x4b800000, v217
	v_cmp_gt_f32_e32 vcc, s57, v210
	s_nop 1
	v_cndmask_b32_e32 v210, v210, v226, vcc
	v_rsq_f32_e32 v210, v210
	s_nop 0
	v_mul_f32_e32 v226, 0x45800000, v210
	v_cndmask_b32_e32 v210, v210, v226, vcc
	v_cmp_gt_f32_e32 vcc, s57, v211
	s_nop 1
	v_cndmask_b32_e32 v211, v211, v227, vcc
	v_rsq_f32_e32 v211, v211
	s_nop 0
	v_mul_f32_e32 v227, 0x45800000, v211
	v_cndmask_b32_e32 v211, v211, v227, vcc
	v_cmp_gt_f32_e32 vcc, s57, v212
	s_nop 1
	v_cndmask_b32_e32 v212, v212, v228, vcc
	v_rsq_f32_e32 v212, v212
	s_nop 0
	v_mul_f32_e32 v228, 0x45800000, v212
	v_cndmask_b32_e32 v212, v212, v228, vcc
	v_cmp_gt_f32_e32 vcc, s57, v213
	s_nop 1
	v_cndmask_b32_e32 v213, v213, v229, vcc
	v_rsq_f32_e32 v213, v213
	s_nop 0
	v_mul_f32_e32 v229, 0x45800000, v213
	v_cndmask_b32_e32 v213, v213, v229, vcc
	v_cmp_gt_f32_e32 vcc, s57, v214
	s_nop 1
	v_cndmask_b32_e32 v214, v214, v232, vcc
	v_rsq_f32_e32 v214, v214
	s_nop 0
	v_mul_f32_e32 v232, 0x45800000, v214
	v_cndmask_b32_e32 v214, v214, v232, vcc
	v_cmp_gt_f32_e32 vcc, s57, v215
	s_nop 1
	v_cndmask_b32_e32 v215, v215, v233, vcc
	v_rsq_f32_e32 v215, v215
	s_nop 0
	v_mul_f32_e32 v233, 0x45800000, v215
	v_cndmask_b32_e32 v215, v215, v233, vcc
	v_cmp_gt_f32_e32 vcc, s57, v216
	s_nop 1
	v_cndmask_b32_e32 v216, v216, v234, vcc
	v_rsq_f32_e32 v216, v216
	s_nop 0
	v_mul_f32_e32 v234, 0x45800000, v216
	v_cndmask_b32_e32 v216, v216, v234, vcc
	v_cmp_gt_f32_e32 vcc, s57, v217
	s_nop 1
	v_cndmask_b32_e32 v217, v217, v235, vcc
	v_rsq_f32_e32 v217, v217
	s_nop 0
	v_mul_f32_e32 v235, 0x45800000, v217
	v_cndmask_b32_e32 v217, v217, v235, vcc
	s_waitcnt lgkmcnt(8)
	v_fma_f32 v140, v140, v210, v202
	v_fma_f32 v141, v141, v210, v203
	v_fma_f32 v142, v142, v210, v204
	v_fma_f32 v143, v143, v210, v205
	v_fma_f32 v136, v136, v210, v206
	v_fma_f32 v137, v137, v210, v207
	v_fma_f32 v138, v138, v210, v208
	v_fma_f32 v139, v139, v210, v209
	v_fma_f32 v120, v120, v210, v218
	v_fma_f32 v121, v121, v210, v219
	v_fma_f32 v122, v122, v210, v220
	v_fma_f32 v123, v123, v210, v221
	v_fma_f32 v112, v112, v210, v222
	v_fma_f32 v113, v113, v210, v223
	v_fma_f32 v114, v114, v210, v224
	v_fma_f32 v115, v115, v210, v225
	v_fma_f32 v108, v108, v211, v202
	v_fma_f32 v109, v109, v211, v203
	v_fma_f32 v110, v110, v211, v204
	v_fma_f32 v111, v111, v211, v205
	v_fma_f32 v104, v104, v211, v206
	v_fma_f32 v105, v105, v211, v207
	v_fma_f32 v106, v106, v211, v208
	v_fma_f32 v107, v107, v211, v209
	v_fma_f32 v100, v100, v211, v218
	v_fma_f32 v101, v101, v211, v219
	v_fma_f32 v102, v102, v211, v220
	v_fma_f32 v103, v103, v211, v221
	v_fma_f32 v96, v96, v211, v222
	v_fma_f32 v97, v97, v211, v223
	v_fma_f32 v98, v98, v211, v224
	v_fma_f32 v99, v99, v211, v225
	v_fma_f32 v92, v92, v212, v202
	v_fma_f32 v93, v93, v212, v203
	v_fma_f32 v94, v94, v212, v204
	v_fma_f32 v95, v95, v212, v205
	v_fma_f32 v88, v88, v212, v206
	v_fma_f32 v89, v89, v212, v207
	v_fma_f32 v90, v90, v212, v208
	v_fma_f32 v91, v91, v212, v209
	v_fma_f32 v84, v84, v212, v218
	v_fma_f32 v85, v85, v212, v219
	v_fma_f32 v86, v86, v212, v220
	v_fma_f32 v87, v87, v212, v221
	v_fma_f32 v80, v80, v212, v222
	v_fma_f32 v81, v81, v212, v223
	v_fma_f32 v82, v82, v212, v224
	v_fma_f32 v83, v83, v212, v225
	v_fma_f32 v76, v76, v213, v202
	v_fma_f32 v77, v77, v213, v203
	v_fma_f32 v78, v78, v213, v204
	v_fma_f32 v79, v79, v213, v205
	v_fma_f32 v72, v72, v213, v206
	v_fma_f32 v73, v73, v213, v207
	v_fma_f32 v74, v74, v213, v208
	v_fma_f32 v75, v75, v213, v209
	v_fma_f32 v68, v68, v213, v218
	v_fma_f32 v69, v69, v213, v219
	v_fma_f32 v70, v70, v213, v220
	v_fma_f32 v71, v71, v213, v221
	v_fma_f32 v64, v64, v213, v222
	v_fma_f32 v65, v65, v213, v223
	v_fma_f32 v66, v66, v213, v224
	v_fma_f32 v67, v67, v213, v225
	v_fma_f32 v60, v60, v214, v202
	v_fma_f32 v61, v61, v214, v203
	v_fma_f32 v62, v62, v214, v204
	v_fma_f32 v63, v63, v214, v205
	v_fma_f32 v56, v56, v214, v206
	v_fma_f32 v57, v57, v214, v207
	v_fma_f32 v58, v58, v214, v208
	v_fma_f32 v59, v59, v214, v209
	v_fma_f32 v52, v52, v214, v218
	v_fma_f32 v53, v53, v214, v219
	v_fma_f32 v54, v54, v214, v220
	v_fma_f32 v55, v55, v214, v221
	v_fma_f32 v48, v48, v214, v222
	v_fma_f32 v49, v49, v214, v223
	v_fma_f32 v50, v50, v214, v224
	v_fma_f32 v51, v51, v214, v225
	v_fma_f32 v44, v44, v215, v202
	v_fma_f32 v45, v45, v215, v203
	v_fma_f32 v46, v46, v215, v204
	v_fma_f32 v47, v47, v215, v205
	v_fma_f32 v40, v40, v215, v206
	v_fma_f32 v41, v41, v215, v207
	v_fma_f32 v42, v42, v215, v208
	v_fma_f32 v43, v43, v215, v209
	v_fma_f32 v36, v36, v215, v218
	v_fma_f32 v37, v37, v215, v219
	v_fma_f32 v38, v38, v215, v220
	v_fma_f32 v39, v39, v215, v221
	v_fma_f32 v32, v32, v215, v222
	v_fma_f32 v33, v33, v215, v223
	v_fma_f32 v34, v34, v215, v224
	v_fma_f32 v35, v35, v215, v225
	v_fma_f32 v28, v28, v216, v202
	v_fma_f32 v29, v29, v216, v203
	v_fma_f32 v30, v30, v216, v204
	v_fma_f32 v31, v31, v216, v205
	v_fma_f32 v24, v24, v216, v206
	v_fma_f32 v25, v25, v216, v207
	v_fma_f32 v26, v26, v216, v208
	v_fma_f32 v27, v27, v216, v209
	v_fma_f32 v20, v20, v216, v218
	v_fma_f32 v21, v21, v216, v219
	v_fma_f32 v22, v22, v216, v220
	v_fma_f32 v23, v23, v216, v221
	v_fma_f32 v16, v16, v216, v222
	v_fma_f32 v17, v17, v216, v223
	v_fma_f32 v18, v18, v216, v224
	v_fma_f32 v19, v19, v216, v225
	v_fma_f32 v12, v12, v217, v202
	v_fma_f32 v13, v13, v217, v203
	v_fma_f32 v14, v14, v217, v204
	v_fma_f32 v15, v15, v217, v205
	v_fma_f32 v8, v8, v217, v206
	v_fma_f32 v9, v9, v217, v207
	v_fma_f32 v10, v10, v217, v208
	v_fma_f32 v11, v11, v217, v209
	v_fma_f32 v4, v4, v217, v218
	v_fma_f32 v5, v5, v217, v219
	v_fma_f32 v6, v6, v217, v220
	v_fma_f32 v7, v7, v217, v221
	v_fma_f32 v0, v0, v217, v222
	v_fma_f32 v1, v1, v217, v223
	v_fma_f32 v2, v2, v217, v224
	v_fma_f32 v3, v3, v217, v225
	v_mov_b32_e32 v214, 0
	v_mov_b32_e32 v215, 0
	v_mov_b32_e32 v216, 0
	v_mov_b32_e32 v217, 0
	s_lshl_b32 s67, s32, 12
	s_sub_i32 s67, 0x2000, s67
	s_mul_i32 s89, s32, 0x1400
	s_add_i32 s89, s89, 0xc00
	s_lshl_b32 s57, s32, 10
	s_add_i32 s100, s57, 5120
	s_add_i32 s98, s57, 1024
	s_mov_b64 exec, s[2:3]
	v_add_u32_e32 v250, s67, v169
	ds_write_b128 v250, v[140:143] offset:0
	ds_write_b128 v250, v[136:139] offset:16
	ds_write_b128 v250, v[120:123] offset:512
	ds_write_b128 v250, v[112:115] offset:528
	v_add_u32_e32 v250, s100, v169
	ds_write_b128 v250, v[60:63] offset:0
	ds_write_b128 v250, v[56:59] offset:16
	ds_write_b128 v250, v[52:55] offset:512
	ds_write_b128 v250, v[48:51] offset:528
	ds_write_b128 v169, v[214:217] offset:0
	ds_write_b128 v169, v[214:217] offset:16
	ds_write_b128 v169, v[214:217] offset:512
	ds_write_b128 v169, v[214:217] offset:528
	s_mov_b64 exec, s[28:29]
	v_add_u32_e32 v251, s98, v169
	ds_write_b128 v251, v[76:79] offset:0
	ds_write_b128 v251, v[72:75] offset:16
	ds_write_b128 v251, v[68:71] offset:512
	ds_write_b128 v251, v[64:67] offset:528
	v_add_u32_e32 v251, s89, v169
	ds_write_b128 v251, v[12:15] offset:0
	ds_write_b128 v251, v[8:11] offset:16
	ds_write_b128 v251, v[4:7] offset:512
	ds_write_b128 v251, v[0:3] offset:528
	ds_write_b128 v169, v[214:217] offset:7168
	ds_write_b128 v169, v[214:217] offset:7184
	ds_write_b128 v169, v[214:217] offset:7680
	ds_write_b128 v169, v[214:217] offset:7696
	s_mov_b64 exec, -1
	s_cmp_eq_u32 s32, 0
	s_cselect_b64 s[76:77], s[2:3], 0
	s_cselect_b64 s[78:79], 0, s[28:29]
	s_mul_i32 s80, s88, 0x16000
	s_add_u32 s80, s80, 0x5b00000
	s_add_u32 s80, s80, s70
	s_addc_u32 s81, s71, 0
	v_lshl_or_b32 v252, s66, 7, v172
	v_lshlrev_b32_e32 v252, 2, v252
	s_mov_b64 exec, s[76:77]
	global_store_dwordx4 v252, v[140:143], s[80:81]
	global_store_dwordx4 v252, v[136:139], s[80:81] offset:16
	v_add_u32_e32 v250, 0x2c00, v252
	global_store_dwordx4 v250, v[120:123], s[80:81]
	global_store_dwordx4 v250, v[112:115], s[80:81] offset:16
	s_mov_b64 exec, s[78:79]
	v_add_u32_e32 v250, 0xb000, v252
	global_store_dwordx4 v250, v[12:15], s[80:81]
	global_store_dwordx4 v250, v[8:11], s[80:81] offset:16
	v_add_u32_e32 v250, 0xdc00, v252
	global_store_dwordx4 v250, v[4:7], s[80:81]
	global_store_dwordx4 v250, v[0:3], s[80:81] offset:16
	s_mov_b64 exec, -1
	s_waitcnt lgkmcnt(0)
	s_barrier
	ds_read_b128 v[186:189], v231 offset:0
	ds_read_b128 v[190:193], v231 offset:512
	ds_read_b128 v[194:197], v231 offset:2048
	ds_read_b128 v[198:201], v231 offset:2560
	s_nop 0
	v_cndmask_b32_e64 v218, 0, v116, s[2:3]
	v_cndmask_b32_e64 v222, 0, v128, s[28:29]
	v_cndmask_b32_e64 v219, 0, v117, s[2:3]
	v_cndmask_b32_e64 v223, 0, v129, s[28:29]
	v_cndmask_b32_e64 v220, 0, v118, s[2:3]
	v_cndmask_b32_e64 v224, 0, v130, s[28:29]
	v_cndmask_b32_e64 v221, 0, v119, s[2:3]
	v_cndmask_b32_e64 v225, 0, v131, s[28:29]
	v_cndmask_b32_e64 v226, 0, v160, s[2:3]
	v_cndmask_b32_e64 v232, 0, v178, s[28:29]
	v_cndmask_b32_e64 v227, 0, v161, s[2:3]
	v_cndmask_b32_e64 v233, 0, v179, s[28:29]
	v_cndmask_b32_e64 v228, 0, v162, s[2:3]
	v_cndmask_b32_e64 v234, 0, v180, s[28:29]
	v_cndmask_b32_e64 v229, 0, v163, s[2:3]
	v_cndmask_b32_e64 v235, 0, v181, s[28:29]
	s_waitcnt lgkmcnt(0)
	s_nop 1
	v_fma_f32 v202, v124, v140, v132
	v_fma_f32 v203, v125, v141, v133
	v_fma_f32 v204, v126, v142, v134
	v_fma_f32 v205, v127, v143, v135
	v_fmac_f32_dpp v202, v76, v116 row_shr:1 row_mask:0xf bank_mask:0xf
	v_fmac_f32_dpp v203, v77, v117 row_shr:1 row_mask:0xf bank_mask:0xf
	v_fmac_f32_dpp v204, v78, v118 row_shr:1 row_mask:0xf bank_mask:0xf
	v_fmac_f32_dpp v205, v79, v119 row_shr:1 row_mask:0xf bank_mask:0xf
	v_fmac_f32_e32 v202, v186, v218
	v_fmac_f32_e32 v203, v187, v219
	v_fmac_f32_e32 v204, v188, v220
	v_fmac_f32_e32 v205, v189, v221
	v_fmac_f32_e32 v202, v108, v128
	v_fmac_f32_e32 v203, v109, v129
	v_fmac_f32_e32 v204, v110, v130
	v_fmac_f32_e32 v205, v111, v131
	v_fma_f32 v206, v164, v120, v182
	v_fma_f32 v207, v165, v121, v183
	v_fma_f32 v208, v166, v122, v184
	v_fma_f32 v209, v167, v123, v185
	v_fmac_f32_dpp v206, v68, v160 row_shr:1 row_mask:0xf bank_mask:0xf
	v_fmac_f32_dpp v207, v69, v161 row_shr:1 row_mask:0xf bank_mask:0xf
	v_fmac_f32_dpp v208, v70, v162 row_shr:1 row_mask:0xf bank_mask:0xf
	v_fmac_f32_dpp v209, v71, v163 row_shr:1 row_mask:0xf bank_mask:0xf
	v_fmac_f32_e32 v206, v190, v226
	v_fmac_f32_e32 v207, v191, v227
	v_fmac_f32_e32 v208, v192, v228
	v_fmac_f32_e32 v209, v193, v229
	v_fmac_f32_e32 v206, v100, v178
	v_fmac_f32_e32 v207, v101, v179
	v_fmac_f32_e32 v208, v102, v180
	v_fmac_f32_e32 v209, v103, v181
	s_mov_b64 exec, s[76:77]
	v_add_u32_e32 v250, 0x5800, v252
	global_store_dwordx4 v250, v[202:205], s[80:81]
	v_add_u32_e32 v250, 0x8400, v252
	global_store_dwordx4 v250, v[206:209], s[80:81]
	s_mov_b64 exec, -1
	s_nop 4
	v_mul_f32_e32 v210, 0xbfb8aa3b, v202
	v_mul_f32_e32 v211, 0xbfb8aa3b, v203
	v_mul_f32_e32 v212, 0xbfb8aa3b, v204
	v_mul_f32_e32 v213, 0xbfb8aa3b, v205
	v_exp_f32_e32 v210, v210
	v_exp_f32_e32 v211, v211
	v_exp_f32_e32 v212, v212
	v_exp_f32_e32 v213, v213
	v_add_f32_e32 v210, 1.0, v210
	v_add_f32_e32 v211, 1.0, v211
	v_add_f32_e32 v212, 1.0, v212
	v_add_f32_e32 v213, 1.0, v213
	v_rcp_f32_e32 v210, v210
	v_rcp_f32_e32 v211, v211
	v_rcp_f32_e32 v212, v212
	v_rcp_f32_e32 v213, v213
	v_mul_f32_e32 v202, v202, v210
	v_mul_f32_e32 v203, v203, v211
	v_mul_f32_e32 v204, v204, v212
	v_mul_f32_e32 v205, v205, v213
	v_mul_f32_e32 v202, v202, v206
	v_mul_f32_e32 v203, v203, v207
	v_mul_f32_e32 v204, v204, v208
	v_mul_f32_e32 v205, v205, v209
	v_cvt_pk_bf16_f32 v236, v202, v203
	v_cvt_pk_bf16_f32 v237, v204, v205
	v_fma_f32 v202, v124, v108, v132
	v_fma_f32 v203, v125, v109, v133
	v_fma_f32 v204, v126, v110, v134
	v_fma_f32 v205, v127, v111, v135
	v_fmac_f32_e32 v202, v140, v116
	v_fmac_f32_e32 v203, v141, v117
	v_fmac_f32_e32 v204, v142, v118
	v_fmac_f32_e32 v205, v143, v119
	v_fmac_f32_e32 v202, v92, v128
	v_fmac_f32_e32 v203, v93, v129
	v_fmac_f32_e32 v204, v94, v130
	v_fmac_f32_e32 v205, v95, v131
	v_fma_f32 v206, v164, v100, v182
	v_fma_f32 v207, v165, v101, v183
	v_fma_f32 v208, v166, v102, v184
	v_fma_f32 v209, v167, v103, v185
	v_fmac_f32_e32 v206, v120, v160
	v_fmac_f32_e32 v207, v121, v161
	v_fmac_f32_e32 v208, v122, v162
	v_fmac_f32_e32 v209, v123, v163
	v_fmac_f32_e32 v206, v84, v178
	v_fmac_f32_e32 v207, v85, v179
	v_fmac_f32_e32 v208, v86, v180
	v_fmac_f32_e32 v209, v87, v181
	v_mul_f32_e32 v210, 0xbfb8aa3b, v202
	v_mul_f32_e32 v211, 0xbfb8aa3b, v203
	v_mul_f32_e32 v212, 0xbfb8aa3b, v204
	v_mul_f32_e32 v213, 0xbfb8aa3b, v205
	v_exp_f32_e32 v210, v210
	v_exp_f32_e32 v211, v211
	v_exp_f32_e32 v212, v212
	v_exp_f32_e32 v213, v213
	v_add_f32_e32 v210, 1.0, v210
	v_add_f32_e32 v211, 1.0, v211
	v_add_f32_e32 v212, 1.0, v212
	v_add_f32_e32 v213, 1.0, v213
	v_rcp_f32_e32 v210, v210
	v_rcp_f32_e32 v211, v211
	v_rcp_f32_e32 v212, v212
	v_rcp_f32_e32 v213, v213
	v_mul_f32_e32 v202, v202, v210
	v_mul_f32_e32 v203, v203, v211
	v_mul_f32_e32 v204, v204, v212
	v_mul_f32_e32 v205, v205, v213
	v_mul_f32_e32 v202, v202, v206
	v_mul_f32_e32 v203, v203, v207
	v_mul_f32_e32 v204, v204, v208
	v_mul_f32_e32 v205, v205, v209
	v_cvt_pk_bf16_f32 v238, v202, v203
	v_cvt_pk_bf16_f32 v239, v204, v205
	v_fma_f32 v202, v124, v92, v132
	v_fma_f32 v203, v125, v93, v133
	v_fma_f32 v204, v126, v94, v134
	v_fma_f32 v205, v127, v95, v135
	v_fmac_f32_e32 v202, v108, v116
	v_fmac_f32_e32 v203, v109, v117
	v_fmac_f32_e32 v204, v110, v118
	v_fmac_f32_e32 v205, v111, v119
	v_fmac_f32_e32 v202, v76, v128
	v_fmac_f32_e32 v203, v77, v129
	v_fmac_f32_e32 v204, v78, v130
	v_fmac_f32_e32 v205, v79, v131
	v_fma_f32 v206, v164, v84, v182
	v_fma_f32 v207, v165, v85, v183
	v_fma_f32 v208, v166, v86, v184
	v_fma_f32 v209, v167, v87, v185
	v_fmac_f32_e32 v206, v100, v160
	v_fmac_f32_e32 v207, v101, v161
	v_fmac_f32_e32 v208, v102, v162
	v_fmac_f32_e32 v209, v103, v163
	v_fmac_f32_e32 v206, v68, v178
	v_fmac_f32_e32 v207, v69, v179
	v_fmac_f32_e32 v208, v70, v180
	v_fmac_f32_e32 v209, v71, v181
	v_mul_f32_e32 v210, 0xbfb8aa3b, v202
	v_mul_f32_e32 v211, 0xbfb8aa3b, v203
	v_mul_f32_e32 v212, 0xbfb8aa3b, v204
	v_mul_f32_e32 v213, 0xbfb8aa3b, v205
	v_exp_f32_e32 v210, v210
	v_exp_f32_e32 v211, v211
	v_exp_f32_e32 v212, v212
	v_exp_f32_e32 v213, v213
	v_add_f32_e32 v210, 1.0, v210
	v_add_f32_e32 v211, 1.0, v211
	v_add_f32_e32 v212, 1.0, v212
	v_add_f32_e32 v213, 1.0, v213
	v_rcp_f32_e32 v210, v210
	v_rcp_f32_e32 v211, v211
	v_rcp_f32_e32 v212, v212
	v_rcp_f32_e32 v213, v213
	v_mul_f32_e32 v202, v202, v210
	v_mul_f32_e32 v203, v203, v211
	v_mul_f32_e32 v204, v204, v212
	v_mul_f32_e32 v205, v205, v213
	v_mul_f32_e32 v202, v202, v206
	v_mul_f32_e32 v203, v203, v207
	v_mul_f32_e32 v204, v204, v208
	v_mul_f32_e32 v205, v205, v209
	v_cvt_pk_bf16_f32 v240, v202, v203
	v_cvt_pk_bf16_f32 v241, v204, v205
	v_fma_f32 v202, v124, v76, v132
	v_fma_f32 v203, v125, v77, v133
	v_fma_f32 v204, v126, v78, v134
	v_fma_f32 v205, v127, v79, v135
	v_fmac_f32_e32 v202, v92, v116
	v_fmac_f32_e32 v203, v93, v117
	v_fmac_f32_e32 v204, v94, v118
	v_fmac_f32_e32 v205, v95, v119
	v_fmac_f32_dpp v202, v140, v128 row_shl:1 row_mask:0xf bank_mask:0xf
	v_fmac_f32_dpp v203, v141, v129 row_shl:1 row_mask:0xf bank_mask:0xf
	v_fmac_f32_dpp v204, v142, v130 row_shl:1 row_mask:0xf bank_mask:0xf
	v_fmac_f32_dpp v205, v143, v131 row_shl:1 row_mask:0xf bank_mask:0xf
	v_fmac_f32_e32 v202, v186, v222
	v_fmac_f32_e32 v203, v187, v223
	v_fmac_f32_e32 v204, v188, v224
	v_fmac_f32_e32 v205, v189, v225
	v_fma_f32 v206, v164, v68, v182
	v_fma_f32 v207, v165, v69, v183
	v_fma_f32 v208, v166, v70, v184
	v_fma_f32 v209, v167, v71, v185
	v_fmac_f32_e32 v206, v84, v160
	v_fmac_f32_e32 v207, v85, v161
	v_fmac_f32_e32 v208, v86, v162
	v_fmac_f32_e32 v209, v87, v163
	v_fmac_f32_dpp v206, v120, v178 row_shl:1 row_mask:0xf bank_mask:0xf
	v_fmac_f32_dpp v207, v121, v179 row_shl:1 row_mask:0xf bank_mask:0xf
	v_fmac_f32_dpp v208, v122, v180 row_shl:1 row_mask:0xf bank_mask:0xf
	v_fmac_f32_dpp v209, v123, v181 row_shl:1 row_mask:0xf bank_mask:0xf
	v_fmac_f32_e32 v206, v190, v232
	v_fmac_f32_e32 v207, v191, v233
	v_fmac_f32_e32 v208, v192, v234
	v_fmac_f32_e32 v209, v193, v235
	v_mul_f32_e32 v210, 0xbfb8aa3b, v202
	v_mul_f32_e32 v211, 0xbfb8aa3b, v203
	v_mul_f32_e32 v212, 0xbfb8aa3b, v204
	v_mul_f32_e32 v213, 0xbfb8aa3b, v205
	v_exp_f32_e32 v210, v210
	v_exp_f32_e32 v211, v211
	v_exp_f32_e32 v212, v212
	v_exp_f32_e32 v213, v213
	v_add_f32_e32 v210, 1.0, v210
	v_add_f32_e32 v211, 1.0, v211
	v_add_f32_e32 v212, 1.0, v212
	v_add_f32_e32 v213, 1.0, v213
	v_rcp_f32_e32 v210, v210
	v_rcp_f32_e32 v211, v211
	v_rcp_f32_e32 v212, v212
	v_rcp_f32_e32 v213, v213
	v_mul_f32_e32 v202, v202, v210
	v_mul_f32_e32 v203, v203, v211
	v_mul_f32_e32 v204, v204, v212
	v_mul_f32_e32 v205, v205, v213
	v_mul_f32_e32 v202, v202, v206
	v_mul_f32_e32 v203, v203, v207
	v_mul_f32_e32 v204, v204, v208
	v_mul_f32_e32 v205, v205, v209
	v_cvt_pk_bf16_f32 v242, v202, v203
	v_cvt_pk_bf16_f32 v243, v204, v205
	v_fma_f32 v202, v124, v60, v132
	v_fma_f32 v203, v125, v61, v133
	v_fma_f32 v204, v126, v62, v134
	v_fma_f32 v205, v127, v63, v135
	v_fmac_f32_dpp v202, v12, v116 row_shr:1 row_mask:0xf bank_mask:0xf
	v_fmac_f32_dpp v203, v13, v117 row_shr:1 row_mask:0xf bank_mask:0xf
	v_fmac_f32_dpp v204, v14, v118 row_shr:1 row_mask:0xf bank_mask:0xf
	v_fmac_f32_dpp v205, v15, v119 row_shr:1 row_mask:0xf bank_mask:0xf
	v_fmac_f32_e32 v202, v194, v218
	v_fmac_f32_e32 v203, v195, v219
	v_fmac_f32_e32 v204, v196, v220
	v_fmac_f32_e32 v205, v197, v221
	v_fmac_f32_e32 v202, v44, v128
	v_fmac_f32_e32 v203, v45, v129
	v_fmac_f32_e32 v204, v46, v130
	v_fmac_f32_e32 v205, v47, v131
	v_fma_f32 v206, v164, v52, v182
	v_fma_f32 v207, v165, v53, v183
	v_fma_f32 v208, v166, v54, v184
	v_fma_f32 v209, v167, v55, v185
	v_fmac_f32_dpp v206, v4, v160 row_shr:1 row_mask:0xf bank_mask:0xf
	v_fmac_f32_dpp v207, v5, v161 row_shr:1 row_mask:0xf bank_mask:0xf
	v_fmac_f32_dpp v208, v6, v162 row_shr:1 row_mask:0xf bank_mask:0xf
	v_fmac_f32_dpp v209, v7, v163 row_shr:1 row_mask:0xf bank_mask:0xf
	v_fmac_f32_e32 v206, v198, v226
	v_fmac_f32_e32 v207, v199, v227
	v_fmac_f32_e32 v208, v200, v228
	v_fmac_f32_e32 v209, v201, v229
	v_fmac_f32_e32 v206, v36, v178
	v_fmac_f32_e32 v207, v37, v179
	v_fmac_f32_e32 v208, v38, v180
	v_fmac_f32_e32 v209, v39, v181
	v_mul_f32_e32 v210, 0xbfb8aa3b, v202
	v_mul_f32_e32 v211, 0xbfb8aa3b, v203
	v_mul_f32_e32 v212, 0xbfb8aa3b, v204
	v_mul_f32_e32 v213, 0xbfb8aa3b, v205
	v_exp_f32_e32 v210, v210
	v_exp_f32_e32 v211, v211
	v_exp_f32_e32 v212, v212
	v_exp_f32_e32 v213, v213
	v_add_f32_e32 v210, 1.0, v210
	v_add_f32_e32 v211, 1.0, v211
	v_add_f32_e32 v212, 1.0, v212
	v_add_f32_e32 v213, 1.0, v213
	v_rcp_f32_e32 v210, v210
	v_rcp_f32_e32 v211, v211
	v_rcp_f32_e32 v212, v212
	v_rcp_f32_e32 v213, v213
	v_mul_f32_e32 v202, v202, v210
	v_mul_f32_e32 v203, v203, v211
	v_mul_f32_e32 v204, v204, v212
	v_mul_f32_e32 v205, v205, v213
	v_mul_f32_e32 v202, v202, v206
	v_mul_f32_e32 v203, v203, v207
	v_mul_f32_e32 v204, v204, v208
	v_mul_f32_e32 v205, v205, v209
	v_cvt_pk_bf16_f32 v244, v202, v203
	v_cvt_pk_bf16_f32 v245, v204, v205
	v_fma_f32 v202, v124, v44, v132
	v_fma_f32 v203, v125, v45, v133
	v_fma_f32 v204, v126, v46, v134
	v_fma_f32 v205, v127, v47, v135
	v_fmac_f32_e32 v202, v60, v116
	v_fmac_f32_e32 v203, v61, v117
	v_fmac_f32_e32 v204, v62, v118
	v_fmac_f32_e32 v205, v63, v119
	v_fmac_f32_e32 v202, v28, v128
	v_fmac_f32_e32 v203, v29, v129
	v_fmac_f32_e32 v204, v30, v130
	v_fmac_f32_e32 v205, v31, v131
	v_fma_f32 v206, v164, v36, v182
	v_fma_f32 v207, v165, v37, v183
	v_fma_f32 v208, v166, v38, v184
	v_fma_f32 v209, v167, v39, v185
	v_fmac_f32_e32 v206, v52, v160
	v_fmac_f32_e32 v207, v53, v161
	v_fmac_f32_e32 v208, v54, v162
	v_fmac_f32_e32 v209, v55, v163
	v_fmac_f32_e32 v206, v20, v178
	v_fmac_f32_e32 v207, v21, v179
	v_fmac_f32_e32 v208, v22, v180
	v_fmac_f32_e32 v209, v23, v181
	v_mul_f32_e32 v210, 0xbfb8aa3b, v202
	v_mul_f32_e32 v211, 0xbfb8aa3b, v203
	v_mul_f32_e32 v212, 0xbfb8aa3b, v204
	v_mul_f32_e32 v213, 0xbfb8aa3b, v205
	v_exp_f32_e32 v210, v210
	v_exp_f32_e32 v211, v211
	v_exp_f32_e32 v212, v212
	v_exp_f32_e32 v213, v213
	v_add_f32_e32 v210, 1.0, v210
	v_add_f32_e32 v211, 1.0, v211
	v_add_f32_e32 v212, 1.0, v212
	v_add_f32_e32 v213, 1.0, v213
	v_rcp_f32_e32 v210, v210
	v_rcp_f32_e32 v211, v211
	v_rcp_f32_e32 v212, v212
	v_rcp_f32_e32 v213, v213
	v_mul_f32_e32 v202, v202, v210
	v_mul_f32_e32 v203, v203, v211
	v_mul_f32_e32 v204, v204, v212
	v_mul_f32_e32 v205, v205, v213
	v_mul_f32_e32 v202, v202, v206
	v_mul_f32_e32 v203, v203, v207
	v_mul_f32_e32 v204, v204, v208
	v_mul_f32_e32 v205, v205, v209
	v_cvt_pk_bf16_f32 v246, v202, v203
	v_cvt_pk_bf16_f32 v247, v204, v205
	v_fma_f32 v202, v124, v28, v132
	v_fma_f32 v203, v125, v29, v133
	v_fma_f32 v204, v126, v30, v134
	v_fma_f32 v205, v127, v31, v135
	v_fmac_f32_e32 v202, v44, v116
	v_fmac_f32_e32 v203, v45, v117
	v_fmac_f32_e32 v204, v46, v118
	v_fmac_f32_e32 v205, v47, v119
	v_fmac_f32_e32 v202, v12, v128
	v_fmac_f32_e32 v203, v13, v129
	v_fmac_f32_e32 v204, v14, v130
	v_fmac_f32_e32 v205, v15, v131
	v_fma_f32 v206, v164, v20, v182
	v_fma_f32 v207, v165, v21, v183
	v_fma_f32 v208, v166, v22, v184
	v_fma_f32 v209, v167, v23, v185
	v_fmac_f32_e32 v206, v36, v160
	v_fmac_f32_e32 v207, v37, v161
	v_fmac_f32_e32 v208, v38, v162
	v_fmac_f32_e32 v209, v39, v163
	v_fmac_f32_e32 v206, v4, v178
	v_fmac_f32_e32 v207, v5, v179
	v_fmac_f32_e32 v208, v6, v180
	v_fmac_f32_e32 v209, v7, v181
	v_mul_f32_e32 v210, 0xbfb8aa3b, v202
	v_mul_f32_e32 v211, 0xbfb8aa3b, v203
	v_mul_f32_e32 v212, 0xbfb8aa3b, v204
	v_mul_f32_e32 v213, 0xbfb8aa3b, v205
	v_exp_f32_e32 v210, v210
	v_exp_f32_e32 v211, v211
	v_exp_f32_e32 v212, v212
	v_exp_f32_e32 v213, v213
	v_add_f32_e32 v210, 1.0, v210
	v_add_f32_e32 v211, 1.0, v211
	v_add_f32_e32 v212, 1.0, v212
	v_add_f32_e32 v213, 1.0, v213
	v_rcp_f32_e32 v210, v210
	v_rcp_f32_e32 v211, v211
	v_rcp_f32_e32 v212, v212
	v_rcp_f32_e32 v213, v213
	v_mul_f32_e32 v202, v202, v210
	v_mul_f32_e32 v203, v203, v211
	v_mul_f32_e32 v204, v204, v212
	v_mul_f32_e32 v205, v205, v213
	v_mul_f32_e32 v202, v202, v206
	v_mul_f32_e32 v203, v203, v207
	v_mul_f32_e32 v204, v204, v208
	v_mul_f32_e32 v205, v205, v209
	v_cvt_pk_bf16_f32 v248, v202, v203
	v_cvt_pk_bf16_f32 v249, v204, v205
	v_fma_f32 v202, v124, v12, v132
	v_fma_f32 v203, v125, v13, v133
	v_fma_f32 v204, v126, v14, v134
	v_fma_f32 v205, v127, v15, v135
	v_fmac_f32_e32 v202, v28, v116
	v_fmac_f32_e32 v203, v29, v117
	v_fmac_f32_e32 v204, v30, v118
	v_fmac_f32_e32 v205, v31, v119
	v_fmac_f32_dpp v202, v60, v128 row_shl:1 row_mask:0xf bank_mask:0xf
	v_fmac_f32_dpp v203, v61, v129 row_shl:1 row_mask:0xf bank_mask:0xf
	v_fmac_f32_dpp v204, v62, v130 row_shl:1 row_mask:0xf bank_mask:0xf
	v_fmac_f32_dpp v205, v63, v131 row_shl:1 row_mask:0xf bank_mask:0xf
	v_fmac_f32_e32 v202, v194, v222
	v_fmac_f32_e32 v203, v195, v223
	v_fmac_f32_e32 v204, v196, v224
	v_fmac_f32_e32 v205, v197, v225
	v_fma_f32 v206, v164, v4, v182
	v_fma_f32 v207, v165, v5, v183
	v_fma_f32 v208, v166, v6, v184
	v_fma_f32 v209, v167, v7, v185
	v_fmac_f32_e32 v206, v20, v160
	v_fmac_f32_e32 v207, v21, v161
	v_fmac_f32_e32 v208, v22, v162
	v_fmac_f32_e32 v209, v23, v163
	v_fmac_f32_dpp v206, v52, v178 row_shl:1 row_mask:0xf bank_mask:0xf
	v_fmac_f32_dpp v207, v53, v179 row_shl:1 row_mask:0xf bank_mask:0xf
	v_fmac_f32_dpp v208, v54, v180 row_shl:1 row_mask:0xf bank_mask:0xf
	v_fmac_f32_dpp v209, v55, v181 row_shl:1 row_mask:0xf bank_mask:0xf
	v_fmac_f32_e32 v206, v198, v232
	v_fmac_f32_e32 v207, v199, v233
	v_fmac_f32_e32 v208, v200, v234
	v_fmac_f32_e32 v209, v201, v235
	s_mov_b64 exec, s[78:79]
	v_add_u32_e32 v250, 0x10800, v252
	global_store_dwordx4 v250, v[202:205], s[80:81]
	v_add_u32_e32 v250, 0x13400, v252
	global_store_dwordx4 v250, v[206:209], s[80:81]
	s_mov_b64 exec, -1
	s_nop 4
	v_mul_f32_e32 v210, 0xbfb8aa3b, v202
	v_mul_f32_e32 v211, 0xbfb8aa3b, v203
	v_mul_f32_e32 v212, 0xbfb8aa3b, v204
	v_mul_f32_e32 v213, 0xbfb8aa3b, v205
	v_exp_f32_e32 v210, v210
	v_exp_f32_e32 v211, v211
	v_exp_f32_e32 v212, v212
	v_exp_f32_e32 v213, v213
	v_add_f32_e32 v210, 1.0, v210
	v_add_f32_e32 v211, 1.0, v211
	v_add_f32_e32 v212, 1.0, v212
	v_add_f32_e32 v213, 1.0, v213
	v_rcp_f32_e32 v210, v210
	v_rcp_f32_e32 v211, v211
	v_rcp_f32_e32 v212, v212
	v_rcp_f32_e32 v213, v213
	v_mul_f32_e32 v202, v202, v210
	v_mul_f32_e32 v203, v203, v211
	v_mul_f32_e32 v204, v204, v212
	v_mul_f32_e32 v205, v205, v213
	v_mul_f32_e32 v202, v202, v206
	v_mul_f32_e32 v203, v203, v207
	v_mul_f32_e32 v204, v204, v208
	v_mul_f32_e32 v205, v205, v209
	v_cvt_pk_bf16_f32 v250, v202, v203
	v_cvt_pk_bf16_f32 v251, v204, v205
	ds_read_b128 v[116:119], v177 offset:2064
	ds_read_b128 v[124:127], v177 offset:2576
	ds_read_b128 v[128:131], v177 offset:4112
	ds_read_b128 v[132:135], v177 offset:5136
	ds_read_b128 v[160:163], v177 offset:3088
	ds_read_b128 v[164:167], v177 offset:3600
	ds_read_b128 v[178:181], v177 offset:4624
	ds_read_b128 v[182:185], v177 offset:5648
	v_mov_b32_e32 v140, v236
	v_mov_b32_e32 v141, v237
	v_mov_b32_e32 v108, v238
	v_mov_b32_e32 v109, v239
	v_mov_b32_e32 v92, v240
	v_mov_b32_e32 v93, v241
	v_mov_b32_e32 v76, v242
	v_mov_b32_e32 v77, v243
	v_mov_b32_e32 v60, v244
	v_mov_b32_e32 v61, v245
	v_mov_b32_e32 v44, v246
	v_mov_b32_e32 v45, v247
	v_mov_b32_e32 v28, v248
	v_mov_b32_e32 v29, v249
	v_mov_b32_e32 v12, v250
	v_mov_b32_e32 v13, v251
	ds_read_b128 v[186:189], v231 offset:16
	ds_read_b128 v[190:193], v231 offset:528
	ds_read_b128 v[194:197], v231 offset:2064
	ds_read_b128 v[198:201], v231 offset:2576
	s_waitcnt lgkmcnt(4)
	v_cndmask_b32_e64 v218, 0, v116, s[2:3]
	v_cndmask_b32_e64 v222, 0, v128, s[28:29]
	v_cndmask_b32_e64 v219, 0, v117, s[2:3]
	v_cndmask_b32_e64 v223, 0, v129, s[28:29]
	v_cndmask_b32_e64 v220, 0, v118, s[2:3]
	v_cndmask_b32_e64 v224, 0, v130, s[28:29]
	v_cndmask_b32_e64 v221, 0, v119, s[2:3]
	v_cndmask_b32_e64 v225, 0, v131, s[28:29]
	v_cndmask_b32_e64 v226, 0, v160, s[2:3]
	v_cndmask_b32_e64 v232, 0, v178, s[28:29]
	v_cndmask_b32_e64 v227, 0, v161, s[2:3]
	v_cndmask_b32_e64 v233, 0, v179, s[28:29]
	v_cndmask_b32_e64 v228, 0, v162, s[2:3]
	v_cndmask_b32_e64 v234, 0, v180, s[28:29]
	v_cndmask_b32_e64 v229, 0, v163, s[2:3]
	v_cndmask_b32_e64 v235, 0, v181, s[28:29]
	s_waitcnt lgkmcnt(0)
	s_nop 1
	v_fma_f32 v202, v124, v136, v132
	v_fma_f32 v203, v125, v137, v133
	v_fma_f32 v204, v126, v138, v134
	v_fma_f32 v205, v127, v139, v135
	v_fmac_f32_dpp v202, v72, v116 row_shr:1 row_mask:0xf bank_mask:0xf
	v_fmac_f32_dpp v203, v73, v117 row_shr:1 row_mask:0xf bank_mask:0xf
	v_fmac_f32_dpp v204, v74, v118 row_shr:1 row_mask:0xf bank_mask:0xf
	v_fmac_f32_dpp v205, v75, v119 row_shr:1 row_mask:0xf bank_mask:0xf
	v_fmac_f32_e32 v202, v186, v218
	v_fmac_f32_e32 v203, v187, v219
	v_fmac_f32_e32 v204, v188, v220
	v_fmac_f32_e32 v205, v189, v221
	v_fmac_f32_e32 v202, v104, v128
	v_fmac_f32_e32 v203, v105, v129
	v_fmac_f32_e32 v204, v106, v130
	v_fmac_f32_e32 v205, v107, v131
	v_fma_f32 v206, v164, v112, v182
	v_fma_f32 v207, v165, v113, v183
	v_fma_f32 v208, v166, v114, v184
	v_fma_f32 v209, v167, v115, v185
	v_fmac_f32_dpp v206, v64, v160 row_shr:1 row_mask:0xf bank_mask:0xf
	v_fmac_f32_dpp v207, v65, v161 row_shr:1 row_mask:0xf bank_mask:0xf
	v_fmac_f32_dpp v208, v66, v162 row_shr:1 row_mask:0xf bank_mask:0xf
	v_fmac_f32_dpp v209, v67, v163 row_shr:1 row_mask:0xf bank_mask:0xf
	v_fmac_f32_e32 v206, v190, v226
	v_fmac_f32_e32 v207, v191, v227
	v_fmac_f32_e32 v208, v192, v228
	v_fmac_f32_e32 v209, v193, v229
	v_fmac_f32_e32 v206, v96, v178
	v_fmac_f32_e32 v207, v97, v179
	v_fmac_f32_e32 v208, v98, v180
	v_fmac_f32_e32 v209, v99, v181
	s_mov_b64 exec, s[76:77]
	v_add_u32_e32 v250, 0x5800, v252
	global_store_dwordx4 v250, v[202:205], s[80:81] offset:16
	v_add_u32_e32 v250, 0x8400, v252
	global_store_dwordx4 v250, v[206:209], s[80:81] offset:16
	s_mov_b64 exec, -1
	s_nop 4
	v_mul_f32_e32 v210, 0xbfb8aa3b, v202
	v_mul_f32_e32 v211, 0xbfb8aa3b, v203
	v_mul_f32_e32 v212, 0xbfb8aa3b, v204
	v_mul_f32_e32 v213, 0xbfb8aa3b, v205
	v_exp_f32_e32 v210, v210
	v_exp_f32_e32 v211, v211
	v_exp_f32_e32 v212, v212
	v_exp_f32_e32 v213, v213
	v_add_f32_e32 v210, 1.0, v210
	v_add_f32_e32 v211, 1.0, v211
	v_add_f32_e32 v212, 1.0, v212
	v_add_f32_e32 v213, 1.0, v213
	v_rcp_f32_e32 v210, v210
	v_rcp_f32_e32 v211, v211
	v_rcp_f32_e32 v212, v212
	v_rcp_f32_e32 v213, v213
	v_mul_f32_e32 v202, v202, v210
	v_mul_f32_e32 v203, v203, v211
	v_mul_f32_e32 v204, v204, v212
	v_mul_f32_e32 v205, v205, v213
	v_mul_f32_e32 v202, v202, v206
	v_mul_f32_e32 v203, v203, v207
	v_mul_f32_e32 v204, v204, v208
	v_mul_f32_e32 v205, v205, v209
	v_cvt_pk_bf16_f32 v142, v202, v203
	v_cvt_pk_bf16_f32 v143, v204, v205
	v_fma_f32 v202, v124, v104, v132
	v_fma_f32 v203, v125, v105, v133
	v_fma_f32 v204, v126, v106, v134
	v_fma_f32 v205, v127, v107, v135
	v_fmac_f32_e32 v202, v136, v116
	v_fmac_f32_e32 v203, v137, v117
	v_fmac_f32_e32 v204, v138, v118
	v_fmac_f32_e32 v205, v139, v119
	v_fmac_f32_e32 v202, v88, v128
	v_fmac_f32_e32 v203, v89, v129
	v_fmac_f32_e32 v204, v90, v130
	v_fmac_f32_e32 v205, v91, v131
	v_fma_f32 v206, v164, v96, v182
	v_fma_f32 v207, v165, v97, v183
	v_fma_f32 v208, v166, v98, v184
	v_fma_f32 v209, v167, v99, v185
	v_fmac_f32_e32 v206, v112, v160
	v_fmac_f32_e32 v207, v113, v161
	v_fmac_f32_e32 v208, v114, v162
	v_fmac_f32_e32 v209, v115, v163
	v_fmac_f32_e32 v206, v80, v178
	v_fmac_f32_e32 v207, v81, v179
	v_fmac_f32_e32 v208, v82, v180
	v_fmac_f32_e32 v209, v83, v181
	v_mul_f32_e32 v210, 0xbfb8aa3b, v202
	v_mul_f32_e32 v211, 0xbfb8aa3b, v203
	v_mul_f32_e32 v212, 0xbfb8aa3b, v204
	v_mul_f32_e32 v213, 0xbfb8aa3b, v205
	v_exp_f32_e32 v210, v210
	v_exp_f32_e32 v211, v211
	v_exp_f32_e32 v212, v212
	v_exp_f32_e32 v213, v213
	v_add_f32_e32 v210, 1.0, v210
	v_add_f32_e32 v211, 1.0, v211
	v_add_f32_e32 v212, 1.0, v212
	v_add_f32_e32 v213, 1.0, v213
	v_rcp_f32_e32 v210, v210
	v_rcp_f32_e32 v211, v211
	v_rcp_f32_e32 v212, v212
	v_rcp_f32_e32 v213, v213
	v_mul_f32_e32 v202, v202, v210
	v_mul_f32_e32 v203, v203, v211
	v_mul_f32_e32 v204, v204, v212
	v_mul_f32_e32 v205, v205, v213
	v_mul_f32_e32 v202, v202, v206
	v_mul_f32_e32 v203, v203, v207
	v_mul_f32_e32 v204, v204, v208
	v_mul_f32_e32 v205, v205, v209
	v_cvt_pk_bf16_f32 v110, v202, v203
	v_cvt_pk_bf16_f32 v111, v204, v205
	v_fma_f32 v202, v124, v88, v132
	v_fma_f32 v203, v125, v89, v133
	v_fma_f32 v204, v126, v90, v134
	v_fma_f32 v205, v127, v91, v135
	v_fmac_f32_e32 v202, v104, v116
	v_fmac_f32_e32 v203, v105, v117
	v_fmac_f32_e32 v204, v106, v118
	v_fmac_f32_e32 v205, v107, v119
	v_fmac_f32_e32 v202, v72, v128
	v_fmac_f32_e32 v203, v73, v129
	v_fmac_f32_e32 v204, v74, v130
	v_fmac_f32_e32 v205, v75, v131
	v_fma_f32 v206, v164, v80, v182
	v_fma_f32 v207, v165, v81, v183
	v_fma_f32 v208, v166, v82, v184
	v_fma_f32 v209, v167, v83, v185
	v_fmac_f32_e32 v206, v96, v160
	v_fmac_f32_e32 v207, v97, v161
	v_fmac_f32_e32 v208, v98, v162
	v_fmac_f32_e32 v209, v99, v163
	v_fmac_f32_e32 v206, v64, v178
	v_fmac_f32_e32 v207, v65, v179
	v_fmac_f32_e32 v208, v66, v180
	v_fmac_f32_e32 v209, v67, v181
	v_mul_f32_e32 v210, 0xbfb8aa3b, v202
	v_mul_f32_e32 v211, 0xbfb8aa3b, v203
	v_mul_f32_e32 v212, 0xbfb8aa3b, v204
	v_mul_f32_e32 v213, 0xbfb8aa3b, v205
	v_exp_f32_e32 v210, v210
	v_exp_f32_e32 v211, v211
	v_exp_f32_e32 v212, v212
	v_exp_f32_e32 v213, v213
	v_add_f32_e32 v210, 1.0, v210
	v_add_f32_e32 v211, 1.0, v211
	v_add_f32_e32 v212, 1.0, v212
	v_add_f32_e32 v213, 1.0, v213
	v_rcp_f32_e32 v210, v210
	v_rcp_f32_e32 v211, v211
	v_rcp_f32_e32 v212, v212
	v_rcp_f32_e32 v213, v213
	v_mul_f32_e32 v202, v202, v210
	v_mul_f32_e32 v203, v203, v211
	v_mul_f32_e32 v204, v204, v212
	v_mul_f32_e32 v205, v205, v213
	v_mul_f32_e32 v202, v202, v206
	v_mul_f32_e32 v203, v203, v207
	v_mul_f32_e32 v204, v204, v208
	v_mul_f32_e32 v205, v205, v209
	v_cvt_pk_bf16_f32 v94, v202, v203
	v_cvt_pk_bf16_f32 v95, v204, v205
	v_fma_f32 v202, v124, v72, v132
	v_fma_f32 v203, v125, v73, v133
	v_fma_f32 v204, v126, v74, v134
	v_fma_f32 v205, v127, v75, v135
	v_fmac_f32_e32 v202, v88, v116
	v_fmac_f32_e32 v203, v89, v117
	v_fmac_f32_e32 v204, v90, v118
	v_fmac_f32_e32 v205, v91, v119
	v_fmac_f32_dpp v202, v136, v128 row_shl:1 row_mask:0xf bank_mask:0xf
	v_fmac_f32_dpp v203, v137, v129 row_shl:1 row_mask:0xf bank_mask:0xf
	v_fmac_f32_dpp v204, v138, v130 row_shl:1 row_mask:0xf bank_mask:0xf
	v_fmac_f32_dpp v205, v139, v131 row_shl:1 row_mask:0xf bank_mask:0xf
	v_fmac_f32_e32 v202, v186, v222
	v_fmac_f32_e32 v203, v187, v223
	v_fmac_f32_e32 v204, v188, v224
	v_fmac_f32_e32 v205, v189, v225
	v_fma_f32 v206, v164, v64, v182
	v_fma_f32 v207, v165, v65, v183
	v_fma_f32 v208, v166, v66, v184
	v_fma_f32 v209, v167, v67, v185
	v_fmac_f32_e32 v206, v80, v160
	v_fmac_f32_e32 v207, v81, v161
	v_fmac_f32_e32 v208, v82, v162
	v_fmac_f32_e32 v209, v83, v163
	v_fmac_f32_dpp v206, v112, v178 row_shl:1 row_mask:0xf bank_mask:0xf
	v_fmac_f32_dpp v207, v113, v179 row_shl:1 row_mask:0xf bank_mask:0xf
	v_fmac_f32_dpp v208, v114, v180 row_shl:1 row_mask:0xf bank_mask:0xf
	v_fmac_f32_dpp v209, v115, v181 row_shl:1 row_mask:0xf bank_mask:0xf
	v_fmac_f32_e32 v206, v190, v232
	v_fmac_f32_e32 v207, v191, v233
	v_fmac_f32_e32 v208, v192, v234
	v_fmac_f32_e32 v209, v193, v235
	v_mul_f32_e32 v210, 0xbfb8aa3b, v202
	v_mul_f32_e32 v211, 0xbfb8aa3b, v203
	v_mul_f32_e32 v212, 0xbfb8aa3b, v204
	v_mul_f32_e32 v213, 0xbfb8aa3b, v205
	v_exp_f32_e32 v210, v210
	v_exp_f32_e32 v211, v211
	v_exp_f32_e32 v212, v212
	v_exp_f32_e32 v213, v213
	v_add_f32_e32 v210, 1.0, v210
	v_add_f32_e32 v211, 1.0, v211
	v_add_f32_e32 v212, 1.0, v212
	v_add_f32_e32 v213, 1.0, v213
	v_rcp_f32_e32 v210, v210
	v_rcp_f32_e32 v211, v211
	v_rcp_f32_e32 v212, v212
	v_rcp_f32_e32 v213, v213
	v_mul_f32_e32 v202, v202, v210
	v_mul_f32_e32 v203, v203, v211
	v_mul_f32_e32 v204, v204, v212
	v_mul_f32_e32 v205, v205, v213
	v_mul_f32_e32 v202, v202, v206
	v_mul_f32_e32 v203, v203, v207
	v_mul_f32_e32 v204, v204, v208
	v_mul_f32_e32 v205, v205, v209
	v_cvt_pk_bf16_f32 v78, v202, v203
	v_cvt_pk_bf16_f32 v79, v204, v205
	v_fma_f32 v202, v124, v56, v132
	v_fma_f32 v203, v125, v57, v133
	v_fma_f32 v204, v126, v58, v134
	v_fma_f32 v205, v127, v59, v135
	v_fmac_f32_dpp v202, v8, v116 row_shr:1 row_mask:0xf bank_mask:0xf
	v_fmac_f32_dpp v203, v9, v117 row_shr:1 row_mask:0xf bank_mask:0xf
	v_fmac_f32_dpp v204, v10, v118 row_shr:1 row_mask:0xf bank_mask:0xf
	v_fmac_f32_dpp v205, v11, v119 row_shr:1 row_mask:0xf bank_mask:0xf
	v_fmac_f32_e32 v202, v194, v218
	v_fmac_f32_e32 v203, v195, v219
	v_fmac_f32_e32 v204, v196, v220
	v_fmac_f32_e32 v205, v197, v221
	v_fmac_f32_e32 v202, v40, v128
	v_fmac_f32_e32 v203, v41, v129
	v_fmac_f32_e32 v204, v42, v130
	v_fmac_f32_e32 v205, v43, v131
	v_fma_f32 v206, v164, v48, v182
	v_fma_f32 v207, v165, v49, v183
	v_fma_f32 v208, v166, v50, v184
	v_fma_f32 v209, v167, v51, v185
	v_fmac_f32_dpp v206, v0, v160 row_shr:1 row_mask:0xf bank_mask:0xf
	v_fmac_f32_dpp v207, v1, v161 row_shr:1 row_mask:0xf bank_mask:0xf
	v_fmac_f32_dpp v208, v2, v162 row_shr:1 row_mask:0xf bank_mask:0xf
	v_fmac_f32_dpp v209, v3, v163 row_shr:1 row_mask:0xf bank_mask:0xf
	v_fmac_f32_e32 v206, v198, v226
	v_fmac_f32_e32 v207, v199, v227
	v_fmac_f32_e32 v208, v200, v228
	v_fmac_f32_e32 v209, v201, v229
	v_fmac_f32_e32 v206, v32, v178
	v_fmac_f32_e32 v207, v33, v179
	v_fmac_f32_e32 v208, v34, v180
	v_fmac_f32_e32 v209, v35, v181
	v_mul_f32_e32 v210, 0xbfb8aa3b, v202
	v_mul_f32_e32 v211, 0xbfb8aa3b, v203
	v_mul_f32_e32 v212, 0xbfb8aa3b, v204
	v_mul_f32_e32 v213, 0xbfb8aa3b, v205
	v_exp_f32_e32 v210, v210
	v_exp_f32_e32 v211, v211
	v_exp_f32_e32 v212, v212
	v_exp_f32_e32 v213, v213
	v_add_f32_e32 v210, 1.0, v210
	v_add_f32_e32 v211, 1.0, v211
	v_add_f32_e32 v212, 1.0, v212
	v_add_f32_e32 v213, 1.0, v213
	v_rcp_f32_e32 v210, v210
	v_rcp_f32_e32 v211, v211
	v_rcp_f32_e32 v212, v212
	v_rcp_f32_e32 v213, v213
	v_mul_f32_e32 v202, v202, v210
	v_mul_f32_e32 v203, v203, v211
	v_mul_f32_e32 v204, v204, v212
	v_mul_f32_e32 v205, v205, v213
	v_mul_f32_e32 v202, v202, v206
	v_mul_f32_e32 v203, v203, v207
	v_mul_f32_e32 v204, v204, v208
	v_mul_f32_e32 v205, v205, v209
	v_cvt_pk_bf16_f32 v62, v202, v203
	v_cvt_pk_bf16_f32 v63, v204, v205
	v_fma_f32 v202, v124, v40, v132
	v_fma_f32 v203, v125, v41, v133
	v_fma_f32 v204, v126, v42, v134
	v_fma_f32 v205, v127, v43, v135
	v_fmac_f32_e32 v202, v56, v116
	v_fmac_f32_e32 v203, v57, v117
	v_fmac_f32_e32 v204, v58, v118
	v_fmac_f32_e32 v205, v59, v119
	v_fmac_f32_e32 v202, v24, v128
	v_fmac_f32_e32 v203, v25, v129
	v_fmac_f32_e32 v204, v26, v130
	v_fmac_f32_e32 v205, v27, v131
	v_fma_f32 v206, v164, v32, v182
	v_fma_f32 v207, v165, v33, v183
	v_fma_f32 v208, v166, v34, v184
	v_fma_f32 v209, v167, v35, v185
	v_fmac_f32_e32 v206, v48, v160
	v_fmac_f32_e32 v207, v49, v161
	v_fmac_f32_e32 v208, v50, v162
	v_fmac_f32_e32 v209, v51, v163
	v_fmac_f32_e32 v206, v16, v178
	v_fmac_f32_e32 v207, v17, v179
	v_fmac_f32_e32 v208, v18, v180
	v_fmac_f32_e32 v209, v19, v181
	v_mul_f32_e32 v210, 0xbfb8aa3b, v202
	v_mul_f32_e32 v211, 0xbfb8aa3b, v203
	v_mul_f32_e32 v212, 0xbfb8aa3b, v204
	v_mul_f32_e32 v213, 0xbfb8aa3b, v205
	v_exp_f32_e32 v210, v210
	v_exp_f32_e32 v211, v211
	v_exp_f32_e32 v212, v212
	v_exp_f32_e32 v213, v213
	v_add_f32_e32 v210, 1.0, v210
	v_add_f32_e32 v211, 1.0, v211
	v_add_f32_e32 v212, 1.0, v212
	v_add_f32_e32 v213, 1.0, v213
	v_rcp_f32_e32 v210, v210
	v_rcp_f32_e32 v211, v211
	v_rcp_f32_e32 v212, v212
	v_rcp_f32_e32 v213, v213
	v_mul_f32_e32 v202, v202, v210
	v_mul_f32_e32 v203, v203, v211
	v_mul_f32_e32 v204, v204, v212
	v_mul_f32_e32 v205, v205, v213
	v_mul_f32_e32 v202, v202, v206
	v_mul_f32_e32 v203, v203, v207
	v_mul_f32_e32 v204, v204, v208
	v_mul_f32_e32 v205, v205, v209
	v_cvt_pk_bf16_f32 v46, v202, v203
	v_cvt_pk_bf16_f32 v47, v204, v205
	v_fma_f32 v202, v124, v24, v132
	v_fma_f32 v203, v125, v25, v133
	v_fma_f32 v204, v126, v26, v134
	v_fma_f32 v205, v127, v27, v135
	v_fmac_f32_e32 v202, v40, v116
	v_fmac_f32_e32 v203, v41, v117
	v_fmac_f32_e32 v204, v42, v118
	v_fmac_f32_e32 v205, v43, v119
	v_fmac_f32_e32 v202, v8, v128
	v_fmac_f32_e32 v203, v9, v129
	v_fmac_f32_e32 v204, v10, v130
	v_fmac_f32_e32 v205, v11, v131
	v_fma_f32 v206, v164, v16, v182
	v_fma_f32 v207, v165, v17, v183
	v_fma_f32 v208, v166, v18, v184
	v_fma_f32 v209, v167, v19, v185
	v_fmac_f32_e32 v206, v32, v160
	v_fmac_f32_e32 v207, v33, v161
	v_fmac_f32_e32 v208, v34, v162
	v_fmac_f32_e32 v209, v35, v163
	v_fmac_f32_e32 v206, v0, v178
	v_fmac_f32_e32 v207, v1, v179
	v_fmac_f32_e32 v208, v2, v180
	v_fmac_f32_e32 v209, v3, v181
	v_mul_f32_e32 v210, 0xbfb8aa3b, v202
	v_mul_f32_e32 v211, 0xbfb8aa3b, v203
	v_mul_f32_e32 v212, 0xbfb8aa3b, v204
	v_mul_f32_e32 v213, 0xbfb8aa3b, v205
	v_exp_f32_e32 v210, v210
	v_exp_f32_e32 v211, v211
	v_exp_f32_e32 v212, v212
	v_exp_f32_e32 v213, v213
	v_add_f32_e32 v210, 1.0, v210
	v_add_f32_e32 v211, 1.0, v211
	v_add_f32_e32 v212, 1.0, v212
	v_add_f32_e32 v213, 1.0, v213
	v_rcp_f32_e32 v210, v210
	v_rcp_f32_e32 v211, v211
	v_rcp_f32_e32 v212, v212
	v_rcp_f32_e32 v213, v213
	v_mul_f32_e32 v202, v202, v210
	v_mul_f32_e32 v203, v203, v211
	v_mul_f32_e32 v204, v204, v212
	v_mul_f32_e32 v205, v205, v213
	v_mul_f32_e32 v202, v202, v206
	v_mul_f32_e32 v203, v203, v207
	v_mul_f32_e32 v204, v204, v208
	v_mul_f32_e32 v205, v205, v209
	v_cvt_pk_bf16_f32 v30, v202, v203
	v_cvt_pk_bf16_f32 v31, v204, v205
	v_fma_f32 v202, v124, v8, v132
	v_fma_f32 v203, v125, v9, v133
	v_fma_f32 v204, v126, v10, v134
	v_fma_f32 v205, v127, v11, v135
	v_fmac_f32_e32 v202, v24, v116
	v_fmac_f32_e32 v203, v25, v117
	v_fmac_f32_e32 v204, v26, v118
	v_fmac_f32_e32 v205, v27, v119
	v_fmac_f32_dpp v202, v56, v128 row_shl:1 row_mask:0xf bank_mask:0xf
	v_fmac_f32_dpp v203, v57, v129 row_shl:1 row_mask:0xf bank_mask:0xf
	v_fmac_f32_dpp v204, v58, v130 row_shl:1 row_mask:0xf bank_mask:0xf
	v_fmac_f32_dpp v205, v59, v131 row_shl:1 row_mask:0xf bank_mask:0xf
	v_fmac_f32_e32 v202, v194, v222
	v_fmac_f32_e32 v203, v195, v223
	v_fmac_f32_e32 v204, v196, v224
	v_fmac_f32_e32 v205, v197, v225
	v_fma_f32 v206, v164, v0, v182
	v_fma_f32 v207, v165, v1, v183
	v_fma_f32 v208, v166, v2, v184
	v_fma_f32 v209, v167, v3, v185
	v_fmac_f32_e32 v206, v16, v160
	v_fmac_f32_e32 v207, v17, v161
	v_fmac_f32_e32 v208, v18, v162
	v_fmac_f32_e32 v209, v19, v163
	v_fmac_f32_dpp v206, v48, v178 row_shl:1 row_mask:0xf bank_mask:0xf
	v_fmac_f32_dpp v207, v49, v179 row_shl:1 row_mask:0xf bank_mask:0xf
	v_fmac_f32_dpp v208, v50, v180 row_shl:1 row_mask:0xf bank_mask:0xf
	v_fmac_f32_dpp v209, v51, v181 row_shl:1 row_mask:0xf bank_mask:0xf
	v_fmac_f32_e32 v206, v198, v232
	v_fmac_f32_e32 v207, v199, v233
	v_fmac_f32_e32 v208, v200, v234
	v_fmac_f32_e32 v209, v201, v235
	s_mov_b64 exec, s[78:79]
	v_add_u32_e32 v250, 0x10800, v252
	global_store_dwordx4 v250, v[202:205], s[80:81] offset:16
	v_add_u32_e32 v250, 0x13400, v252
	global_store_dwordx4 v250, v[206:209], s[80:81] offset:16
	s_mov_b64 exec, -1
	s_nop 4
	v_mul_f32_e32 v210, 0xbfb8aa3b, v202
	v_mul_f32_e32 v211, 0xbfb8aa3b, v203
	v_mul_f32_e32 v212, 0xbfb8aa3b, v204
	v_mul_f32_e32 v213, 0xbfb8aa3b, v205
	v_exp_f32_e32 v210, v210
	v_exp_f32_e32 v211, v211
	v_exp_f32_e32 v212, v212
	v_exp_f32_e32 v213, v213
	v_add_f32_e32 v210, 1.0, v210
	v_add_f32_e32 v211, 1.0, v211
	v_add_f32_e32 v212, 1.0, v212
	v_add_f32_e32 v213, 1.0, v213
	v_rcp_f32_e32 v210, v210
	v_rcp_f32_e32 v211, v211
	v_rcp_f32_e32 v212, v212
	v_rcp_f32_e32 v213, v213
	v_mul_f32_e32 v202, v202, v210
	v_mul_f32_e32 v203, v203, v211
	v_mul_f32_e32 v204, v204, v212
	v_mul_f32_e32 v205, v205, v213
	v_mul_f32_e32 v202, v202, v206
	v_mul_f32_e32 v203, v203, v207
	v_mul_f32_e32 v204, v204, v208
	v_mul_f32_e32 v205, v205, v209
	v_cvt_pk_bf16_f32 v14, v202, v203
	v_cvt_pk_bf16_f32 v15, v204, v205
	global_store_dwordx4 v168, v[140:143], s[4:5]
	v_add_u32_e32 v250, 0x1600, v168
	global_store_dwordx4 v250, v[108:111], s[4:5]
	s_nop 0
	v_add_u32_e32 v250, 0x2c00, v168
	global_store_dwordx4 v250, v[92:95], s[4:5]
	s_nop 0
	v_add_u32_e32 v250, 0x4200, v168
	global_store_dwordx4 v250, v[76:79], s[4:5]
	s_nop 0
	v_add_u32_e32 v250, 0xb0000, v168
	global_store_dwordx4 v250, v[60:63], s[4:5]
	s_nop 0
	v_add_u32_e32 v250, 0xb1600, v168
	global_store_dwordx4 v250, v[44:47], s[4:5]
	s_nop 0
	v_add_u32_e32 v250, 0xb2c00, v168
	global_store_dwordx4 v250, v[28:31], s[4:5]
	s_nop 0
	v_add_u32_e32 v250, 0xb4200, v168
	global_store_dwordx4 v250, v[12:15], s[4:5]
	s_nop 0
	s_and_b64 s[2:3], s[6:7], exec
	s_cbranch_scc0 .LepD_nonext
	s_xor_b32 s101, s101, 1
	s_or_b32 s101, s101, 2
	s_and_b32 s55, s101, 1
	s_mulk_i32 s55, 0x1800
	s_add_i32 s55, s55, 0x22c00
	v_readfirstlane_b32 s57, v230
	s_cmp_lt_u32 s57, 64
	s_cbranch_scc0 .LepD_nfe
	s_add_i32 s4, s56, 0
	s_ashr_i32 s4, s4, 2
	s_add_i32 s4, s4, 1
	s_cmp_gt_i32 s56, -1
	s_cselect_b32 s4, s4, 0
	s_mul_hi_i32 s5, s4, 0x5800
	s_mulk_i32 s4, 0x5800
	v_readlane_b32 s57, v254, 49
	v_readlane_b32 s99, v254, 50
	s_nop 0
	s_add_u32 s4, s57, s4
	s_addc_u32 s5, s99, s5
	v_readlane_b32 s2, v254, 5
	v_readlane_b32 s3, v254, 6
	v_readlane_b32 s28, v254, 7
	v_readlane_b32 s29, v254, 8
	s_nop 0
	v_and_b32_e32 v238, 63, v230
	v_lshrrev_b32_e32 v239, 5, v238
	v_and_b32_e32 v240, 31, v238
	v_lshlrev_b32_e32 v240, 4, v240
	s_lshl_b32 s57, s54, 9
	v_add_u32_e32 v240, s57, v240
	v_mul_u32_u24_e32 v241, 0x2c00, v239
	v_mul_u32_u24_e32 v242, 0x5800, v239
	v_add_u32_e32 v241, v241, v240
	v_add_u32_e32 v242, v242, v240
	v_lshlrev_b32_e32 v243, 4, v238
	s_lshl_b32 s57, s56, 10
	v_add_u32_e32 v243, s57, v243
	s_mov_b32 m0, s55
	s_nop 0
	global_load_lds_dwordx4 v243, s[12:13]
	s_add_i32 m0, s55, 1024
	s_nop 0
	global_load_lds_dwordx4 v241, s[4:5]
	s_add_i32 m0, s55, 2048
	s_nop 0
	global_load_lds_dwordx4 v242, s[2:3]
	v_add_u32_e32 v243, 0x2c00, v242
	s_add_i32 m0, s55, 3072
	s_nop 0
	global_load_lds_dwordx4 v243, s[2:3]
	v_add_u32_e32 v243, 0xb000, v241
	s_add_i32 m0, s55, 4096
	s_nop 0
	global_load_lds_dwordx4 v243, s[2:3]
	s_add_i32 m0, s55, 5120
	s_nop 0
	global_load_lds_dwordx4 v241, s[28:29]
.LepD_nfe:
.LepD_nonext:
	s_mov_b64 s[4:5], -1
	s_and_b64 vcc, exec, s[6:7]
	s_cbranch_vccz .LBB0_963
	s_andn2_b64 vcc, exec, s[10:11]
	s_cbranch_vccnz .LBB0_962
	s_barrier
	s_branch .LBB0_962

.LBB0_1742:
	s_add_u32 s0, s70, 0xf500000
	s_addc_u32 s1, s71, 0
	s_add_u32 s33, s70, 0xec63000
	s_addc_u32 s50, s71, 0
	s_cmp_gt_i32 s72, 18
	s_cselect_b64 s[4:5], -1, 0
	s_cmp_lt_i32 s73, 19
	s_cselect_b64 s[6:7], -1, 0
	s_or_b64 s[4:5], s[4:5], s[6:7]
	s_and_b64 vcc, exec, s[4:5]
	s_cbranch_vccnz .LBB0_1809
	v_readlane_b32 s4, v255, 2
	v_mov_b32_e32 v9, v230
	v_readlane_b32 s5, v255, 3
	s_and_b64 vcc, exec, s[4:5]
	v_readfirstlane_b32 s4, v9
	s_cbranch_vccnz .LBB0_1759
	v_lshlrev_b32_e32 v0, 4, v9
	s_waitcnt lgkmcnt(0)
	v_add_u32_e32 v1, 0x2000, v0
	v_ashrrev_i32_e32 v2, 31, v1
	v_lshrrev_b32_e32 v2, 22, v2
	v_add_u32_e32 v2, v1, v2
	v_ashrrev_i32_e32 v8, 10, v2
	v_mul_i32_i24_e32 v2, 0x400, v8
	v_sub_u32_e32 v1, v1, v2
	v_lshrrev_b32_e32 v2, 4, v1
	v_bitop3_b32 v1, v2, v1, 32 bitop3:0x6c
	v_ashrrev_i32_e32 v2, 31, v1
	v_lshrrev_b32_e32 v2, 26, v2
	v_add_u32_e32 v2, v1, v2
	v_lshlrev_b32_e32 v3, 3, v8
	v_ashrrev_i32_e32 v10, 6, v2
	v_and_b32_e32 v3, -16, v3
	v_add_u32_e32 v3, v10, v3
	v_and_b32_e32 v4, 3, v10
	s_mov_b32 s6, 0x1fffe0
	v_lshrrev_b32_e32 v5, 2, v3
	v_lshlrev_b32_e32 v6, 1, v3
	v_and_b32_e32 v2, 0xc0, v2
	v_and_or_b32 v4, v3, s6, v4
	v_and_b32_e32 v5, 4, v5
	v_and_b32_e32 v6, 24, v6
	v_sub_u32_e32 v1, v1, v2
	v_mov_b32_e32 v2, 1
	v_or3_b32 v4, v4, v5, v6
	v_lshlrev_b32_e32 v5, 5, v8
	v_ashrrev_i16_sdwa v1, v2, sext(v1) dst_sel:DWORD dst_unused:UNUSED_PAD src0_sel:DWORD src1_sel:BYTE_0
	v_and_b32_e32 v5, 32, v5
	v_bfe_i32 v11, v1, 0, 16
	v_add_lshl_u32 v1, v5, v11, 1
	v_lshl_add_u32 v144, v4, 11, v1
	v_lshl_add_u32 v146, v3, 11, v1
	v_lshrrev_b32_e32 v248, 11, v146
	v_and_b32_e32 v249, 0x7ff, v146
	v_and_b32_e32 v250, 15, v248
	v_lshlrev_b32_e32 v250, 2, v250
	v_bfe_u32 v251, v248, 4, 2
	v_and_or_b32 v248, v248, 64, v250
	v_or_b32_e32 v248, v248, v251
	v_lshl_or_b32 v146, v248, 11, v249
	v_bfe_i32 v1, v9, 27, 1
	v_lshrrev_b32_e32 v1, 22, v1
	v_add_u32_e32 v1, v0, v1
	v_and_b32_e32 v1, 0xfffffc00, v1
	v_sub_u32_e32 v0, v0, v1
	v_lshrrev_b32_e32 v1, 4, v0
	v_ashrrev_i32_e32 v3, 31, v9
	v_bitop3_b32 v0, v1, v0, 32 bitop3:0x6c
	v_lshrrev_b32_e32 v3, 26, v3
	v_ashrrev_i32_e32 v1, 31, v0
	v_add_u32_e32 v3, v9, v3
	s_add_u32 s20, s70, 0x3b00000
	v_lshrrev_b32_e32 v1, 26, v1
	v_ashrrev_i32_e32 v13, 6, v3
	s_addc_u32 s21, s71, 0
	s_ashr_i32 s7, s4, 6
	v_add_u32_e32 v1, v0, v1
	v_lshlrev_b32_e32 v3, 3, v13
	v_readlane_b32 s8, v254, 62
	s_ashr_i32 s5, s4, 8
	s_lshl_b32 s30, s7, 10
	v_ashrrev_i32_e32 v12, 6, v1
	v_and_b32_e32 v3, -16, v3
	v_readlane_b32 s9, v254, 63
	v_add_u32_e32 v3, v12, v3
	v_and_b32_e32 v4, 3, v12
	s_movk_i32 s31, 0x59
	s_and_b64 s[8:9], s[8:9], exec
	v_and_or_b32 v4, v3, s6, v4
	s_cselect_b32 s6, s31, 0x58
	v_readlane_b32 s8, v254, 51
	s_mul_i32 s6, s6, s8
	v_readlane_b32 s8, v254, 61
	s_add_i32 s6, s6, s8
	s_mul_hi_i32 s8, s6, 0x2e8ba2e9
	s_lshr_b32 s9, s8, 31
	s_ashr_i32 s8, s8, 5
	s_add_i32 s8, s8, s9
	s_lshl_b32 s9, s8, 3
	s_mulk_i32 s8, 0xb0
	s_sub_i32 s8, s6, s8
	s_bfe_u32 s6, s8, 0x3001c
	s_add_i32 s12, s8, s6
	s_sext_i32_i16 s6, s12
	s_and_b32 s12, s12, 0xfff8
	s_sub_i32 s8, s8, s12
	s_sext_i32_i16 s8, s8
	v_lshrrev_b32_e32 v5, 2, v3
	v_lshlrev_b32_e32 v6, 1, v3
	v_and_b32_e32 v1, 0xc0, v1
	s_lshr_b32 s6, s6, 3
	s_add_i32 s8, s9, s8
	v_and_b32_e32 v5, 4, v5
	v_and_b32_e32 v6, 24, v6
	v_sub_u32_e32 v0, v0, v1
	s_ashr_i32 s9, s8, 31
	s_bfe_i64 s[14:15], s[6:7], 0x100000
	v_or3_b32 v4, v4, v5, v6
	v_lshlrev_b32_e32 v5, 5, v13
	v_ashrrev_i16_sdwa v0, v2, sext(v0) dst_sel:DWORD dst_unused:UNUSED_PAD src0_sel:DWORD src1_sel:BYTE_0
	s_lshl_b64 s[12:13], s[8:9], 19
	s_lshl_b64 s[14:15], s[14:15], 18
	v_and_b32_e32 v5, 32, v5
	v_bfe_i32 v14, v0, 0, 16
	s_add_u32 s38, s0, s14
	v_add_lshl_u32 v0, v5, v14, 1
	s_addc_u32 s39, s1, s15
	s_add_i32 s42, s30, 0
	v_lshl_add_u32 v148, v4, 11, v0
	s_add_i32 m0, s42, 0x10000
	v_lshl_add_u32 v150, v3, 11, v0
	v_lshrrev_b32_e32 v248, 11, v150
	v_and_b32_e32 v249, 0x7ff, v150
	v_and_b32_e32 v250, 15, v248
	v_lshlrev_b32_e32 v250, 2, v250
	v_bfe_u32 v251, v248, 4, 2
	v_and_or_b32 v248, v248, 64, v250
	v_or_b32_e32 v248, v248, v251
	v_lshl_or_b32 v150, v248, 11, v249
	global_load_lds_dwordx4 v148, s[38:39]
	s_add_i32 m0, s42, 0x12000
	s_add_u32 s14, s38, 0x580000
	global_load_lds_dwordx4 v144, s[38:39]
	s_addc_u32 s15, s39, 0
	s_add_i32 m0, s42, 0x14000
	v_mov_b32_e32 v149, 0
	global_load_lds_dwordx4 v148, s[14:15]
	s_add_i32 m0, s42, 0x16000
	s_add_u32 s36, s20, s12
	s_addc_u32 s37, s21, s13
	s_add_i32 s43, s42, 0x2000
	global_load_lds_dwordx4 v144, s[14:15]
	s_mov_b32 m0, s42
	s_add_u32 s12, s36, 0x40000
	global_load_lds_dwordx4 v150, s[36:37]
	s_mov_b32 m0, s43
	s_addc_u32 s13, s37, 0
	s_add_i32 s44, s42, 0x4000
	global_load_lds_dwordx4 v146, s[36:37]
	s_mov_b32 m0, s44
	s_add_i32 s45, s42, 0x6000
	global_load_lds_dwordx4 v150, s[12:13]
	s_mov_b32 m0, s45
	v_mov_b32_e32 v145, v149
	global_load_lds_dwordx4 v146, s[12:13]
	v_mov_b32_e32 v151, v149
	v_mov_b32_e32 v147, v149
	s_cmp_eq_u32 s5, 1
	s_mov_b32 s46, 0
	s_mov_b32 s101, 0
	v_lshl_add_u64 v[6:7], s[38:39], 0, v[148:149]
	v_lshl_add_u64 v[4:5], s[38:39], 0, v[144:145]
	v_lshl_add_u64 v[0:1], s[36:37], 0, v[150:151]
	s_cselect_b64 s[12:13], -1, 0
	s_cmp_lg_u32 s5, 1
	v_lshl_add_u64 v[2:3], s[36:37], 0, v[146:147]
	s_cbranch_scc1 .LBB0_1746
	s_barrier

.LBB0_1755:
	s_and_b32 s32, s101, 1
	s_mulk_i32 s32, 0x1800
	s_add_i32 s32, s32, 0x22c00
	s_bitcmp1_b32 s101, 1
	s_cbranch_scc1 .LepA_fast
	v_readfirstlane_b32 s79, v230
	s_cmp_lt_u32 s79, 64
	s_cbranch_scc0 .LepA_nfs
	s_add_i32 s4, s8, -32
	s_ashr_i32 s4, s4, 2
	s_add_i32 s4, s4, 1
	s_cmp_gt_i32 s8, 31
	s_cselect_b32 s4, s4, 0
	s_mul_hi_i32 s5, s4, 0x5800
	s_mulk_i32 s4, 0x5800
	s_add_u32 s4, s33, s4
	s_addc_u32 s5, s50, s5
	v_readlane_b32 s36, v254, 5
	v_readlane_b32 s37, v254, 6
	v_readlane_b32 s38, v254, 7
	v_readlane_b32 s39, v254, 8
	s_nop 0
	s_add_u32 s36, s36, 0x10800
	s_addc_u32 s37, s37, 0
	s_add_u32 s38, s38, 0x5800
	s_addc_u32 s39, s39, 0
	v_and_b32_e32 v238, 63, v230
	v_lshrrev_b32_e32 v239, 5, v238
	v_and_b32_e32 v240, 31, v238
	v_lshlrev_b32_e32 v240, 4, v240
	s_lshl_b32 s79, s9, 9
	v_add_u32_e32 v240, s79, v240
	v_mul_u32_u24_e32 v241, 0x2c00, v239
	v_mul_u32_u24_e32 v242, 0x5800, v239
	v_add_u32_e32 v241, v241, v240
	v_add_u32_e32 v242, v242, v240
	v_lshlrev_b32_e32 v243, 4, v238
	s_lshl_b32 s79, s8, 10
	v_add_u32_e32 v243, s79, v243
	s_mov_b32 m0, s32
	s_nop 0
	global_load_lds_dwordx4 v243, s[10:11]
	s_add_i32 m0, s32, 1024
	s_nop 0
	global_load_lds_dwordx4 v241, s[4:5]
	s_add_i32 m0, s32, 2048
	s_nop 0
	global_load_lds_dwordx4 v242, s[36:37]
	v_add_u32_e32 v243, 0x2c00, v242
	s_add_i32 m0, s32, 3072
	s_nop 0
	global_load_lds_dwordx4 v243, s[36:37]
	v_add_u32_e32 v243, 0xb000, v241
	s_add_i32 m0, s32, 4096
	s_nop 0
	global_load_lds_dwordx4 v243, s[36:37]
	s_add_i32 m0, s32, 5120
	s_nop 0
	global_load_lds_dwordx4 v241, s[38:39]

.LepA_fast:
	s_and_b32 s27, s12, 1
	v_and_b32_e32 v237, 15, v164
	v_and_b32_e32 v236, 64, v164
	v_lshl_add_u32 v236, v237, 2, v236
	v_mul_u32_u24_e32 v171, 0x1600, v236
	v_lshl_add_u32 v171, v166, 1, v171
	v_lshl_add_u32 v236, v236, 2, s32
	v_lshl_add_u32 v229, v166, 2, s32
	ds_read_b128 v[208:211], v236
	ds_read_b128 v[212:215], v236 offset:512
	ds_read_b128 v[200:203], v229 offset:1024
	ds_read_b128 v[204:207], v229 offset:1040
	ds_read_b128 v[216:219], v229 offset:1536
	ds_read_b128 v[220:223], v229 offset:1552
	ds_read_b128 v[128:131], v229 offset:2048
	ds_read_b128 v[132:135], v229 offset:2560
	ds_read_b128 v[136:139], v229 offset:4096
	ds_read_b128 v[140:143], v229 offset:5120
	ds_read_b128 v[160:163], v229 offset:3072
	ds_read_b128 v[172:175], v229 offset:3584
	ds_read_b128 v[176:179], v229 offset:4608
	ds_read_b128 v[180:183], v229 offset:5632
	s_mul_i32 s4, s8, 0x160000
	s_lshl_b32 s79, s9, 8
	s_add_i32 s4, s4, s79
	s_add_i32 s4, s4, 0x9300000
	s_add_u32 s4, s4, s70
	s_addc_u32 s5, s71, 0
	s_mov_b32 s79, 0x20800
	v_lshl_add_u32 v228, v166, 2, s79
	v_cmp_eq_u32_e64 s[36:37], 0, v237
	v_cmp_eq_u32_e64 s[38:39], 15, v237
	v_and_b32_e32 v231, 8, v237
	v_lshlrev_b32_e32 v231, 9, v231
	s_lshl_b32 s79, s27, 10
	v_add3_u32 v231, v231, v228, s79
	s_waitcnt lgkmcnt(12)
	v_fmamk_f32 v208, v208, 0x3a800000, v170
	v_fmamk_f32 v209, v209, 0x3a800000, v170
	v_fmamk_f32 v210, v210, 0x3a800000, v170
	v_fmamk_f32 v211, v211, 0x3a800000, v170
	v_fmamk_f32 v212, v212, 0x3a800000, v170
	v_fmamk_f32 v213, v213, 0x3a800000, v170
	v_fmamk_f32 v214, v214, 0x3a800000, v170
	v_fmamk_f32 v215, v215, 0x3a800000, v170
	s_mov_b32 s79, 0x800000
	v_mul_f32_e32 v224, 0x4b800000, v208
	v_mul_f32_e32 v225, 0x4b800000, v209
	v_mul_f32_e32 v226, 0x4b800000, v210
	v_mul_f32_e32 v227, 0x4b800000, v211
	v_mul_f32_e32 v232, 0x4b800000, v212
	v_mul_f32_e32 v233, 0x4b800000, v213
	v_mul_f32_e32 v234, 0x4b800000, v214
	v_mul_f32_e32 v235, 0x4b800000, v215
	v_cmp_gt_f32_e32 vcc, s79, v208
	s_nop 1
	v_cndmask_b32_e32 v208, v208, v224, vcc
	v_rsq_f32_e32 v208, v208
	s_nop 0
	v_mul_f32_e32 v224, 0x45800000, v208
	v_cndmask_b32_e32 v208, v208, v224, vcc
	v_cmp_gt_f32_e32 vcc, s79, v209
	s_nop 1
	v_cndmask_b32_e32 v209, v209, v225, vcc
	v_rsq_f32_e32 v209, v209
	s_nop 0
	v_mul_f32_e32 v225, 0x45800000, v209
	v_cndmask_b32_e32 v209, v209, v225, vcc
	v_cmp_gt_f32_e32 vcc, s79, v210
	s_nop 1
	v_cndmask_b32_e32 v210, v210, v226, vcc
	v_rsq_f32_e32 v210, v210
	s_nop 0
	v_mul_f32_e32 v226, 0x45800000, v210
	v_cndmask_b32_e32 v210, v210, v226, vcc
	v_cmp_gt_f32_e32 vcc, s79, v211
	s_nop 1
	v_cndmask_b32_e32 v211, v211, v227, vcc
	v_rsq_f32_e32 v211, v211
	s_nop 0
	v_mul_f32_e32 v227, 0x45800000, v211
	v_cndmask_b32_e32 v211, v211, v227, vcc
	v_cmp_gt_f32_e32 vcc, s79, v212
	s_nop 1
	v_cndmask_b32_e32 v212, v212, v232, vcc
	v_rsq_f32_e32 v212, v212
	s_nop 0
	v_mul_f32_e32 v232, 0x45800000, v212
	v_cndmask_b32_e32 v212, v212, v232, vcc
	v_cmp_gt_f32_e32 vcc, s79, v213
	s_nop 1
	v_cndmask_b32_e32 v213, v213, v233, vcc
	v_rsq_f32_e32 v213, v213
	s_nop 0
	v_mul_f32_e32 v233, 0x45800000, v213
	v_cndmask_b32_e32 v213, v213, v233, vcc
	v_cmp_gt_f32_e32 vcc, s79, v214
	s_nop 1
	v_cndmask_b32_e32 v214, v214, v234, vcc
	v_rsq_f32_e32 v214, v214
	s_nop 0
	v_mul_f32_e32 v234, 0x45800000, v214
	v_cndmask_b32_e32 v214, v214, v234, vcc
	v_cmp_gt_f32_e32 vcc, s79, v215
	s_nop 1
	v_cndmask_b32_e32 v215, v215, v235, vcc
	v_rsq_f32_e32 v215, v215
	s_nop 0
	v_mul_f32_e32 v235, 0x45800000, v215
	v_cndmask_b32_e32 v215, v215, v235, vcc
	s_waitcnt lgkmcnt(8)
	v_fma_f32 v124, v124, v208, v200
	v_fma_f32 v125, v125, v208, v201
	v_fma_f32 v126, v126, v208, v202
	v_fma_f32 v127, v127, v208, v203
	v_fma_f32 v120, v120, v208, v204
	v_fma_f32 v121, v121, v208, v205
	v_fma_f32 v122, v122, v208, v206
	v_fma_f32 v123, v123, v208, v207
	v_fma_f32 v108, v108, v208, v216
	v_fma_f32 v109, v109, v208, v217
	v_fma_f32 v110, v110, v208, v218
	v_fma_f32 v111, v111, v208, v219
	v_fma_f32 v104, v104, v208, v220
	v_fma_f32 v105, v105, v208, v221
	v_fma_f32 v106, v106, v208, v222
	v_fma_f32 v107, v107, v208, v223
	v_fma_f32 v116, v116, v209, v200
	v_fma_f32 v117, v117, v209, v201
	v_fma_f32 v118, v118, v209, v202
	v_fma_f32 v119, v119, v209, v203
	v_fma_f32 v112, v112, v209, v204
	v_fma_f32 v113, v113, v209, v205
	v_fma_f32 v114, v114, v209, v206
	v_fma_f32 v115, v115, v209, v207
	v_fma_f32 v100, v100, v209, v216
	v_fma_f32 v101, v101, v209, v217
	v_fma_f32 v102, v102, v209, v218
	v_fma_f32 v103, v103, v209, v219
	v_fma_f32 v92, v92, v209, v220
	v_fma_f32 v93, v93, v209, v221
	v_fma_f32 v94, v94, v209, v222
	v_fma_f32 v95, v95, v209, v223
	v_fma_f32 v96, v96, v210, v200
	v_fma_f32 v97, v97, v210, v201
	v_fma_f32 v98, v98, v210, v202
	v_fma_f32 v99, v99, v210, v203
	v_fma_f32 v88, v88, v210, v204
	v_fma_f32 v89, v89, v210, v205
	v_fma_f32 v90, v90, v210, v206
	v_fma_f32 v91, v91, v210, v207
	v_fma_f32 v84, v84, v210, v216
	v_fma_f32 v85, v85, v210, v217
	v_fma_f32 v86, v86, v210, v218
	v_fma_f32 v87, v87, v210, v219
	v_fma_f32 v76, v76, v210, v220
	v_fma_f32 v77, v77, v210, v221
	v_fma_f32 v78, v78, v210, v222
	v_fma_f32 v79, v79, v210, v223
	v_fma_f32 v80, v80, v211, v200
	v_fma_f32 v81, v81, v211, v201
	v_fma_f32 v82, v82, v211, v202
	v_fma_f32 v83, v83, v211, v203
	v_fma_f32 v72, v72, v211, v204
	v_fma_f32 v73, v73, v211, v205
	v_fma_f32 v74, v74, v211, v206
	v_fma_f32 v75, v75, v211, v207
	v_fma_f32 v68, v68, v211, v216
	v_fma_f32 v69, v69, v211, v217
	v_fma_f32 v70, v70, v211, v218
	v_fma_f32 v71, v71, v211, v219
	v_fma_f32 v64, v64, v211, v220
	v_fma_f32 v65, v65, v211, v221
	v_fma_f32 v66, v66, v211, v222
	v_fma_f32 v67, v67, v211, v223
	v_fma_f32 v60, v60, v212, v200
	v_fma_f32 v61, v61, v212, v201
	v_fma_f32 v62, v62, v212, v202
	v_fma_f32 v63, v63, v212, v203
	v_fma_f32 v56, v56, v212, v204
	v_fma_f32 v57, v57, v212, v205
	v_fma_f32 v58, v58, v212, v206
	v_fma_f32 v59, v59, v212, v207
	v_fma_f32 v52, v52, v212, v216
	v_fma_f32 v53, v53, v212, v217
	v_fma_f32 v54, v54, v212, v218
	v_fma_f32 v55, v55, v212, v219
	v_fma_f32 v44, v44, v212, v220
	v_fma_f32 v45, v45, v212, v221
	v_fma_f32 v46, v46, v212, v222
	v_fma_f32 v47, v47, v212, v223
	v_fma_f32 v48, v48, v213, v200
	v_fma_f32 v49, v49, v213, v201
	v_fma_f32 v50, v50, v213, v202
	v_fma_f32 v51, v51, v213, v203
	v_fma_f32 v40, v40, v213, v204
	v_fma_f32 v41, v41, v213, v205
	v_fma_f32 v42, v42, v213, v206
	v_fma_f32 v43, v43, v213, v207
	v_fma_f32 v36, v36, v213, v216
	v_fma_f32 v37, v37, v213, v217
	v_fma_f32 v38, v38, v213, v218
	v_fma_f32 v39, v39, v213, v219
	v_fma_f32 v28, v28, v213, v220
	v_fma_f32 v29, v29, v213, v221
	v_fma_f32 v30, v30, v213, v222
	v_fma_f32 v31, v31, v213, v223
	v_fma_f32 v32, v32, v214, v200
	v_fma_f32 v33, v33, v214, v201
	v_fma_f32 v34, v34, v214, v202
	v_fma_f32 v35, v35, v214, v203
	v_fma_f32 v24, v24, v214, v204
	v_fma_f32 v25, v25, v214, v205
	v_fma_f32 v26, v26, v214, v206
	v_fma_f32 v27, v27, v214, v207
	v_fma_f32 v20, v20, v214, v216
	v_fma_f32 v21, v21, v214, v217
	v_fma_f32 v22, v22, v214, v218
	v_fma_f32 v23, v23, v214, v219
	v_fma_f32 v12, v12, v214, v220
	v_fma_f32 v13, v13, v214, v221
	v_fma_f32 v14, v14, v214, v222
	v_fma_f32 v15, v15, v214, v223
	v_fma_f32 v16, v16, v215, v200
	v_fma_f32 v17, v17, v215, v201
	v_fma_f32 v18, v18, v215, v202
	v_fma_f32 v19, v19, v215, v203
	v_fma_f32 v8, v8, v215, v204
	v_fma_f32 v9, v9, v215, v205
	v_fma_f32 v10, v10, v215, v206
	v_fma_f32 v11, v11, v215, v207
	v_fma_f32 v4, v4, v215, v216
	v_fma_f32 v5, v5, v215, v217
	v_fma_f32 v6, v6, v215, v218
	v_fma_f32 v7, v7, v215, v219
	v_fma_f32 v0, v0, v215, v220
	v_fma_f32 v1, v1, v215, v221
	v_fma_f32 v2, v2, v215, v222
	v_fma_f32 v3, v3, v215, v223
	v_mov_b32_e32 v212, 0
	v_mov_b32_e32 v213, 0
	v_mov_b32_e32 v214, 0
	v_mov_b32_e32 v215, 0
	s_lshl_b32 s96, s27, 12
	s_sub_i32 s96, 0x2000, s96
	s_mul_i32 s94, s27, 0x1400
	s_add_i32 s94, s94, 0xc00
	s_lshl_b32 s79, s27, 10
	s_add_i32 s95, s79, 5120
	s_add_i32 s92, s79, 1024
	s_mov_b64 exec, s[36:37]
	v_add_u32_e32 v250, s96, v228
	ds_write_b128 v250, v[124:127] offset:0
	ds_write_b128 v250, v[120:123] offset:16
	ds_write_b128 v250, v[108:111] offset:512
	ds_write_b128 v250, v[104:107] offset:528
	v_add_u32_e32 v250, s95, v228
	ds_write_b128 v250, v[60:63] offset:0
	ds_write_b128 v250, v[56:59] offset:16
	ds_write_b128 v250, v[52:55] offset:512
	ds_write_b128 v250, v[44:47] offset:528
	ds_write_b128 v228, v[212:215] offset:0
	ds_write_b128 v228, v[212:215] offset:16
	ds_write_b128 v228, v[212:215] offset:512
	ds_write_b128 v228, v[212:215] offset:528
	s_mov_b64 exec, s[38:39]
	v_add_u32_e32 v251, s92, v228
	ds_write_b128 v251, v[80:83] offset:0
	ds_write_b128 v251, v[72:75] offset:16
	ds_write_b128 v251, v[68:71] offset:512
	ds_write_b128 v251, v[64:67] offset:528
	v_add_u32_e32 v251, s94, v228
	ds_write_b128 v251, v[16:19] offset:0
	ds_write_b128 v251, v[8:11] offset:16
	ds_write_b128 v251, v[4:7] offset:512
	ds_write_b128 v251, v[0:3] offset:528
	ds_write_b128 v228, v[212:215] offset:7168
	ds_write_b128 v228, v[212:215] offset:7184
	ds_write_b128 v228, v[212:215] offset:7680
	ds_write_b128 v228, v[212:215] offset:7696
	s_mov_b64 exec, -1
	s_waitcnt lgkmcnt(0)
	s_barrier
	ds_read_b128 v[184:187], v231 offset:0
	ds_read_b128 v[188:191], v231 offset:512
	ds_read_b128 v[192:195], v231 offset:2048
	ds_read_b128 v[196:199], v231 offset:2560
	s_nop 0
	v_cndmask_b32_e64 v216, 0, v128, s[36:37]
	v_cndmask_b32_e64 v220, 0, v136, s[38:39]
	v_cndmask_b32_e64 v217, 0, v129, s[36:37]
	v_cndmask_b32_e64 v221, 0, v137, s[38:39]
	v_cndmask_b32_e64 v218, 0, v130, s[36:37]
	v_cndmask_b32_e64 v222, 0, v138, s[38:39]
	v_cndmask_b32_e64 v219, 0, v131, s[36:37]
	v_cndmask_b32_e64 v223, 0, v139, s[38:39]
	v_cndmask_b32_e64 v224, 0, v160, s[36:37]
	v_cndmask_b32_e64 v232, 0, v176, s[38:39]
	v_cndmask_b32_e64 v225, 0, v161, s[36:37]
	v_cndmask_b32_e64 v233, 0, v177, s[38:39]
	v_cndmask_b32_e64 v226, 0, v162, s[36:37]
	v_cndmask_b32_e64 v234, 0, v178, s[38:39]
	v_cndmask_b32_e64 v227, 0, v163, s[36:37]
	v_cndmask_b32_e64 v235, 0, v179, s[38:39]
	s_waitcnt lgkmcnt(0)
	s_nop 1
	v_fma_f32 v200, v132, v124, v140
	v_fma_f32 v201, v133, v125, v141
	v_fma_f32 v202, v134, v126, v142
	v_fma_f32 v203, v135, v127, v143
	v_fmac_f32_dpp v200, v80, v128 row_shr:1 row_mask:0xf bank_mask:0xf
	v_fmac_f32_dpp v201, v81, v129 row_shr:1 row_mask:0xf bank_mask:0xf
	v_fmac_f32_dpp v202, v82, v130 row_shr:1 row_mask:0xf bank_mask:0xf
	v_fmac_f32_dpp v203, v83, v131 row_shr:1 row_mask:0xf bank_mask:0xf
	v_fmac_f32_e32 v200, v184, v216
	v_fmac_f32_e32 v201, v185, v217
	v_fmac_f32_e32 v202, v186, v218
	v_fmac_f32_e32 v203, v187, v219
	v_fmac_f32_e32 v200, v116, v136
	v_fmac_f32_e32 v201, v117, v137
	v_fmac_f32_e32 v202, v118, v138
	v_fmac_f32_e32 v203, v119, v139
	v_fma_f32 v204, v172, v108, v180
	v_fma_f32 v205, v173, v109, v181
	v_fma_f32 v206, v174, v110, v182
	v_fma_f32 v207, v175, v111, v183
	v_fmac_f32_dpp v204, v68, v160 row_shr:1 row_mask:0xf bank_mask:0xf
	v_fmac_f32_dpp v205, v69, v161 row_shr:1 row_mask:0xf bank_mask:0xf
	v_fmac_f32_dpp v206, v70, v162 row_shr:1 row_mask:0xf bank_mask:0xf
	v_fmac_f32_dpp v207, v71, v163 row_shr:1 row_mask:0xf bank_mask:0xf
	v_fmac_f32_e32 v204, v188, v224
	v_fmac_f32_e32 v205, v189, v225
	v_fmac_f32_e32 v206, v190, v226
	v_fmac_f32_e32 v207, v191, v227
	v_fmac_f32_e32 v204, v100, v176
	v_fmac_f32_e32 v205, v101, v177
	v_fmac_f32_e32 v206, v102, v178
	v_fmac_f32_e32 v207, v103, v179
	v_mul_f32_e32 v208, 0xbfb8aa3b, v200
	v_mul_f32_e32 v209, 0xbfb8aa3b, v201
	v_mul_f32_e32 v210, 0xbfb8aa3b, v202
	v_mul_f32_e32 v211, 0xbfb8aa3b, v203
	v_exp_f32_e32 v208, v208
	v_exp_f32_e32 v209, v209
	v_exp_f32_e32 v210, v210
	v_exp_f32_e32 v211, v211
	v_add_f32_e32 v208, 1.0, v208
	v_add_f32_e32 v209, 1.0, v209
	v_add_f32_e32 v210, 1.0, v210
	v_add_f32_e32 v211, 1.0, v211
	v_rcp_f32_e32 v208, v208
	v_rcp_f32_e32 v209, v209
	v_rcp_f32_e32 v210, v210
	v_rcp_f32_e32 v211, v211
	v_mul_f32_e32 v200, v200, v208
	v_mul_f32_e32 v201, v201, v209
	v_mul_f32_e32 v202, v202, v210
	v_mul_f32_e32 v203, v203, v211
	v_mul_f32_e32 v200, v200, v204
	v_mul_f32_e32 v201, v201, v205
	v_mul_f32_e32 v202, v202, v206
	v_mul_f32_e32 v203, v203, v207
	v_cvt_pk_bf16_f32 v236, v200, v201
	v_cvt_pk_bf16_f32 v237, v202, v203
	v_fma_f32 v200, v132, v116, v140
	v_fma_f32 v201, v133, v117, v141
	v_fma_f32 v202, v134, v118, v142
	v_fma_f32 v203, v135, v119, v143
	v_fmac_f32_e32 v200, v124, v128
	v_fmac_f32_e32 v201, v125, v129
	v_fmac_f32_e32 v202, v126, v130
	v_fmac_f32_e32 v203, v127, v131
	v_fmac_f32_e32 v200, v96, v136
	v_fmac_f32_e32 v201, v97, v137
	v_fmac_f32_e32 v202, v98, v138
	v_fmac_f32_e32 v203, v99, v139
	v_fma_f32 v204, v172, v100, v180
	v_fma_f32 v205, v173, v101, v181
	v_fma_f32 v206, v174, v102, v182
	v_fma_f32 v207, v175, v103, v183
	v_fmac_f32_e32 v204, v108, v160
	v_fmac_f32_e32 v205, v109, v161
	v_fmac_f32_e32 v206, v110, v162
	v_fmac_f32_e32 v207, v111, v163
	v_fmac_f32_e32 v204, v84, v176
	v_fmac_f32_e32 v205, v85, v177
	v_fmac_f32_e32 v206, v86, v178
	v_fmac_f32_e32 v207, v87, v179
	v_mul_f32_e32 v208, 0xbfb8aa3b, v200
	v_mul_f32_e32 v209, 0xbfb8aa3b, v201
	v_mul_f32_e32 v210, 0xbfb8aa3b, v202
	v_mul_f32_e32 v211, 0xbfb8aa3b, v203
	v_exp_f32_e32 v208, v208
	v_exp_f32_e32 v209, v209
	v_exp_f32_e32 v210, v210
	v_exp_f32_e32 v211, v211
	v_add_f32_e32 v208, 1.0, v208
	v_add_f32_e32 v209, 1.0, v209
	v_add_f32_e32 v210, 1.0, v210
	v_add_f32_e32 v211, 1.0, v211
	v_rcp_f32_e32 v208, v208
	v_rcp_f32_e32 v209, v209
	v_rcp_f32_e32 v210, v210
	v_rcp_f32_e32 v211, v211
	v_mul_f32_e32 v200, v200, v208
	v_mul_f32_e32 v201, v201, v209
	v_mul_f32_e32 v202, v202, v210
	v_mul_f32_e32 v203, v203, v211
	v_mul_f32_e32 v200, v200, v204
	v_mul_f32_e32 v201, v201, v205
	v_mul_f32_e32 v202, v202, v206
	v_mul_f32_e32 v203, v203, v207
	v_cvt_pk_bf16_f32 v238, v200, v201
	v_cvt_pk_bf16_f32 v239, v202, v203
	v_fma_f32 v200, v132, v96, v140
	v_fma_f32 v201, v133, v97, v141
	v_fma_f32 v202, v134, v98, v142
	v_fma_f32 v203, v135, v99, v143
	v_fmac_f32_e32 v200, v116, v128
	v_fmac_f32_e32 v201, v117, v129
	v_fmac_f32_e32 v202, v118, v130
	v_fmac_f32_e32 v203, v119, v131
	v_fmac_f32_e32 v200, v80, v136
	v_fmac_f32_e32 v201, v81, v137
	v_fmac_f32_e32 v202, v82, v138
	v_fmac_f32_e32 v203, v83, v139
	v_fma_f32 v204, v172, v84, v180
	v_fma_f32 v205, v173, v85, v181
	v_fma_f32 v206, v174, v86, v182
	v_fma_f32 v207, v175, v87, v183
	v_fmac_f32_e32 v204, v100, v160
	v_fmac_f32_e32 v205, v101, v161
	v_fmac_f32_e32 v206, v102, v162
	v_fmac_f32_e32 v207, v103, v163
	v_fmac_f32_e32 v204, v68, v176
	v_fmac_f32_e32 v205, v69, v177
	v_fmac_f32_e32 v206, v70, v178
	v_fmac_f32_e32 v207, v71, v179
	v_mul_f32_e32 v208, 0xbfb8aa3b, v200
	v_mul_f32_e32 v209, 0xbfb8aa3b, v201
	v_mul_f32_e32 v210, 0xbfb8aa3b, v202
	v_mul_f32_e32 v211, 0xbfb8aa3b, v203
	v_exp_f32_e32 v208, v208
	v_exp_f32_e32 v209, v209
	v_exp_f32_e32 v210, v210
	v_exp_f32_e32 v211, v211
	v_add_f32_e32 v208, 1.0, v208
	v_add_f32_e32 v209, 1.0, v209
	v_add_f32_e32 v210, 1.0, v210
	v_add_f32_e32 v211, 1.0, v211
	v_rcp_f32_e32 v208, v208
	v_rcp_f32_e32 v209, v209
	v_rcp_f32_e32 v210, v210
	v_rcp_f32_e32 v211, v211
	v_mul_f32_e32 v200, v200, v208
	v_mul_f32_e32 v201, v201, v209
	v_mul_f32_e32 v202, v202, v210
	v_mul_f32_e32 v203, v203, v211
	v_mul_f32_e32 v200, v200, v204
	v_mul_f32_e32 v201, v201, v205
	v_mul_f32_e32 v202, v202, v206
	v_mul_f32_e32 v203, v203, v207
	v_cvt_pk_bf16_f32 v240, v200, v201
	v_cvt_pk_bf16_f32 v241, v202, v203
	v_fma_f32 v200, v132, v80, v140
	v_fma_f32 v201, v133, v81, v141
	v_fma_f32 v202, v134, v82, v142
	v_fma_f32 v203, v135, v83, v143
	v_fmac_f32_e32 v200, v96, v128
	v_fmac_f32_e32 v201, v97, v129
	v_fmac_f32_e32 v202, v98, v130
	v_fmac_f32_e32 v203, v99, v131
	v_fmac_f32_dpp v200, v124, v136 row_shl:1 row_mask:0xf bank_mask:0xf
	v_fmac_f32_dpp v201, v125, v137 row_shl:1 row_mask:0xf bank_mask:0xf
	v_fmac_f32_dpp v202, v126, v138 row_shl:1 row_mask:0xf bank_mask:0xf
	v_fmac_f32_dpp v203, v127, v139 row_shl:1 row_mask:0xf bank_mask:0xf
	v_fmac_f32_e32 v200, v184, v220
	v_fmac_f32_e32 v201, v185, v221
	v_fmac_f32_e32 v202, v186, v222
	v_fmac_f32_e32 v203, v187, v223
	v_fma_f32 v204, v172, v68, v180
	v_fma_f32 v205, v173, v69, v181
	v_fma_f32 v206, v174, v70, v182
	v_fma_f32 v207, v175, v71, v183
	v_fmac_f32_e32 v204, v84, v160
	v_fmac_f32_e32 v205, v85, v161
	v_fmac_f32_e32 v206, v86, v162
	v_fmac_f32_e32 v207, v87, v163
	v_fmac_f32_dpp v204, v108, v176 row_shl:1 row_mask:0xf bank_mask:0xf
	v_fmac_f32_dpp v205, v109, v177 row_shl:1 row_mask:0xf bank_mask:0xf
	v_fmac_f32_dpp v206, v110, v178 row_shl:1 row_mask:0xf bank_mask:0xf
	v_fmac_f32_dpp v207, v111, v179 row_shl:1 row_mask:0xf bank_mask:0xf
	v_fmac_f32_e32 v204, v188, v232
	v_fmac_f32_e32 v205, v189, v233
	v_fmac_f32_e32 v206, v190, v234
	v_fmac_f32_e32 v207, v191, v235
	v_mul_f32_e32 v208, 0xbfb8aa3b, v200
	v_mul_f32_e32 v209, 0xbfb8aa3b, v201
	v_mul_f32_e32 v210, 0xbfb8aa3b, v202
	v_mul_f32_e32 v211, 0xbfb8aa3b, v203
	v_exp_f32_e32 v208, v208
	v_exp_f32_e32 v209, v209
	v_exp_f32_e32 v210, v210
	v_exp_f32_e32 v211, v211
	v_add_f32_e32 v208, 1.0, v208
	v_add_f32_e32 v209, 1.0, v209
	v_add_f32_e32 v210, 1.0, v210
	v_add_f32_e32 v211, 1.0, v211
	v_rcp_f32_e32 v208, v208
	v_rcp_f32_e32 v209, v209
	v_rcp_f32_e32 v210, v210
	v_rcp_f32_e32 v211, v211
	v_mul_f32_e32 v200, v200, v208
	v_mul_f32_e32 v201, v201, v209
	v_mul_f32_e32 v202, v202, v210
	v_mul_f32_e32 v203, v203, v211
	v_mul_f32_e32 v200, v200, v204
	v_mul_f32_e32 v201, v201, v205
	v_mul_f32_e32 v202, v202, v206
	v_mul_f32_e32 v203, v203, v207
	v_cvt_pk_bf16_f32 v242, v200, v201
	v_cvt_pk_bf16_f32 v243, v202, v203
	v_fma_f32 v200, v132, v60, v140
	v_fma_f32 v201, v133, v61, v141
	v_fma_f32 v202, v134, v62, v142
	v_fma_f32 v203, v135, v63, v143
	v_fmac_f32_dpp v200, v16, v128 row_shr:1 row_mask:0xf bank_mask:0xf
	v_fmac_f32_dpp v201, v17, v129 row_shr:1 row_mask:0xf bank_mask:0xf
	v_fmac_f32_dpp v202, v18, v130 row_shr:1 row_mask:0xf bank_mask:0xf
	v_fmac_f32_dpp v203, v19, v131 row_shr:1 row_mask:0xf bank_mask:0xf
	v_fmac_f32_e32 v200, v192, v216
	v_fmac_f32_e32 v201, v193, v217
	v_fmac_f32_e32 v202, v194, v218
	v_fmac_f32_e32 v203, v195, v219
	v_fmac_f32_e32 v200, v48, v136
	v_fmac_f32_e32 v201, v49, v137
	v_fmac_f32_e32 v202, v50, v138
	v_fmac_f32_e32 v203, v51, v139
	v_fma_f32 v204, v172, v52, v180
	v_fma_f32 v205, v173, v53, v181
	v_fma_f32 v206, v174, v54, v182
	v_fma_f32 v207, v175, v55, v183
	v_fmac_f32_dpp v204, v4, v160 row_shr:1 row_mask:0xf bank_mask:0xf
	v_fmac_f32_dpp v205, v5, v161 row_shr:1 row_mask:0xf bank_mask:0xf
	v_fmac_f32_dpp v206, v6, v162 row_shr:1 row_mask:0xf bank_mask:0xf
	v_fmac_f32_dpp v207, v7, v163 row_shr:1 row_mask:0xf bank_mask:0xf
	v_fmac_f32_e32 v204, v196, v224
	v_fmac_f32_e32 v205, v197, v225
	v_fmac_f32_e32 v206, v198, v226
	v_fmac_f32_e32 v207, v199, v227
	v_fmac_f32_e32 v204, v36, v176
	v_fmac_f32_e32 v205, v37, v177
	v_fmac_f32_e32 v206, v38, v178
	v_fmac_f32_e32 v207, v39, v179
	v_mul_f32_e32 v208, 0xbfb8aa3b, v200
	v_mul_f32_e32 v209, 0xbfb8aa3b, v201
	v_mul_f32_e32 v210, 0xbfb8aa3b, v202
	v_mul_f32_e32 v211, 0xbfb8aa3b, v203
	v_exp_f32_e32 v208, v208
	v_exp_f32_e32 v209, v209
	v_exp_f32_e32 v210, v210
	v_exp_f32_e32 v211, v211
	v_add_f32_e32 v208, 1.0, v208
	v_add_f32_e32 v209, 1.0, v209
	v_add_f32_e32 v210, 1.0, v210
	v_add_f32_e32 v211, 1.0, v211
	v_rcp_f32_e32 v208, v208
	v_rcp_f32_e32 v209, v209
	v_rcp_f32_e32 v210, v210
	v_rcp_f32_e32 v211, v211
	v_mul_f32_e32 v200, v200, v208
	v_mul_f32_e32 v201, v201, v209
	v_mul_f32_e32 v202, v202, v210
	v_mul_f32_e32 v203, v203, v211
	v_mul_f32_e32 v200, v200, v204
	v_mul_f32_e32 v201, v201, v205
	v_mul_f32_e32 v202, v202, v206
	v_mul_f32_e32 v203, v203, v207
	v_cvt_pk_bf16_f32 v244, v200, v201
	v_cvt_pk_bf16_f32 v245, v202, v203
	v_fma_f32 v200, v132, v48, v140
	v_fma_f32 v201, v133, v49, v141
	v_fma_f32 v202, v134, v50, v142
	v_fma_f32 v203, v135, v51, v143
	v_fmac_f32_e32 v200, v60, v128
	v_fmac_f32_e32 v201, v61, v129
	v_fmac_f32_e32 v202, v62, v130
	v_fmac_f32_e32 v203, v63, v131
	v_fmac_f32_e32 v200, v32, v136
	v_fmac_f32_e32 v201, v33, v137
	v_fmac_f32_e32 v202, v34, v138
	v_fmac_f32_e32 v203, v35, v139
	v_fma_f32 v204, v172, v36, v180
	v_fma_f32 v205, v173, v37, v181
	v_fma_f32 v206, v174, v38, v182
	v_fma_f32 v207, v175, v39, v183
	v_fmac_f32_e32 v204, v52, v160
	v_fmac_f32_e32 v205, v53, v161
	v_fmac_f32_e32 v206, v54, v162
	v_fmac_f32_e32 v207, v55, v163
	v_fmac_f32_e32 v204, v20, v176
	v_fmac_f32_e32 v205, v21, v177
	v_fmac_f32_e32 v206, v22, v178
	v_fmac_f32_e32 v207, v23, v179
	v_mul_f32_e32 v208, 0xbfb8aa3b, v200
	v_mul_f32_e32 v209, 0xbfb8aa3b, v201
	v_mul_f32_e32 v210, 0xbfb8aa3b, v202
	v_mul_f32_e32 v211, 0xbfb8aa3b, v203
	v_exp_f32_e32 v208, v208
	v_exp_f32_e32 v209, v209
	v_exp_f32_e32 v210, v210
	v_exp_f32_e32 v211, v211
	v_add_f32_e32 v208, 1.0, v208
	v_add_f32_e32 v209, 1.0, v209
	v_add_f32_e32 v210, 1.0, v210
	v_add_f32_e32 v211, 1.0, v211
	v_rcp_f32_e32 v208, v208
	v_rcp_f32_e32 v209, v209
	v_rcp_f32_e32 v210, v210
	v_rcp_f32_e32 v211, v211
	v_mul_f32_e32 v200, v200, v208
	v_mul_f32_e32 v201, v201, v209
	v_mul_f32_e32 v202, v202, v210
	v_mul_f32_e32 v203, v203, v211
	v_mul_f32_e32 v200, v200, v204
	v_mul_f32_e32 v201, v201, v205
	v_mul_f32_e32 v202, v202, v206
	v_mul_f32_e32 v203, v203, v207
	v_cvt_pk_bf16_f32 v246, v200, v201
	v_cvt_pk_bf16_f32 v247, v202, v203
	v_fma_f32 v200, v132, v32, v140
	v_fma_f32 v201, v133, v33, v141
	v_fma_f32 v202, v134, v34, v142
	v_fma_f32 v203, v135, v35, v143
	v_fmac_f32_e32 v200, v48, v128
	v_fmac_f32_e32 v201, v49, v129
	v_fmac_f32_e32 v202, v50, v130
	v_fmac_f32_e32 v203, v51, v131
	v_fmac_f32_e32 v200, v16, v136
	v_fmac_f32_e32 v201, v17, v137
	v_fmac_f32_e32 v202, v18, v138
	v_fmac_f32_e32 v203, v19, v139
	v_fma_f32 v204, v172, v20, v180
	v_fma_f32 v205, v173, v21, v181
	v_fma_f32 v206, v174, v22, v182
	v_fma_f32 v207, v175, v23, v183
	v_fmac_f32_e32 v204, v36, v160
	v_fmac_f32_e32 v205, v37, v161
	v_fmac_f32_e32 v206, v38, v162
	v_fmac_f32_e32 v207, v39, v163
	v_fmac_f32_e32 v204, v4, v176
	v_fmac_f32_e32 v205, v5, v177
	v_fmac_f32_e32 v206, v6, v178
	v_fmac_f32_e32 v207, v7, v179
	v_mul_f32_e32 v208, 0xbfb8aa3b, v200
	v_mul_f32_e32 v209, 0xbfb8aa3b, v201
	v_mul_f32_e32 v210, 0xbfb8aa3b, v202
	v_mul_f32_e32 v211, 0xbfb8aa3b, v203
	v_exp_f32_e32 v208, v208
	v_exp_f32_e32 v209, v209
	v_exp_f32_e32 v210, v210
	v_exp_f32_e32 v211, v211
	v_add_f32_e32 v208, 1.0, v208
	v_add_f32_e32 v209, 1.0, v209
	v_add_f32_e32 v210, 1.0, v210
	v_add_f32_e32 v211, 1.0, v211
	v_rcp_f32_e32 v208, v208
	v_rcp_f32_e32 v209, v209
	v_rcp_f32_e32 v210, v210
	v_rcp_f32_e32 v211, v211
	v_mul_f32_e32 v200, v200, v208
	v_mul_f32_e32 v201, v201, v209
	v_mul_f32_e32 v202, v202, v210
	v_mul_f32_e32 v203, v203, v211
	v_mul_f32_e32 v200, v200, v204
	v_mul_f32_e32 v201, v201, v205
	v_mul_f32_e32 v202, v202, v206
	v_mul_f32_e32 v203, v203, v207
	v_cvt_pk_bf16_f32 v248, v200, v201
	v_cvt_pk_bf16_f32 v249, v202, v203
	v_fma_f32 v200, v132, v16, v140
	v_fma_f32 v201, v133, v17, v141
	v_fma_f32 v202, v134, v18, v142
	v_fma_f32 v203, v135, v19, v143
	v_fmac_f32_e32 v200, v32, v128
	v_fmac_f32_e32 v201, v33, v129
	v_fmac_f32_e32 v202, v34, v130
	v_fmac_f32_e32 v203, v35, v131
	v_fmac_f32_dpp v200, v60, v136 row_shl:1 row_mask:0xf bank_mask:0xf
	v_fmac_f32_dpp v201, v61, v137 row_shl:1 row_mask:0xf bank_mask:0xf
	v_fmac_f32_dpp v202, v62, v138 row_shl:1 row_mask:0xf bank_mask:0xf
	v_fmac_f32_dpp v203, v63, v139 row_shl:1 row_mask:0xf bank_mask:0xf
	v_fmac_f32_e32 v200, v192, v220
	v_fmac_f32_e32 v201, v193, v221
	v_fmac_f32_e32 v202, v194, v222
	v_fmac_f32_e32 v203, v195, v223
	v_fma_f32 v204, v172, v4, v180
	v_fma_f32 v205, v173, v5, v181
	v_fma_f32 v206, v174, v6, v182
	v_fma_f32 v207, v175, v7, v183
	v_fmac_f32_e32 v204, v20, v160
	v_fmac_f32_e32 v205, v21, v161
	v_fmac_f32_e32 v206, v22, v162
	v_fmac_f32_e32 v207, v23, v163
	v_fmac_f32_dpp v204, v52, v176 row_shl:1 row_mask:0xf bank_mask:0xf
	v_fmac_f32_dpp v205, v53, v177 row_shl:1 row_mask:0xf bank_mask:0xf
	v_fmac_f32_dpp v206, v54, v178 row_shl:1 row_mask:0xf bank_mask:0xf
	v_fmac_f32_dpp v207, v55, v179 row_shl:1 row_mask:0xf bank_mask:0xf
	v_fmac_f32_e32 v204, v196, v232
	v_fmac_f32_e32 v205, v197, v233
	v_fmac_f32_e32 v206, v198, v234
	v_fmac_f32_e32 v207, v199, v235
	v_mul_f32_e32 v208, 0xbfb8aa3b, v200
	v_mul_f32_e32 v209, 0xbfb8aa3b, v201
	v_mul_f32_e32 v210, 0xbfb8aa3b, v202
	v_mul_f32_e32 v211, 0xbfb8aa3b, v203
	v_exp_f32_e32 v208, v208
	v_exp_f32_e32 v209, v209
	v_exp_f32_e32 v210, v210
	v_exp_f32_e32 v211, v211
	v_add_f32_e32 v208, 1.0, v208
	v_add_f32_e32 v209, 1.0, v209
	v_add_f32_e32 v210, 1.0, v210
	v_add_f32_e32 v211, 1.0, v211
	v_rcp_f32_e32 v208, v208
	v_rcp_f32_e32 v209, v209
	v_rcp_f32_e32 v210, v210
	v_rcp_f32_e32 v211, v211
	v_mul_f32_e32 v200, v200, v208
	v_mul_f32_e32 v201, v201, v209
	v_mul_f32_e32 v202, v202, v210
	v_mul_f32_e32 v203, v203, v211
	v_mul_f32_e32 v200, v200, v204
	v_mul_f32_e32 v201, v201, v205
	v_mul_f32_e32 v202, v202, v206
	v_mul_f32_e32 v203, v203, v207
	v_cvt_pk_bf16_f32 v250, v200, v201
	v_cvt_pk_bf16_f32 v251, v202, v203
	ds_read_b128 v[128:131], v229 offset:2064
	ds_read_b128 v[132:135], v229 offset:2576
	ds_read_b128 v[136:139], v229 offset:4112
	ds_read_b128 v[140:143], v229 offset:5136
	ds_read_b128 v[160:163], v229 offset:3088
	ds_read_b128 v[172:175], v229 offset:3600
	ds_read_b128 v[176:179], v229 offset:4624
	ds_read_b128 v[180:183], v229 offset:5648
	v_mov_b32_e32 v124, v236
	v_mov_b32_e32 v125, v237
	v_mov_b32_e32 v116, v238
	v_mov_b32_e32 v117, v239
	v_mov_b32_e32 v96, v240
	v_mov_b32_e32 v97, v241
	v_mov_b32_e32 v80, v242
	v_mov_b32_e32 v81, v243
	v_mov_b32_e32 v60, v244
	v_mov_b32_e32 v61, v245
	v_mov_b32_e32 v48, v246
	v_mov_b32_e32 v49, v247
	v_mov_b32_e32 v32, v248
	v_mov_b32_e32 v33, v249
	v_mov_b32_e32 v16, v250
	v_mov_b32_e32 v17, v251
	ds_read_b128 v[184:187], v231 offset:16
	ds_read_b128 v[188:191], v231 offset:528
	ds_read_b128 v[192:195], v231 offset:2064
	ds_read_b128 v[196:199], v231 offset:2576
	s_waitcnt lgkmcnt(4)
	v_cndmask_b32_e64 v216, 0, v128, s[36:37]
	v_cndmask_b32_e64 v220, 0, v136, s[38:39]
	v_cndmask_b32_e64 v217, 0, v129, s[36:37]
	v_cndmask_b32_e64 v221, 0, v137, s[38:39]
	v_cndmask_b32_e64 v218, 0, v130, s[36:37]
	v_cndmask_b32_e64 v222, 0, v138, s[38:39]
	v_cndmask_b32_e64 v219, 0, v131, s[36:37]
	v_cndmask_b32_e64 v223, 0, v139, s[38:39]
	v_cndmask_b32_e64 v224, 0, v160, s[36:37]
	v_cndmask_b32_e64 v232, 0, v176, s[38:39]
	v_cndmask_b32_e64 v225, 0, v161, s[36:37]
	v_cndmask_b32_e64 v233, 0, v177, s[38:39]
	v_cndmask_b32_e64 v226, 0, v162, s[36:37]
	v_cndmask_b32_e64 v234, 0, v178, s[38:39]
	v_cndmask_b32_e64 v227, 0, v163, s[36:37]
	v_cndmask_b32_e64 v235, 0, v179, s[38:39]
	s_waitcnt lgkmcnt(0)
	s_nop 1
	v_fma_f32 v200, v132, v120, v140
	v_fma_f32 v201, v133, v121, v141
	v_fma_f32 v202, v134, v122, v142
	v_fma_f32 v203, v135, v123, v143
	v_fmac_f32_dpp v200, v72, v128 row_shr:1 row_mask:0xf bank_mask:0xf
	v_fmac_f32_dpp v201, v73, v129 row_shr:1 row_mask:0xf bank_mask:0xf
	v_fmac_f32_dpp v202, v74, v130 row_shr:1 row_mask:0xf bank_mask:0xf
	v_fmac_f32_dpp v203, v75, v131 row_shr:1 row_mask:0xf bank_mask:0xf
	v_fmac_f32_e32 v200, v184, v216
	v_fmac_f32_e32 v201, v185, v217
	v_fmac_f32_e32 v202, v186, v218
	v_fmac_f32_e32 v203, v187, v219
	v_fmac_f32_e32 v200, v112, v136
	v_fmac_f32_e32 v201, v113, v137
	v_fmac_f32_e32 v202, v114, v138
	v_fmac_f32_e32 v203, v115, v139
	v_fma_f32 v204, v172, v104, v180
	v_fma_f32 v205, v173, v105, v181
	v_fma_f32 v206, v174, v106, v182
	v_fma_f32 v207, v175, v107, v183
	v_fmac_f32_dpp v204, v64, v160 row_shr:1 row_mask:0xf bank_mask:0xf
	v_fmac_f32_dpp v205, v65, v161 row_shr:1 row_mask:0xf bank_mask:0xf
	v_fmac_f32_dpp v206, v66, v162 row_shr:1 row_mask:0xf bank_mask:0xf
	v_fmac_f32_dpp v207, v67, v163 row_shr:1 row_mask:0xf bank_mask:0xf
	v_fmac_f32_e32 v204, v188, v224
	v_fmac_f32_e32 v205, v189, v225
	v_fmac_f32_e32 v206, v190, v226
	v_fmac_f32_e32 v207, v191, v227
	v_fmac_f32_e32 v204, v92, v176
	v_fmac_f32_e32 v205, v93, v177
	v_fmac_f32_e32 v206, v94, v178
	v_fmac_f32_e32 v207, v95, v179
	v_mul_f32_e32 v208, 0xbfb8aa3b, v200
	v_mul_f32_e32 v209, 0xbfb8aa3b, v201
	v_mul_f32_e32 v210, 0xbfb8aa3b, v202
	v_mul_f32_e32 v211, 0xbfb8aa3b, v203
	v_exp_f32_e32 v208, v208
	v_exp_f32_e32 v209, v209
	v_exp_f32_e32 v210, v210
	v_exp_f32_e32 v211, v211
	v_add_f32_e32 v208, 1.0, v208
	v_add_f32_e32 v209, 1.0, v209
	v_add_f32_e32 v210, 1.0, v210
	v_add_f32_e32 v211, 1.0, v211
	v_rcp_f32_e32 v208, v208
	v_rcp_f32_e32 v209, v209
	v_rcp_f32_e32 v210, v210
	v_rcp_f32_e32 v211, v211
	v_mul_f32_e32 v200, v200, v208
	v_mul_f32_e32 v201, v201, v209
	v_mul_f32_e32 v202, v202, v210
	v_mul_f32_e32 v203, v203, v211
	v_mul_f32_e32 v200, v200, v204
	v_mul_f32_e32 v201, v201, v205
	v_mul_f32_e32 v202, v202, v206
	v_mul_f32_e32 v203, v203, v207
	v_cvt_pk_bf16_f32 v126, v200, v201
	v_cvt_pk_bf16_f32 v127, v202, v203
	v_fma_f32 v200, v132, v112, v140
	v_fma_f32 v201, v133, v113, v141
	v_fma_f32 v202, v134, v114, v142
	v_fma_f32 v203, v135, v115, v143
	v_fmac_f32_e32 v200, v120, v128
	v_fmac_f32_e32 v201, v121, v129
	v_fmac_f32_e32 v202, v122, v130
	v_fmac_f32_e32 v203, v123, v131
	v_fmac_f32_e32 v200, v88, v136
	v_fmac_f32_e32 v201, v89, v137
	v_fmac_f32_e32 v202, v90, v138
	v_fmac_f32_e32 v203, v91, v139
	v_fma_f32 v204, v172, v92, v180
	v_fma_f32 v205, v173, v93, v181
	v_fma_f32 v206, v174, v94, v182
	v_fma_f32 v207, v175, v95, v183
	v_fmac_f32_e32 v204, v104, v160
	v_fmac_f32_e32 v205, v105, v161
	v_fmac_f32_e32 v206, v106, v162
	v_fmac_f32_e32 v207, v107, v163
	v_fmac_f32_e32 v204, v76, v176
	v_fmac_f32_e32 v205, v77, v177
	v_fmac_f32_e32 v206, v78, v178
	v_fmac_f32_e32 v207, v79, v179
	v_mul_f32_e32 v208, 0xbfb8aa3b, v200
	v_mul_f32_e32 v209, 0xbfb8aa3b, v201
	v_mul_f32_e32 v210, 0xbfb8aa3b, v202
	v_mul_f32_e32 v211, 0xbfb8aa3b, v203
	v_exp_f32_e32 v208, v208
	v_exp_f32_e32 v209, v209
	v_exp_f32_e32 v210, v210
	v_exp_f32_e32 v211, v211
	v_add_f32_e32 v208, 1.0, v208
	v_add_f32_e32 v209, 1.0, v209
	v_add_f32_e32 v210, 1.0, v210
	v_add_f32_e32 v211, 1.0, v211
	v_rcp_f32_e32 v208, v208
	v_rcp_f32_e32 v209, v209
	v_rcp_f32_e32 v210, v210
	v_rcp_f32_e32 v211, v211
	v_mul_f32_e32 v200, v200, v208
	v_mul_f32_e32 v201, v201, v209
	v_mul_f32_e32 v202, v202, v210
	v_mul_f32_e32 v203, v203, v211
	v_mul_f32_e32 v200, v200, v204
	v_mul_f32_e32 v201, v201, v205
	v_mul_f32_e32 v202, v202, v206
	v_mul_f32_e32 v203, v203, v207
	v_cvt_pk_bf16_f32 v118, v200, v201
	v_cvt_pk_bf16_f32 v119, v202, v203
	v_fma_f32 v200, v132, v88, v140
	v_fma_f32 v201, v133, v89, v141
	v_fma_f32 v202, v134, v90, v142
	v_fma_f32 v203, v135, v91, v143
	v_fmac_f32_e32 v200, v112, v128
	v_fmac_f32_e32 v201, v113, v129
	v_fmac_f32_e32 v202, v114, v130
	v_fmac_f32_e32 v203, v115, v131
	v_fmac_f32_e32 v200, v72, v136
	v_fmac_f32_e32 v201, v73, v137
	v_fmac_f32_e32 v202, v74, v138
	v_fmac_f32_e32 v203, v75, v139
	v_fma_f32 v204, v172, v76, v180
	v_fma_f32 v205, v173, v77, v181
	v_fma_f32 v206, v174, v78, v182
	v_fma_f32 v207, v175, v79, v183
	v_fmac_f32_e32 v204, v92, v160
	v_fmac_f32_e32 v205, v93, v161
	v_fmac_f32_e32 v206, v94, v162
	v_fmac_f32_e32 v207, v95, v163
	v_fmac_f32_e32 v204, v64, v176
	v_fmac_f32_e32 v205, v65, v177
	v_fmac_f32_e32 v206, v66, v178
	v_fmac_f32_e32 v207, v67, v179
	v_mul_f32_e32 v208, 0xbfb8aa3b, v200
	v_mul_f32_e32 v209, 0xbfb8aa3b, v201
	v_mul_f32_e32 v210, 0xbfb8aa3b, v202
	v_mul_f32_e32 v211, 0xbfb8aa3b, v203
	v_exp_f32_e32 v208, v208
	v_exp_f32_e32 v209, v209
	v_exp_f32_e32 v210, v210
	v_exp_f32_e32 v211, v211
	v_add_f32_e32 v208, 1.0, v208
	v_add_f32_e32 v209, 1.0, v209
	v_add_f32_e32 v210, 1.0, v210
	v_add_f32_e32 v211, 1.0, v211
	v_rcp_f32_e32 v208, v208
	v_rcp_f32_e32 v209, v209
	v_rcp_f32_e32 v210, v210
	v_rcp_f32_e32 v211, v211
	v_mul_f32_e32 v200, v200, v208
	v_mul_f32_e32 v201, v201, v209
	v_mul_f32_e32 v202, v202, v210
	v_mul_f32_e32 v203, v203, v211
	v_mul_f32_e32 v200, v200, v204
	v_mul_f32_e32 v201, v201, v205
	v_mul_f32_e32 v202, v202, v206
	v_mul_f32_e32 v203, v203, v207
	v_cvt_pk_bf16_f32 v98, v200, v201
	v_cvt_pk_bf16_f32 v99, v202, v203
	v_fma_f32 v200, v132, v72, v140
	v_fma_f32 v201, v133, v73, v141
	v_fma_f32 v202, v134, v74, v142
	v_fma_f32 v203, v135, v75, v143
	v_fmac_f32_e32 v200, v88, v128
	v_fmac_f32_e32 v201, v89, v129
	v_fmac_f32_e32 v202, v90, v130
	v_fmac_f32_e32 v203, v91, v131
	v_fmac_f32_dpp v200, v120, v136 row_shl:1 row_mask:0xf bank_mask:0xf
	v_fmac_f32_dpp v201, v121, v137 row_shl:1 row_mask:0xf bank_mask:0xf
	v_fmac_f32_dpp v202, v122, v138 row_shl:1 row_mask:0xf bank_mask:0xf
	v_fmac_f32_dpp v203, v123, v139 row_shl:1 row_mask:0xf bank_mask:0xf
	v_fmac_f32_e32 v200, v184, v220
	v_fmac_f32_e32 v201, v185, v221
	v_fmac_f32_e32 v202, v186, v222
	v_fmac_f32_e32 v203, v187, v223
	v_fma_f32 v204, v172, v64, v180
	v_fma_f32 v205, v173, v65, v181
	v_fma_f32 v206, v174, v66, v182
	v_fma_f32 v207, v175, v67, v183
	v_fmac_f32_e32 v204, v76, v160
	v_fmac_f32_e32 v205, v77, v161
	v_fmac_f32_e32 v206, v78, v162
	v_fmac_f32_e32 v207, v79, v163
	v_fmac_f32_dpp v204, v104, v176 row_shl:1 row_mask:0xf bank_mask:0xf
	v_fmac_f32_dpp v205, v105, v177 row_shl:1 row_mask:0xf bank_mask:0xf
	v_fmac_f32_dpp v206, v106, v178 row_shl:1 row_mask:0xf bank_mask:0xf
	v_fmac_f32_dpp v207, v107, v179 row_shl:1 row_mask:0xf bank_mask:0xf
	v_fmac_f32_e32 v204, v188, v232
	v_fmac_f32_e32 v205, v189, v233
	v_fmac_f32_e32 v206, v190, v234
	v_fmac_f32_e32 v207, v191, v235
	v_mul_f32_e32 v208, 0xbfb8aa3b, v200
	v_mul_f32_e32 v209, 0xbfb8aa3b, v201
	v_mul_f32_e32 v210, 0xbfb8aa3b, v202
	v_mul_f32_e32 v211, 0xbfb8aa3b, v203
	v_exp_f32_e32 v208, v208
	v_exp_f32_e32 v209, v209
	v_exp_f32_e32 v210, v210
	v_exp_f32_e32 v211, v211
	v_add_f32_e32 v208, 1.0, v208
	v_add_f32_e32 v209, 1.0, v209
	v_add_f32_e32 v210, 1.0, v210
	v_add_f32_e32 v211, 1.0, v211
	v_rcp_f32_e32 v208, v208
	v_rcp_f32_e32 v209, v209
	v_rcp_f32_e32 v210, v210
	v_rcp_f32_e32 v211, v211
	v_mul_f32_e32 v200, v200, v208
	v_mul_f32_e32 v201, v201, v209
	v_mul_f32_e32 v202, v202, v210
	v_mul_f32_e32 v203, v203, v211
	v_mul_f32_e32 v200, v200, v204
	v_mul_f32_e32 v201, v201, v205
	v_mul_f32_e32 v202, v202, v206
	v_mul_f32_e32 v203, v203, v207
	v_cvt_pk_bf16_f32 v82, v200, v201
	v_cvt_pk_bf16_f32 v83, v202, v203
	v_fma_f32 v200, v132, v56, v140
	v_fma_f32 v201, v133, v57, v141
	v_fma_f32 v202, v134, v58, v142
	v_fma_f32 v203, v135, v59, v143
	v_fmac_f32_dpp v200, v8, v128 row_shr:1 row_mask:0xf bank_mask:0xf
	v_fmac_f32_dpp v201, v9, v129 row_shr:1 row_mask:0xf bank_mask:0xf
	v_fmac_f32_dpp v202, v10, v130 row_shr:1 row_mask:0xf bank_mask:0xf
	v_fmac_f32_dpp v203, v11, v131 row_shr:1 row_mask:0xf bank_mask:0xf
	v_fmac_f32_e32 v200, v192, v216
	v_fmac_f32_e32 v201, v193, v217
	v_fmac_f32_e32 v202, v194, v218
	v_fmac_f32_e32 v203, v195, v219
	v_fmac_f32_e32 v200, v40, v136
	v_fmac_f32_e32 v201, v41, v137
	v_fmac_f32_e32 v202, v42, v138
	v_fmac_f32_e32 v203, v43, v139
	v_fma_f32 v204, v172, v44, v180
	v_fma_f32 v205, v173, v45, v181
	v_fma_f32 v206, v174, v46, v182
	v_fma_f32 v207, v175, v47, v183
	v_fmac_f32_dpp v204, v0, v160 row_shr:1 row_mask:0xf bank_mask:0xf
	v_fmac_f32_dpp v205, v1, v161 row_shr:1 row_mask:0xf bank_mask:0xf
	v_fmac_f32_dpp v206, v2, v162 row_shr:1 row_mask:0xf bank_mask:0xf
	v_fmac_f32_dpp v207, v3, v163 row_shr:1 row_mask:0xf bank_mask:0xf
	v_fmac_f32_e32 v204, v196, v224
	v_fmac_f32_e32 v205, v197, v225
	v_fmac_f32_e32 v206, v198, v226
	v_fmac_f32_e32 v207, v199, v227
	v_fmac_f32_e32 v204, v28, v176
	v_fmac_f32_e32 v205, v29, v177
	v_fmac_f32_e32 v206, v30, v178
	v_fmac_f32_e32 v207, v31, v179
	v_mul_f32_e32 v208, 0xbfb8aa3b, v200
	v_mul_f32_e32 v209, 0xbfb8aa3b, v201
	v_mul_f32_e32 v210, 0xbfb8aa3b, v202
	v_mul_f32_e32 v211, 0xbfb8aa3b, v203
	v_exp_f32_e32 v208, v208
	v_exp_f32_e32 v209, v209
	v_exp_f32_e32 v210, v210
	v_exp_f32_e32 v211, v211
	v_add_f32_e32 v208, 1.0, v208
	v_add_f32_e32 v209, 1.0, v209
	v_add_f32_e32 v210, 1.0, v210
	v_add_f32_e32 v211, 1.0, v211
	v_rcp_f32_e32 v208, v208
	v_rcp_f32_e32 v209, v209
	v_rcp_f32_e32 v210, v210
	v_rcp_f32_e32 v211, v211
	v_mul_f32_e32 v200, v200, v208
	v_mul_f32_e32 v201, v201, v209
	v_mul_f32_e32 v202, v202, v210
	v_mul_f32_e32 v203, v203, v211
	v_mul_f32_e32 v200, v200, v204
	v_mul_f32_e32 v201, v201, v205
	v_mul_f32_e32 v202, v202, v206
	v_mul_f32_e32 v203, v203, v207
	v_cvt_pk_bf16_f32 v62, v200, v201
	v_cvt_pk_bf16_f32 v63, v202, v203
	v_fma_f32 v200, v132, v40, v140
	v_fma_f32 v201, v133, v41, v141
	v_fma_f32 v202, v134, v42, v142
	v_fma_f32 v203, v135, v43, v143
	v_fmac_f32_e32 v200, v56, v128
	v_fmac_f32_e32 v201, v57, v129
	v_fmac_f32_e32 v202, v58, v130
	v_fmac_f32_e32 v203, v59, v131
	v_fmac_f32_e32 v200, v24, v136
	v_fmac_f32_e32 v201, v25, v137
	v_fmac_f32_e32 v202, v26, v138
	v_fmac_f32_e32 v203, v27, v139
	v_fma_f32 v204, v172, v28, v180
	v_fma_f32 v205, v173, v29, v181
	v_fma_f32 v206, v174, v30, v182
	v_fma_f32 v207, v175, v31, v183
	v_fmac_f32_e32 v204, v44, v160
	v_fmac_f32_e32 v205, v45, v161
	v_fmac_f32_e32 v206, v46, v162
	v_fmac_f32_e32 v207, v47, v163
	v_fmac_f32_e32 v204, v12, v176
	v_fmac_f32_e32 v205, v13, v177
	v_fmac_f32_e32 v206, v14, v178
	v_fmac_f32_e32 v207, v15, v179
	v_mul_f32_e32 v208, 0xbfb8aa3b, v200
	v_mul_f32_e32 v209, 0xbfb8aa3b, v201
	v_mul_f32_e32 v210, 0xbfb8aa3b, v202
	v_mul_f32_e32 v211, 0xbfb8aa3b, v203
	v_exp_f32_e32 v208, v208
	v_exp_f32_e32 v209, v209
	v_exp_f32_e32 v210, v210
	v_exp_f32_e32 v211, v211
	v_add_f32_e32 v208, 1.0, v208
	v_add_f32_e32 v209, 1.0, v209
	v_add_f32_e32 v210, 1.0, v210
	v_add_f32_e32 v211, 1.0, v211
	v_rcp_f32_e32 v208, v208
	v_rcp_f32_e32 v209, v209
	v_rcp_f32_e32 v210, v210
	v_rcp_f32_e32 v211, v211
	v_mul_f32_e32 v200, v200, v208
	v_mul_f32_e32 v201, v201, v209
	v_mul_f32_e32 v202, v202, v210
	v_mul_f32_e32 v203, v203, v211
	v_mul_f32_e32 v200, v200, v204
	v_mul_f32_e32 v201, v201, v205
	v_mul_f32_e32 v202, v202, v206
	v_mul_f32_e32 v203, v203, v207
	v_cvt_pk_bf16_f32 v50, v200, v201
	v_cvt_pk_bf16_f32 v51, v202, v203
	v_fma_f32 v200, v132, v24, v140
	v_fma_f32 v201, v133, v25, v141
	v_fma_f32 v202, v134, v26, v142
	v_fma_f32 v203, v135, v27, v143
	v_fmac_f32_e32 v200, v40, v128
	v_fmac_f32_e32 v201, v41, v129
	v_fmac_f32_e32 v202, v42, v130
	v_fmac_f32_e32 v203, v43, v131
	v_fmac_f32_e32 v200, v8, v136
	v_fmac_f32_e32 v201, v9, v137
	v_fmac_f32_e32 v202, v10, v138
	v_fmac_f32_e32 v203, v11, v139
	v_fma_f32 v204, v172, v12, v180
	v_fma_f32 v205, v173, v13, v181
	v_fma_f32 v206, v174, v14, v182
	v_fma_f32 v207, v175, v15, v183
	v_fmac_f32_e32 v204, v28, v160
	v_fmac_f32_e32 v205, v29, v161
	v_fmac_f32_e32 v206, v30, v162
	v_fmac_f32_e32 v207, v31, v163
	v_fmac_f32_e32 v204, v0, v176
	v_fmac_f32_e32 v205, v1, v177
	v_fmac_f32_e32 v206, v2, v178
	v_fmac_f32_e32 v207, v3, v179
	v_mul_f32_e32 v208, 0xbfb8aa3b, v200
	v_mul_f32_e32 v209, 0xbfb8aa3b, v201
	v_mul_f32_e32 v210, 0xbfb8aa3b, v202
	v_mul_f32_e32 v211, 0xbfb8aa3b, v203
	v_exp_f32_e32 v208, v208
	v_exp_f32_e32 v209, v209
	v_exp_f32_e32 v210, v210
	v_exp_f32_e32 v211, v211
	v_add_f32_e32 v208, 1.0, v208
	v_add_f32_e32 v209, 1.0, v209
	v_add_f32_e32 v210, 1.0, v210
	v_add_f32_e32 v211, 1.0, v211
	v_rcp_f32_e32 v208, v208
	v_rcp_f32_e32 v209, v209
	v_rcp_f32_e32 v210, v210
	v_rcp_f32_e32 v211, v211
	v_mul_f32_e32 v200, v200, v208
	v_mul_f32_e32 v201, v201, v209
	v_mul_f32_e32 v202, v202, v210
	v_mul_f32_e32 v203, v203, v211
	v_mul_f32_e32 v200, v200, v204
	v_mul_f32_e32 v201, v201, v205
	v_mul_f32_e32 v202, v202, v206
	v_mul_f32_e32 v203, v203, v207
	v_cvt_pk_bf16_f32 v34, v200, v201
	v_cvt_pk_bf16_f32 v35, v202, v203
	v_fma_f32 v200, v132, v8, v140
	v_fma_f32 v201, v133, v9, v141
	v_fma_f32 v202, v134, v10, v142
	v_fma_f32 v203, v135, v11, v143
	v_fmac_f32_e32 v200, v24, v128
	v_fmac_f32_e32 v201, v25, v129
	v_fmac_f32_e32 v202, v26, v130
	v_fmac_f32_e32 v203, v27, v131
	v_fmac_f32_dpp v200, v56, v136 row_shl:1 row_mask:0xf bank_mask:0xf
	v_fmac_f32_dpp v201, v57, v137 row_shl:1 row_mask:0xf bank_mask:0xf
	v_fmac_f32_dpp v202, v58, v138 row_shl:1 row_mask:0xf bank_mask:0xf
	v_fmac_f32_dpp v203, v59, v139 row_shl:1 row_mask:0xf bank_mask:0xf
	v_fmac_f32_e32 v200, v192, v220
	v_fmac_f32_e32 v201, v193, v221
	v_fmac_f32_e32 v202, v194, v222
	v_fmac_f32_e32 v203, v195, v223
	v_fma_f32 v204, v172, v0, v180
	v_fma_f32 v205, v173, v1, v181
	v_fma_f32 v206, v174, v2, v182
	v_fma_f32 v207, v175, v3, v183
	v_fmac_f32_e32 v204, v12, v160
	v_fmac_f32_e32 v205, v13, v161
	v_fmac_f32_e32 v206, v14, v162
	v_fmac_f32_e32 v207, v15, v163
	v_fmac_f32_dpp v204, v44, v176 row_shl:1 row_mask:0xf bank_mask:0xf
	v_fmac_f32_dpp v205, v45, v177 row_shl:1 row_mask:0xf bank_mask:0xf
	v_fmac_f32_dpp v206, v46, v178 row_shl:1 row_mask:0xf bank_mask:0xf
	v_fmac_f32_dpp v207, v47, v179 row_shl:1 row_mask:0xf bank_mask:0xf
	v_fmac_f32_e32 v204, v196, v232
	v_fmac_f32_e32 v205, v197, v233
	v_fmac_f32_e32 v206, v198, v234
	v_fmac_f32_e32 v207, v199, v235
	v_mul_f32_e32 v208, 0xbfb8aa3b, v200
	v_mul_f32_e32 v209, 0xbfb8aa3b, v201
	v_mul_f32_e32 v210, 0xbfb8aa3b, v202
	v_mul_f32_e32 v211, 0xbfb8aa3b, v203
	v_exp_f32_e32 v208, v208
	v_exp_f32_e32 v209, v209
	v_exp_f32_e32 v210, v210
	v_exp_f32_e32 v211, v211
	v_add_f32_e32 v208, 1.0, v208
	v_add_f32_e32 v209, 1.0, v209
	v_add_f32_e32 v210, 1.0, v210
	v_add_f32_e32 v211, 1.0, v211
	v_rcp_f32_e32 v208, v208
	v_rcp_f32_e32 v209, v209
	v_rcp_f32_e32 v210, v210
	v_rcp_f32_e32 v211, v211
	v_mul_f32_e32 v200, v200, v208
	v_mul_f32_e32 v201, v201, v209
	v_mul_f32_e32 v202, v202, v210
	v_mul_f32_e32 v203, v203, v211
	v_mul_f32_e32 v200, v200, v204
	v_mul_f32_e32 v201, v201, v205
	v_mul_f32_e32 v202, v202, v206
	v_mul_f32_e32 v203, v203, v207
	v_cvt_pk_bf16_f32 v18, v200, v201
	v_cvt_pk_bf16_f32 v19, v202, v203
	global_store_dwordx4 v171, v[124:127], s[4:5]
	v_add_u32_e32 v250, 0x1600, v171
	global_store_dwordx4 v250, v[116:119], s[4:5]
	s_nop 0
	v_add_u32_e32 v250, 0x2c00, v171
	global_store_dwordx4 v250, v[96:99], s[4:5]
	s_nop 0
	v_add_u32_e32 v250, 0x4200, v171
	global_store_dwordx4 v250, v[80:83], s[4:5]
	s_nop 0
	v_add_u32_e32 v250, 0xb0000, v171
	global_store_dwordx4 v250, v[60:63], s[4:5]
	s_nop 0
	v_add_u32_e32 v250, 0xb1600, v171
	global_store_dwordx4 v250, v[48:51], s[4:5]
	s_nop 0
	v_add_u32_e32 v250, 0xb2c00, v171
	global_store_dwordx4 v250, v[32:35], s[4:5]
	s_nop 0
	v_add_u32_e32 v250, 0xb4200, v171
	global_store_dwordx4 v250, v[16:19], s[4:5]
	s_nop 0
	s_and_b64 s[36:37], s[6:7], exec
	s_cbranch_scc0 .LepA_nonext
	s_xor_b32 s101, s101, 1
	s_or_b32 s101, s101, 2
	s_and_b32 s32, s101, 1
	s_mulk_i32 s32, 0x1800
	s_add_i32 s32, s32, 0x22c00
	v_readfirstlane_b32 s79, v230
	s_cmp_lt_u32 s79, 64
	s_cbranch_scc0 .LepA_nfe
	s_add_i32 s4, s26, -32
	s_ashr_i32 s4, s4, 2
	s_add_i32 s4, s4, 1
	s_cmp_gt_i32 s26, 31
	s_cselect_b32 s4, s4, 0
	s_mul_hi_i32 s5, s4, 0x5800
	s_mulk_i32 s4, 0x5800
	s_add_u32 s4, s33, s4
	s_addc_u32 s5, s50, s5
	v_readlane_b32 s36, v254, 5
	v_readlane_b32 s37, v254, 6
	v_readlane_b32 s38, v254, 7
	v_readlane_b32 s39, v254, 8
	s_nop 0
	s_add_u32 s36, s36, 0x10800
	s_addc_u32 s37, s37, 0
	s_add_u32 s38, s38, 0x5800
	s_addc_u32 s39, s39, 0
	v_and_b32_e32 v238, 63, v230
	v_lshrrev_b32_e32 v239, 5, v238
	v_and_b32_e32 v240, 31, v238
	v_lshlrev_b32_e32 v240, 4, v240
	s_lshl_b32 s79, s24, 9
	v_add_u32_e32 v240, s79, v240
	v_mul_u32_u24_e32 v241, 0x2c00, v239
	v_mul_u32_u24_e32 v242, 0x5800, v239
	v_add_u32_e32 v241, v241, v240
	v_add_u32_e32 v242, v242, v240
	v_lshlrev_b32_e32 v243, 4, v238
	s_lshl_b32 s79, s26, 10
	v_add_u32_e32 v243, s79, v243
	s_mov_b32 m0, s32
	s_nop 0
	global_load_lds_dwordx4 v243, s[10:11]
	s_add_i32 m0, s32, 1024
	s_nop 0
	global_load_lds_dwordx4 v241, s[4:5]
	s_add_i32 m0, s32, 2048
	s_nop 0
	global_load_lds_dwordx4 v242, s[36:37]
	v_add_u32_e32 v243, 0x2c00, v242
	s_add_i32 m0, s32, 3072
	s_nop 0
	global_load_lds_dwordx4 v243, s[36:37]
	v_add_u32_e32 v243, 0xb000, v241
	s_add_i32 m0, s32, 4096
	s_nop 0
	global_load_lds_dwordx4 v243, s[36:37]
	s_add_i32 m0, s32, 5120
	s_nop 0
	global_load_lds_dwordx4 v241, s[38:39]

.LBB0_1867:
	s_cmp_gt_i32 s72, 20
	s_cselect_b64 s[4:5], -1, 0
	s_cmp_lt_i32 s73, 21
	s_cselect_b64 s[6:7], -1, 0
	s_or_b64 s[4:5], s[4:5], s[6:7]
	s_and_b64 vcc, exec, s[4:5]
	s_cbranch_vccnz .LBB0_1934
	v_readlane_b32 s4, v255, 2
	v_mov_b32_e32 v9, v230
	v_readlane_b32 s5, v255, 3
	s_and_b64 vcc, exec, s[4:5]
	v_readfirstlane_b32 s5, v9
	s_cbranch_vccnz .LBB0_1884
	v_lshlrev_b32_e32 v0, 4, v9
	s_waitcnt lgkmcnt(0)
	v_add_u32_e32 v1, 0x2000, v0
	v_ashrrev_i32_e32 v2, 31, v1
	v_lshrrev_b32_e32 v2, 22, v2
	v_add_u32_e32 v2, v1, v2
	v_ashrrev_i32_e32 v8, 10, v2
	v_mul_i32_i24_e32 v2, 0x400, v8
	v_sub_u32_e32 v1, v1, v2
	v_lshrrev_b32_e32 v2, 4, v1
	v_bitop3_b32 v1, v2, v1, 32 bitop3:0x6c
	v_ashrrev_i32_e32 v2, 31, v1
	v_lshrrev_b32_e32 v2, 26, v2
	v_add_u32_e32 v2, v1, v2
	v_lshlrev_b32_e32 v3, 3, v8
	v_ashrrev_i32_e32 v10, 6, v2
	v_and_b32_e32 v3, -16, v3
	v_add_u32_e32 v3, v10, v3
	v_and_b32_e32 v4, 3, v10
	s_mov_b32 s4, 0x1fffe0
	v_lshrrev_b32_e32 v5, 2, v3
	v_lshlrev_b32_e32 v6, 1, v3
	v_and_b32_e32 v2, 0xc0, v2
	v_and_or_b32 v4, v3, s4, v4
	v_and_b32_e32 v5, 4, v5
	v_and_b32_e32 v6, 24, v6
	v_sub_u32_e32 v1, v1, v2
	v_mov_b32_e32 v2, 1
	v_or3_b32 v4, v4, v5, v6
	v_lshlrev_b32_e32 v5, 5, v8
	v_ashrrev_i16_sdwa v1, v2, sext(v1) dst_sel:DWORD dst_unused:UNUSED_PAD src0_sel:DWORD src1_sel:BYTE_0
	v_and_b32_e32 v5, 32, v5
	v_bfe_i32 v11, v1, 0, 16
	v_add_lshl_u32 v1, v5, v11, 1
	v_lshl_add_u32 v144, v4, 11, v1
	v_lshl_add_u32 v146, v3, 11, v1
	v_lshrrev_b32_e32 v248, 11, v146
	v_and_b32_e32 v249, 0x7ff, v146
	v_and_b32_e32 v250, 15, v248
	v_lshlrev_b32_e32 v250, 2, v250
	v_bfe_u32 v251, v248, 4, 2
	v_and_or_b32 v248, v248, 64, v250
	v_or_b32_e32 v248, v248, v251
	v_lshl_or_b32 v146, v248, 11, v249
	v_bfe_i32 v1, v9, 27, 1
	v_lshrrev_b32_e32 v1, 22, v1
	v_add_u32_e32 v1, v0, v1
	v_and_b32_e32 v1, 0xfffffc00, v1
	v_sub_u32_e32 v0, v0, v1
	v_lshrrev_b32_e32 v1, 4, v0
	v_ashrrev_i32_e32 v3, 31, v9
	v_bitop3_b32 v0, v1, v0, 32 bitop3:0x6c
	v_lshrrev_b32_e32 v3, 26, v3
	v_ashrrev_i32_e32 v1, 31, v0
	v_add_u32_e32 v3, v9, v3
	s_add_u32 s20, s70, 0x4b00000
	v_lshrrev_b32_e32 v1, 26, v1
	v_ashrrev_i32_e32 v13, 6, v3
	s_addc_u32 s21, s71, 0
	s_ashr_i32 s14, s5, 6
	v_add_u32_e32 v1, v0, v1
	v_lshlrev_b32_e32 v3, 3, v13
	v_readlane_b32 s6, v254, 62
	s_ashr_i32 s16, s5, 8
	s_lshl_b32 s38, s14, 10
	v_ashrrev_i32_e32 v12, 6, v1
	v_and_b32_e32 v3, -16, v3
	v_readlane_b32 s7, v254, 63
	v_add_u32_e32 v3, v12, v3
	v_and_b32_e32 v4, 3, v12
	s_movk_i32 s39, 0x59
	s_and_b64 s[6:7], s[6:7], exec
	v_and_or_b32 v4, v3, s4, v4
	s_cselect_b32 s4, s39, 0x58
	v_readlane_b32 s6, v254, 51
	s_mul_i32 s4, s4, s6
	v_readlane_b32 s6, v254, 61
	s_add_i32 s4, s4, s6
	s_mul_hi_i32 s6, s4, 0x2e8ba2e9
	s_lshr_b32 s7, s6, 31
	s_ashr_i32 s6, s6, 5
	s_add_i32 s6, s6, s7
	s_lshl_b32 s7, s6, 3
	s_mulk_i32 s6, 0xb0
	s_sub_i32 s6, s4, s6
	s_bfe_u32 s4, s6, 0x3001c
	s_add_i32 s8, s6, s4
	s_sext_i32_i16 s4, s8
	s_and_b32 s8, s8, 0xfff8
	s_sub_i32 s6, s6, s8
	s_sext_i32_i16 s6, s6
	v_lshrrev_b32_e32 v5, 2, v3
	v_lshlrev_b32_e32 v6, 1, v3
	v_and_b32_e32 v1, 0xc0, v1
	s_lshr_b32 s4, s4, 3
	s_add_i32 s6, s7, s6
	v_and_b32_e32 v5, 4, v5
	v_and_b32_e32 v6, 24, v6
	v_sub_u32_e32 v0, v0, v1
	s_ashr_i32 s7, s6, 31
	s_bfe_i64 s[10:11], s[4:5], 0x100000
	v_or3_b32 v4, v4, v5, v6
	v_lshlrev_b32_e32 v5, 5, v13
	v_ashrrev_i16_sdwa v0, v2, sext(v0) dst_sel:DWORD dst_unused:UNUSED_PAD src0_sel:DWORD src1_sel:BYTE_0
	s_lshl_b64 s[8:9], s[6:7], 19
	s_lshl_b64 s[10:11], s[10:11], 18
	v_and_b32_e32 v5, 32, v5
	v_bfe_i32 v14, v0, 0, 16
	s_add_u32 s34, s0, s10
	v_add_lshl_u32 v0, v5, v14, 1
	s_addc_u32 s35, s1, s11
	s_add_i32 s40, s38, 0
	v_lshl_add_u32 v148, v4, 11, v0
	s_add_i32 m0, s40, 0x10000
	v_lshl_add_u32 v150, v3, 11, v0
	v_lshrrev_b32_e32 v248, 11, v150
	v_and_b32_e32 v249, 0x7ff, v150
	v_and_b32_e32 v250, 15, v248
	v_lshlrev_b32_e32 v250, 2, v250
	v_bfe_u32 v251, v248, 4, 2
	v_and_or_b32 v248, v248, 64, v250
	v_or_b32_e32 v248, v248, v251
	v_lshl_or_b32 v150, v248, 11, v249
	global_load_lds_dwordx4 v148, s[34:35]
	s_add_i32 m0, s40, 0x12000
	s_add_u32 s10, s34, 0x580000
	global_load_lds_dwordx4 v144, s[34:35]
	s_addc_u32 s11, s35, 0
	s_add_i32 m0, s40, 0x14000
	v_mov_b32_e32 v149, 0
	global_load_lds_dwordx4 v148, s[10:11]
	s_add_i32 m0, s40, 0x16000
	s_add_u32 s30, s20, s8
	s_addc_u32 s31, s21, s9
	s_add_i32 s41, s40, 0x2000
	global_load_lds_dwordx4 v144, s[10:11]
	s_mov_b32 m0, s40
	s_add_u32 s8, s30, 0x40000
	global_load_lds_dwordx4 v150, s[30:31]
	s_mov_b32 m0, s41
	s_addc_u32 s9, s31, 0
	s_add_i32 s42, s40, 0x4000
	global_load_lds_dwordx4 v146, s[30:31]
	s_mov_b32 m0, s42
	s_add_i32 s43, s40, 0x6000
	global_load_lds_dwordx4 v150, s[8:9]
	s_mov_b32 m0, s43
	v_mov_b32_e32 v145, v149
	global_load_lds_dwordx4 v146, s[8:9]
	v_mov_b32_e32 v151, v149
	v_mov_b32_e32 v147, v149
	s_cmp_eq_u32 s16, 1
	s_mov_b32 s44, 0
	s_mov_b32 s101, 0
	v_lshl_add_u64 v[6:7], s[34:35], 0, v[148:149]
	v_lshl_add_u64 v[4:5], s[34:35], 0, v[144:145]
	v_lshl_add_u64 v[0:1], s[30:31], 0, v[150:151]
	s_cselect_b64 s[8:9], -1, 0
	s_cmp_lg_u32 s16, 1
	v_lshl_add_u64 v[2:3], s[30:31], 0, v[146:147]
	s_cbranch_scc1 .LBB0_1871
	s_barrier

.LBB0_1880:
	s_and_b32 s32, s101, 1
	s_mulk_i32 s32, 0x1800
	s_add_i32 s32, s32, 0x22c00
	s_bitcmp1_b32 s101, 1
	s_cbranch_scc1 .LepC_fast
	v_readfirstlane_b32 s79, v230
	s_cmp_lt_u32 s79, 64
	s_cbranch_scc0 .LepC_nfs
	s_add_i32 s30, s6, 0
	s_ashr_i32 s30, s30, 2
	s_add_i32 s30, s30, 1
	s_cmp_gt_i32 s6, -1
	s_cselect_b32 s30, s30, 0
	s_mul_hi_i32 s31, s30, 0x5800
	s_mulk_i32 s30, 0x5800
	s_add_u32 s30, s33, s30
	s_addc_u32 s31, s50, s31
	v_readlane_b32 s34, v254, 5
	v_readlane_b32 s35, v254, 6
	v_readlane_b32 s36, v254, 7
	v_readlane_b32 s37, v254, 8
	s_nop 0
	s_add_u32 s34, s34, 0x10800
	s_addc_u32 s35, s35, 0
	s_add_u32 s36, s36, 0x5800
	s_addc_u32 s37, s37, 0
	v_and_b32_e32 v238, 63, v230
	v_lshrrev_b32_e32 v239, 5, v238
	v_and_b32_e32 v240, 31, v238
	v_lshlrev_b32_e32 v240, 4, v240
	s_lshl_b32 s79, s7, 9
	v_add_u32_e32 v240, s79, v240
	v_mul_u32_u24_e32 v241, 0x2c00, v239
	v_mul_u32_u24_e32 v242, 0x5800, v239
	v_add_u32_e32 v241, v241, v240
	v_add_u32_e32 v242, v242, v240
	v_lshlrev_b32_e32 v243, 4, v238
	s_lshl_b32 s79, s6, 10
	v_add_u32_e32 v243, s79, v243
	s_mov_b32 m0, s32
	s_nop 0
	global_load_lds_dwordx4 v243, s[10:11]
	s_add_i32 m0, s32, 1024
	s_nop 0
	global_load_lds_dwordx4 v241, s[30:31]
	s_add_i32 m0, s32, 2048
	s_nop 0
	global_load_lds_dwordx4 v242, s[34:35]
	v_add_u32_e32 v243, 0x2c00, v242
	s_add_i32 m0, s32, 3072
	s_nop 0
	global_load_lds_dwordx4 v243, s[34:35]
	v_add_u32_e32 v243, 0xb000, v241
	s_add_i32 m0, s32, 4096
	s_nop 0
	global_load_lds_dwordx4 v243, s[34:35]
	s_add_i32 m0, s32, 5120
	s_nop 0
	global_load_lds_dwordx4 v241, s[36:37]

.LepC_fast:
	s_and_b32 s23, s8, 1
	v_and_b32_e32 v237, 15, v164
	v_and_b32_e32 v236, 64, v164
	v_lshl_add_u32 v236, v237, 2, v236
	v_mul_u32_u24_e32 v171, 0x1600, v236
	v_lshl_add_u32 v171, v166, 1, v171
	v_lshl_add_u32 v236, v236, 2, s32
	v_lshl_add_u32 v229, v166, 2, s32
	ds_read_b128 v[208:211], v236
	ds_read_b128 v[212:215], v236 offset:512
	ds_read_b128 v[200:203], v229 offset:1024
	ds_read_b128 v[204:207], v229 offset:1040
	ds_read_b128 v[216:219], v229 offset:1536
	ds_read_b128 v[220:223], v229 offset:1552
	ds_read_b128 v[128:131], v229 offset:2048
	ds_read_b128 v[132:135], v229 offset:2560
	ds_read_b128 v[136:139], v229 offset:4096
	ds_read_b128 v[140:143], v229 offset:5120
	ds_read_b128 v[160:163], v229 offset:3072
	ds_read_b128 v[172:175], v229 offset:3584
	ds_read_b128 v[176:179], v229 offset:4608
	ds_read_b128 v[180:183], v229 offset:5632
	s_mul_i32 s30, s6, 0x160000
	s_lshl_b32 s79, s7, 8
	s_add_i32 s30, s30, s79
	s_add_i32 s30, s30, 0xbf00000
	s_add_u32 s30, s30, s70
	s_addc_u32 s31, s71, 0
	s_mov_b32 s79, 0x20800
	v_lshl_add_u32 v228, v166, 2, s79
	v_cmp_eq_u32_e64 s[34:35], 0, v237
	v_cmp_eq_u32_e64 s[36:37], 15, v237
	v_and_b32_e32 v231, 8, v237
	v_lshlrev_b32_e32 v231, 9, v231
	s_lshl_b32 s79, s23, 10
	v_add3_u32 v231, v231, v228, s79
	s_waitcnt lgkmcnt(12)
	v_fmamk_f32 v208, v208, 0x3a800000, v170
	v_fmamk_f32 v209, v209, 0x3a800000, v170
	v_fmamk_f32 v210, v210, 0x3a800000, v170
	v_fmamk_f32 v211, v211, 0x3a800000, v170
	v_fmamk_f32 v212, v212, 0x3a800000, v170
	v_fmamk_f32 v213, v213, 0x3a800000, v170
	v_fmamk_f32 v214, v214, 0x3a800000, v170
	v_fmamk_f32 v215, v215, 0x3a800000, v170
	s_mov_b32 s79, 0x800000
	v_mul_f32_e32 v224, 0x4b800000, v208
	v_mul_f32_e32 v225, 0x4b800000, v209
	v_mul_f32_e32 v226, 0x4b800000, v210
	v_mul_f32_e32 v227, 0x4b800000, v211
	v_mul_f32_e32 v232, 0x4b800000, v212
	v_mul_f32_e32 v233, 0x4b800000, v213
	v_mul_f32_e32 v234, 0x4b800000, v214
	v_mul_f32_e32 v235, 0x4b800000, v215
	v_cmp_gt_f32_e32 vcc, s79, v208
	s_nop 1
	v_cndmask_b32_e32 v208, v208, v224, vcc
	v_rsq_f32_e32 v208, v208
	s_nop 0
	v_mul_f32_e32 v224, 0x45800000, v208
	v_cndmask_b32_e32 v208, v208, v224, vcc
	v_cmp_gt_f32_e32 vcc, s79, v209
	s_nop 1
	v_cndmask_b32_e32 v209, v209, v225, vcc
	v_rsq_f32_e32 v209, v209
	s_nop 0
	v_mul_f32_e32 v225, 0x45800000, v209
	v_cndmask_b32_e32 v209, v209, v225, vcc
	v_cmp_gt_f32_e32 vcc, s79, v210
	s_nop 1
	v_cndmask_b32_e32 v210, v210, v226, vcc
	v_rsq_f32_e32 v210, v210
	s_nop 0
	v_mul_f32_e32 v226, 0x45800000, v210
	v_cndmask_b32_e32 v210, v210, v226, vcc
	v_cmp_gt_f32_e32 vcc, s79, v211
	s_nop 1
	v_cndmask_b32_e32 v211, v211, v227, vcc
	v_rsq_f32_e32 v211, v211
	s_nop 0
	v_mul_f32_e32 v227, 0x45800000, v211
	v_cndmask_b32_e32 v211, v211, v227, vcc
	v_cmp_gt_f32_e32 vcc, s79, v212
	s_nop 1
	v_cndmask_b32_e32 v212, v212, v232, vcc
	v_rsq_f32_e32 v212, v212
	s_nop 0
	v_mul_f32_e32 v232, 0x45800000, v212
	v_cndmask_b32_e32 v212, v212, v232, vcc
	v_cmp_gt_f32_e32 vcc, s79, v213
	s_nop 1
	v_cndmask_b32_e32 v213, v213, v233, vcc
	v_rsq_f32_e32 v213, v213
	s_nop 0
	v_mul_f32_e32 v233, 0x45800000, v213
	v_cndmask_b32_e32 v213, v213, v233, vcc
	v_cmp_gt_f32_e32 vcc, s79, v214
	s_nop 1
	v_cndmask_b32_e32 v214, v214, v234, vcc
	v_rsq_f32_e32 v214, v214
	s_nop 0
	v_mul_f32_e32 v234, 0x45800000, v214
	v_cndmask_b32_e32 v214, v214, v234, vcc
	v_cmp_gt_f32_e32 vcc, s79, v215
	s_nop 1
	v_cndmask_b32_e32 v215, v215, v235, vcc
	v_rsq_f32_e32 v215, v215
	s_nop 0
	v_mul_f32_e32 v235, 0x45800000, v215
	v_cndmask_b32_e32 v215, v215, v235, vcc
	s_waitcnt lgkmcnt(8)
	v_fma_f32 v124, v124, v208, v200
	v_fma_f32 v125, v125, v208, v201
	v_fma_f32 v126, v126, v208, v202
	v_fma_f32 v127, v127, v208, v203
	v_fma_f32 v120, v120, v208, v204
	v_fma_f32 v121, v121, v208, v205
	v_fma_f32 v122, v122, v208, v206
	v_fma_f32 v123, v123, v208, v207
	v_fma_f32 v108, v108, v208, v216
	v_fma_f32 v109, v109, v208, v217
	v_fma_f32 v110, v110, v208, v218
	v_fma_f32 v111, v111, v208, v219
	v_fma_f32 v104, v104, v208, v220
	v_fma_f32 v105, v105, v208, v221
	v_fma_f32 v106, v106, v208, v222
	v_fma_f32 v107, v107, v208, v223
	v_fma_f32 v116, v116, v209, v200
	v_fma_f32 v117, v117, v209, v201
	v_fma_f32 v118, v118, v209, v202
	v_fma_f32 v119, v119, v209, v203
	v_fma_f32 v112, v112, v209, v204
	v_fma_f32 v113, v113, v209, v205
	v_fma_f32 v114, v114, v209, v206
	v_fma_f32 v115, v115, v209, v207
	v_fma_f32 v100, v100, v209, v216
	v_fma_f32 v101, v101, v209, v217
	v_fma_f32 v102, v102, v209, v218
	v_fma_f32 v103, v103, v209, v219
	v_fma_f32 v92, v92, v209, v220
	v_fma_f32 v93, v93, v209, v221
	v_fma_f32 v94, v94, v209, v222
	v_fma_f32 v95, v95, v209, v223
	v_fma_f32 v96, v96, v210, v200
	v_fma_f32 v97, v97, v210, v201
	v_fma_f32 v98, v98, v210, v202
	v_fma_f32 v99, v99, v210, v203
	v_fma_f32 v88, v88, v210, v204
	v_fma_f32 v89, v89, v210, v205
	v_fma_f32 v90, v90, v210, v206
	v_fma_f32 v91, v91, v210, v207
	v_fma_f32 v84, v84, v210, v216
	v_fma_f32 v85, v85, v210, v217
	v_fma_f32 v86, v86, v210, v218
	v_fma_f32 v87, v87, v210, v219
	v_fma_f32 v76, v76, v210, v220
	v_fma_f32 v77, v77, v210, v221
	v_fma_f32 v78, v78, v210, v222
	v_fma_f32 v79, v79, v210, v223
	v_fma_f32 v80, v80, v211, v200
	v_fma_f32 v81, v81, v211, v201
	v_fma_f32 v82, v82, v211, v202
	v_fma_f32 v83, v83, v211, v203
	v_fma_f32 v72, v72, v211, v204
	v_fma_f32 v73, v73, v211, v205
	v_fma_f32 v74, v74, v211, v206
	v_fma_f32 v75, v75, v211, v207
	v_fma_f32 v68, v68, v211, v216
	v_fma_f32 v69, v69, v211, v217
	v_fma_f32 v70, v70, v211, v218
	v_fma_f32 v71, v71, v211, v219
	v_fma_f32 v64, v64, v211, v220
	v_fma_f32 v65, v65, v211, v221
	v_fma_f32 v66, v66, v211, v222
	v_fma_f32 v67, v67, v211, v223
	v_fma_f32 v60, v60, v212, v200
	v_fma_f32 v61, v61, v212, v201
	v_fma_f32 v62, v62, v212, v202
	v_fma_f32 v63, v63, v212, v203
	v_fma_f32 v56, v56, v212, v204
	v_fma_f32 v57, v57, v212, v205
	v_fma_f32 v58, v58, v212, v206
	v_fma_f32 v59, v59, v212, v207
	v_fma_f32 v52, v52, v212, v216
	v_fma_f32 v53, v53, v212, v217
	v_fma_f32 v54, v54, v212, v218
	v_fma_f32 v55, v55, v212, v219
	v_fma_f32 v44, v44, v212, v220
	v_fma_f32 v45, v45, v212, v221
	v_fma_f32 v46, v46, v212, v222
	v_fma_f32 v47, v47, v212, v223
	v_fma_f32 v48, v48, v213, v200
	v_fma_f32 v49, v49, v213, v201
	v_fma_f32 v50, v50, v213, v202
	v_fma_f32 v51, v51, v213, v203
	v_fma_f32 v40, v40, v213, v204
	v_fma_f32 v41, v41, v213, v205
	v_fma_f32 v42, v42, v213, v206
	v_fma_f32 v43, v43, v213, v207
	v_fma_f32 v36, v36, v213, v216
	v_fma_f32 v37, v37, v213, v217
	v_fma_f32 v38, v38, v213, v218
	v_fma_f32 v39, v39, v213, v219
	v_fma_f32 v28, v28, v213, v220
	v_fma_f32 v29, v29, v213, v221
	v_fma_f32 v30, v30, v213, v222
	v_fma_f32 v31, v31, v213, v223
	v_fma_f32 v32, v32, v214, v200
	v_fma_f32 v33, v33, v214, v201
	v_fma_f32 v34, v34, v214, v202
	v_fma_f32 v35, v35, v214, v203
	v_fma_f32 v24, v24, v214, v204
	v_fma_f32 v25, v25, v214, v205
	v_fma_f32 v26, v26, v214, v206
	v_fma_f32 v27, v27, v214, v207
	v_fma_f32 v20, v20, v214, v216
	v_fma_f32 v21, v21, v214, v217
	v_fma_f32 v22, v22, v214, v218
	v_fma_f32 v23, v23, v214, v219
	v_fma_f32 v12, v12, v214, v220
	v_fma_f32 v13, v13, v214, v221
	v_fma_f32 v14, v14, v214, v222
	v_fma_f32 v15, v15, v214, v223
	v_fma_f32 v16, v16, v215, v200
	v_fma_f32 v17, v17, v215, v201
	v_fma_f32 v18, v18, v215, v202
	v_fma_f32 v19, v19, v215, v203
	v_fma_f32 v8, v8, v215, v204
	v_fma_f32 v9, v9, v215, v205
	v_fma_f32 v10, v10, v215, v206
	v_fma_f32 v11, v11, v215, v207
	v_fma_f32 v4, v4, v215, v216
	v_fma_f32 v5, v5, v215, v217
	v_fma_f32 v6, v6, v215, v218
	v_fma_f32 v7, v7, v215, v219
	v_fma_f32 v0, v0, v215, v220
	v_fma_f32 v1, v1, v215, v221
	v_fma_f32 v2, v2, v215, v222
	v_fma_f32 v3, v3, v215, v223
	v_mov_b32_e32 v212, 0
	v_mov_b32_e32 v213, 0
	v_mov_b32_e32 v214, 0
	v_mov_b32_e32 v215, 0
	s_lshl_b32 s96, s23, 12
	s_sub_i32 s96, 0x2000, s96
	s_mul_i32 s94, s23, 0x1400
	s_add_i32 s94, s94, 0xc00
	s_lshl_b32 s79, s23, 10
	s_add_i32 s95, s79, 5120
	s_add_i32 s92, s79, 1024
	s_mov_b64 exec, s[34:35]
	v_add_u32_e32 v250, s96, v228
	ds_write_b128 v250, v[124:127] offset:0
	ds_write_b128 v250, v[120:123] offset:16
	ds_write_b128 v250, v[108:111] offset:512
	ds_write_b128 v250, v[104:107] offset:528
	v_add_u32_e32 v250, s95, v228
	ds_write_b128 v250, v[60:63] offset:0
	ds_write_b128 v250, v[56:59] offset:16
	ds_write_b128 v250, v[52:55] offset:512
	ds_write_b128 v250, v[44:47] offset:528
	ds_write_b128 v228, v[212:215] offset:0
	ds_write_b128 v228, v[212:215] offset:16
	ds_write_b128 v228, v[212:215] offset:512
	ds_write_b128 v228, v[212:215] offset:528
	s_mov_b64 exec, s[36:37]
	v_add_u32_e32 v251, s92, v228
	ds_write_b128 v251, v[80:83] offset:0
	ds_write_b128 v251, v[72:75] offset:16
	ds_write_b128 v251, v[68:71] offset:512
	ds_write_b128 v251, v[64:67] offset:528
	v_add_u32_e32 v251, s94, v228
	ds_write_b128 v251, v[16:19] offset:0
	ds_write_b128 v251, v[8:11] offset:16
	ds_write_b128 v251, v[4:7] offset:512
	ds_write_b128 v251, v[0:3] offset:528
	ds_write_b128 v228, v[212:215] offset:7168
	ds_write_b128 v228, v[212:215] offset:7184
	ds_write_b128 v228, v[212:215] offset:7680
	ds_write_b128 v228, v[212:215] offset:7696
	s_mov_b64 exec, -1
	s_cmp_eq_u32 s23, 0
	s_cselect_b64 s[52:53], s[34:35], 0
	s_cselect_b64 s[54:55], 0, s[36:37]
	s_mul_i32 s56, s6, 0x16000
	s_add_u32 s56, s56, 0x5b00000
	s_add_u32 s56, s56, s70
	s_addc_u32 s57, s71, 0
	v_lshl_or_b32 v252, s7, 7, v166
	v_lshlrev_b32_e32 v252, 2, v252
	s_mov_b64 exec, s[52:53]
	global_store_dwordx4 v252, v[124:127], s[56:57]
	global_store_dwordx4 v252, v[120:123], s[56:57] offset:16
	v_add_u32_e32 v250, 0x2c00, v252
	global_store_dwordx4 v250, v[108:111], s[56:57]
	global_store_dwordx4 v250, v[104:107], s[56:57] offset:16
	s_mov_b64 exec, s[54:55]
	v_add_u32_e32 v250, 0xb000, v252
	global_store_dwordx4 v250, v[16:19], s[56:57]
	global_store_dwordx4 v250, v[8:11], s[56:57] offset:16
	v_add_u32_e32 v250, 0xdc00, v252
	global_store_dwordx4 v250, v[4:7], s[56:57]
	global_store_dwordx4 v250, v[0:3], s[56:57] offset:16
	s_mov_b64 exec, -1
	s_waitcnt lgkmcnt(0)
	s_barrier
	ds_read_b128 v[184:187], v231 offset:0
	ds_read_b128 v[188:191], v231 offset:512
	ds_read_b128 v[192:195], v231 offset:2048
	ds_read_b128 v[196:199], v231 offset:2560
	s_nop 0
	v_cndmask_b32_e64 v216, 0, v128, s[34:35]
	v_cndmask_b32_e64 v220, 0, v136, s[36:37]
	v_cndmask_b32_e64 v217, 0, v129, s[34:35]
	v_cndmask_b32_e64 v221, 0, v137, s[36:37]
	v_cndmask_b32_e64 v218, 0, v130, s[34:35]
	v_cndmask_b32_e64 v222, 0, v138, s[36:37]
	v_cndmask_b32_e64 v219, 0, v131, s[34:35]
	v_cndmask_b32_e64 v223, 0, v139, s[36:37]
	v_cndmask_b32_e64 v224, 0, v160, s[34:35]
	v_cndmask_b32_e64 v232, 0, v176, s[36:37]
	v_cndmask_b32_e64 v225, 0, v161, s[34:35]
	v_cndmask_b32_e64 v233, 0, v177, s[36:37]
	v_cndmask_b32_e64 v226, 0, v162, s[34:35]
	v_cndmask_b32_e64 v234, 0, v178, s[36:37]
	v_cndmask_b32_e64 v227, 0, v163, s[34:35]
	v_cndmask_b32_e64 v235, 0, v179, s[36:37]
	s_waitcnt lgkmcnt(0)
	s_nop 1
	v_fma_f32 v200, v132, v124, v140
	v_fma_f32 v201, v133, v125, v141
	v_fma_f32 v202, v134, v126, v142
	v_fma_f32 v203, v135, v127, v143
	v_fmac_f32_dpp v200, v80, v128 row_shr:1 row_mask:0xf bank_mask:0xf
	v_fmac_f32_dpp v201, v81, v129 row_shr:1 row_mask:0xf bank_mask:0xf
	v_fmac_f32_dpp v202, v82, v130 row_shr:1 row_mask:0xf bank_mask:0xf
	v_fmac_f32_dpp v203, v83, v131 row_shr:1 row_mask:0xf bank_mask:0xf
	v_fmac_f32_e32 v200, v184, v216
	v_fmac_f32_e32 v201, v185, v217
	v_fmac_f32_e32 v202, v186, v218
	v_fmac_f32_e32 v203, v187, v219
	v_fmac_f32_e32 v200, v116, v136
	v_fmac_f32_e32 v201, v117, v137
	v_fmac_f32_e32 v202, v118, v138
	v_fmac_f32_e32 v203, v119, v139
	v_fma_f32 v204, v172, v108, v180
	v_fma_f32 v205, v173, v109, v181
	v_fma_f32 v206, v174, v110, v182
	v_fma_f32 v207, v175, v111, v183
	v_fmac_f32_dpp v204, v68, v160 row_shr:1 row_mask:0xf bank_mask:0xf
	v_fmac_f32_dpp v205, v69, v161 row_shr:1 row_mask:0xf bank_mask:0xf
	v_fmac_f32_dpp v206, v70, v162 row_shr:1 row_mask:0xf bank_mask:0xf
	v_fmac_f32_dpp v207, v71, v163 row_shr:1 row_mask:0xf bank_mask:0xf
	v_fmac_f32_e32 v204, v188, v224
	v_fmac_f32_e32 v205, v189, v225
	v_fmac_f32_e32 v206, v190, v226
	v_fmac_f32_e32 v207, v191, v227
	v_fmac_f32_e32 v204, v100, v176
	v_fmac_f32_e32 v205, v101, v177
	v_fmac_f32_e32 v206, v102, v178
	v_fmac_f32_e32 v207, v103, v179
	s_mov_b64 exec, s[52:53]
	v_add_u32_e32 v250, 0x5800, v252
	global_store_dwordx4 v250, v[200:203], s[56:57]
	v_add_u32_e32 v250, 0x8400, v252
	global_store_dwordx4 v250, v[204:207], s[56:57]
	s_mov_b64 exec, -1
	s_nop 4
	v_mul_f32_e32 v208, 0xbfb8aa3b, v200
	v_mul_f32_e32 v209, 0xbfb8aa3b, v201
	v_mul_f32_e32 v210, 0xbfb8aa3b, v202
	v_mul_f32_e32 v211, 0xbfb8aa3b, v203
	v_exp_f32_e32 v208, v208
	v_exp_f32_e32 v209, v209
	v_exp_f32_e32 v210, v210
	v_exp_f32_e32 v211, v211
	v_add_f32_e32 v208, 1.0, v208
	v_add_f32_e32 v209, 1.0, v209
	v_add_f32_e32 v210, 1.0, v210
	v_add_f32_e32 v211, 1.0, v211
	v_rcp_f32_e32 v208, v208
	v_rcp_f32_e32 v209, v209
	v_rcp_f32_e32 v210, v210
	v_rcp_f32_e32 v211, v211
	v_mul_f32_e32 v200, v200, v208
	v_mul_f32_e32 v201, v201, v209
	v_mul_f32_e32 v202, v202, v210
	v_mul_f32_e32 v203, v203, v211
	v_mul_f32_e32 v200, v200, v204
	v_mul_f32_e32 v201, v201, v205
	v_mul_f32_e32 v202, v202, v206
	v_mul_f32_e32 v203, v203, v207
	v_cvt_pk_bf16_f32 v236, v200, v201
	v_cvt_pk_bf16_f32 v237, v202, v203
	v_fma_f32 v200, v132, v116, v140
	v_fma_f32 v201, v133, v117, v141
	v_fma_f32 v202, v134, v118, v142
	v_fma_f32 v203, v135, v119, v143
	v_fmac_f32_e32 v200, v124, v128
	v_fmac_f32_e32 v201, v125, v129
	v_fmac_f32_e32 v202, v126, v130
	v_fmac_f32_e32 v203, v127, v131
	v_fmac_f32_e32 v200, v96, v136
	v_fmac_f32_e32 v201, v97, v137
	v_fmac_f32_e32 v202, v98, v138
	v_fmac_f32_e32 v203, v99, v139
	v_fma_f32 v204, v172, v100, v180
	v_fma_f32 v205, v173, v101, v181
	v_fma_f32 v206, v174, v102, v182
	v_fma_f32 v207, v175, v103, v183
	v_fmac_f32_e32 v204, v108, v160
	v_fmac_f32_e32 v205, v109, v161
	v_fmac_f32_e32 v206, v110, v162
	v_fmac_f32_e32 v207, v111, v163
	v_fmac_f32_e32 v204, v84, v176
	v_fmac_f32_e32 v205, v85, v177
	v_fmac_f32_e32 v206, v86, v178
	v_fmac_f32_e32 v207, v87, v179
	v_mul_f32_e32 v208, 0xbfb8aa3b, v200
	v_mul_f32_e32 v209, 0xbfb8aa3b, v201
	v_mul_f32_e32 v210, 0xbfb8aa3b, v202
	v_mul_f32_e32 v211, 0xbfb8aa3b, v203
	v_exp_f32_e32 v208, v208
	v_exp_f32_e32 v209, v209
	v_exp_f32_e32 v210, v210
	v_exp_f32_e32 v211, v211
	v_add_f32_e32 v208, 1.0, v208
	v_add_f32_e32 v209, 1.0, v209
	v_add_f32_e32 v210, 1.0, v210
	v_add_f32_e32 v211, 1.0, v211
	v_rcp_f32_e32 v208, v208
	v_rcp_f32_e32 v209, v209
	v_rcp_f32_e32 v210, v210
	v_rcp_f32_e32 v211, v211
	v_mul_f32_e32 v200, v200, v208
	v_mul_f32_e32 v201, v201, v209
	v_mul_f32_e32 v202, v202, v210
	v_mul_f32_e32 v203, v203, v211
	v_mul_f32_e32 v200, v200, v204
	v_mul_f32_e32 v201, v201, v205
	v_mul_f32_e32 v202, v202, v206
	v_mul_f32_e32 v203, v203, v207
	v_cvt_pk_bf16_f32 v238, v200, v201
	v_cvt_pk_bf16_f32 v239, v202, v203
	v_fma_f32 v200, v132, v96, v140
	v_fma_f32 v201, v133, v97, v141
	v_fma_f32 v202, v134, v98, v142
	v_fma_f32 v203, v135, v99, v143
	v_fmac_f32_e32 v200, v116, v128
	v_fmac_f32_e32 v201, v117, v129
	v_fmac_f32_e32 v202, v118, v130
	v_fmac_f32_e32 v203, v119, v131
	v_fmac_f32_e32 v200, v80, v136
	v_fmac_f32_e32 v201, v81, v137
	v_fmac_f32_e32 v202, v82, v138
	v_fmac_f32_e32 v203, v83, v139
	v_fma_f32 v204, v172, v84, v180
	v_fma_f32 v205, v173, v85, v181
	v_fma_f32 v206, v174, v86, v182
	v_fma_f32 v207, v175, v87, v183
	v_fmac_f32_e32 v204, v100, v160
	v_fmac_f32_e32 v205, v101, v161
	v_fmac_f32_e32 v206, v102, v162
	v_fmac_f32_e32 v207, v103, v163
	v_fmac_f32_e32 v204, v68, v176
	v_fmac_f32_e32 v205, v69, v177
	v_fmac_f32_e32 v206, v70, v178
	v_fmac_f32_e32 v207, v71, v179
	v_mul_f32_e32 v208, 0xbfb8aa3b, v200
	v_mul_f32_e32 v209, 0xbfb8aa3b, v201
	v_mul_f32_e32 v210, 0xbfb8aa3b, v202
	v_mul_f32_e32 v211, 0xbfb8aa3b, v203
	v_exp_f32_e32 v208, v208
	v_exp_f32_e32 v209, v209
	v_exp_f32_e32 v210, v210
	v_exp_f32_e32 v211, v211
	v_add_f32_e32 v208, 1.0, v208
	v_add_f32_e32 v209, 1.0, v209
	v_add_f32_e32 v210, 1.0, v210
	v_add_f32_e32 v211, 1.0, v211
	v_rcp_f32_e32 v208, v208
	v_rcp_f32_e32 v209, v209
	v_rcp_f32_e32 v210, v210
	v_rcp_f32_e32 v211, v211
	v_mul_f32_e32 v200, v200, v208
	v_mul_f32_e32 v201, v201, v209
	v_mul_f32_e32 v202, v202, v210
	v_mul_f32_e32 v203, v203, v211
	v_mul_f32_e32 v200, v200, v204
	v_mul_f32_e32 v201, v201, v205
	v_mul_f32_e32 v202, v202, v206
	v_mul_f32_e32 v203, v203, v207
	v_cvt_pk_bf16_f32 v240, v200, v201
	v_cvt_pk_bf16_f32 v241, v202, v203
	v_fma_f32 v200, v132, v80, v140
	v_fma_f32 v201, v133, v81, v141
	v_fma_f32 v202, v134, v82, v142
	v_fma_f32 v203, v135, v83, v143
	v_fmac_f32_e32 v200, v96, v128
	v_fmac_f32_e32 v201, v97, v129
	v_fmac_f32_e32 v202, v98, v130
	v_fmac_f32_e32 v203, v99, v131
	v_fmac_f32_dpp v200, v124, v136 row_shl:1 row_mask:0xf bank_mask:0xf
	v_fmac_f32_dpp v201, v125, v137 row_shl:1 row_mask:0xf bank_mask:0xf
	v_fmac_f32_dpp v202, v126, v138 row_shl:1 row_mask:0xf bank_mask:0xf
	v_fmac_f32_dpp v203, v127, v139 row_shl:1 row_mask:0xf bank_mask:0xf
	v_fmac_f32_e32 v200, v184, v220
	v_fmac_f32_e32 v201, v185, v221
	v_fmac_f32_e32 v202, v186, v222
	v_fmac_f32_e32 v203, v187, v223
	v_fma_f32 v204, v172, v68, v180
	v_fma_f32 v205, v173, v69, v181
	v_fma_f32 v206, v174, v70, v182
	v_fma_f32 v207, v175, v71, v183
	v_fmac_f32_e32 v204, v84, v160
	v_fmac_f32_e32 v205, v85, v161
	v_fmac_f32_e32 v206, v86, v162
	v_fmac_f32_e32 v207, v87, v163
	v_fmac_f32_dpp v204, v108, v176 row_shl:1 row_mask:0xf bank_mask:0xf
	v_fmac_f32_dpp v205, v109, v177 row_shl:1 row_mask:0xf bank_mask:0xf
	v_fmac_f32_dpp v206, v110, v178 row_shl:1 row_mask:0xf bank_mask:0xf
	v_fmac_f32_dpp v207, v111, v179 row_shl:1 row_mask:0xf bank_mask:0xf
	v_fmac_f32_e32 v204, v188, v232
	v_fmac_f32_e32 v205, v189, v233
	v_fmac_f32_e32 v206, v190, v234
	v_fmac_f32_e32 v207, v191, v235
	v_mul_f32_e32 v208, 0xbfb8aa3b, v200
	v_mul_f32_e32 v209, 0xbfb8aa3b, v201
	v_mul_f32_e32 v210, 0xbfb8aa3b, v202
	v_mul_f32_e32 v211, 0xbfb8aa3b, v203
	v_exp_f32_e32 v208, v208
	v_exp_f32_e32 v209, v209
	v_exp_f32_e32 v210, v210
	v_exp_f32_e32 v211, v211
	v_add_f32_e32 v208, 1.0, v208
	v_add_f32_e32 v209, 1.0, v209
	v_add_f32_e32 v210, 1.0, v210
	v_add_f32_e32 v211, 1.0, v211
	v_rcp_f32_e32 v208, v208
	v_rcp_f32_e32 v209, v209
	v_rcp_f32_e32 v210, v210
	v_rcp_f32_e32 v211, v211
	v_mul_f32_e32 v200, v200, v208
	v_mul_f32_e32 v201, v201, v209
	v_mul_f32_e32 v202, v202, v210
	v_mul_f32_e32 v203, v203, v211
	v_mul_f32_e32 v200, v200, v204
	v_mul_f32_e32 v201, v201, v205
	v_mul_f32_e32 v202, v202, v206
	v_mul_f32_e32 v203, v203, v207
	v_cvt_pk_bf16_f32 v242, v200, v201
	v_cvt_pk_bf16_f32 v243, v202, v203
	v_fma_f32 v200, v132, v60, v140
	v_fma_f32 v201, v133, v61, v141
	v_fma_f32 v202, v134, v62, v142
	v_fma_f32 v203, v135, v63, v143
	v_fmac_f32_dpp v200, v16, v128 row_shr:1 row_mask:0xf bank_mask:0xf
	v_fmac_f32_dpp v201, v17, v129 row_shr:1 row_mask:0xf bank_mask:0xf
	v_fmac_f32_dpp v202, v18, v130 row_shr:1 row_mask:0xf bank_mask:0xf
	v_fmac_f32_dpp v203, v19, v131 row_shr:1 row_mask:0xf bank_mask:0xf
	v_fmac_f32_e32 v200, v192, v216
	v_fmac_f32_e32 v201, v193, v217
	v_fmac_f32_e32 v202, v194, v218
	v_fmac_f32_e32 v203, v195, v219
	v_fmac_f32_e32 v200, v48, v136
	v_fmac_f32_e32 v201, v49, v137
	v_fmac_f32_e32 v202, v50, v138
	v_fmac_f32_e32 v203, v51, v139
	v_fma_f32 v204, v172, v52, v180
	v_fma_f32 v205, v173, v53, v181
	v_fma_f32 v206, v174, v54, v182
	v_fma_f32 v207, v175, v55, v183
	v_fmac_f32_dpp v204, v4, v160 row_shr:1 row_mask:0xf bank_mask:0xf
	v_fmac_f32_dpp v205, v5, v161 row_shr:1 row_mask:0xf bank_mask:0xf
	v_fmac_f32_dpp v206, v6, v162 row_shr:1 row_mask:0xf bank_mask:0xf
	v_fmac_f32_dpp v207, v7, v163 row_shr:1 row_mask:0xf bank_mask:0xf
	v_fmac_f32_e32 v204, v196, v224
	v_fmac_f32_e32 v205, v197, v225
	v_fmac_f32_e32 v206, v198, v226
	v_fmac_f32_e32 v207, v199, v227
	v_fmac_f32_e32 v204, v36, v176
	v_fmac_f32_e32 v205, v37, v177
	v_fmac_f32_e32 v206, v38, v178
	v_fmac_f32_e32 v207, v39, v179
	v_mul_f32_e32 v208, 0xbfb8aa3b, v200
	v_mul_f32_e32 v209, 0xbfb8aa3b, v201
	v_mul_f32_e32 v210, 0xbfb8aa3b, v202
	v_mul_f32_e32 v211, 0xbfb8aa3b, v203
	v_exp_f32_e32 v208, v208
	v_exp_f32_e32 v209, v209
	v_exp_f32_e32 v210, v210
	v_exp_f32_e32 v211, v211
	v_add_f32_e32 v208, 1.0, v208
	v_add_f32_e32 v209, 1.0, v209
	v_add_f32_e32 v210, 1.0, v210
	v_add_f32_e32 v211, 1.0, v211
	v_rcp_f32_e32 v208, v208
	v_rcp_f32_e32 v209, v209
	v_rcp_f32_e32 v210, v210
	v_rcp_f32_e32 v211, v211
	v_mul_f32_e32 v200, v200, v208
	v_mul_f32_e32 v201, v201, v209
	v_mul_f32_e32 v202, v202, v210
	v_mul_f32_e32 v203, v203, v211
	v_mul_f32_e32 v200, v200, v204
	v_mul_f32_e32 v201, v201, v205
	v_mul_f32_e32 v202, v202, v206
	v_mul_f32_e32 v203, v203, v207
	v_cvt_pk_bf16_f32 v244, v200, v201
	v_cvt_pk_bf16_f32 v245, v202, v203
	v_fma_f32 v200, v132, v48, v140
	v_fma_f32 v201, v133, v49, v141
	v_fma_f32 v202, v134, v50, v142
	v_fma_f32 v203, v135, v51, v143
	v_fmac_f32_e32 v200, v60, v128
	v_fmac_f32_e32 v201, v61, v129
	v_fmac_f32_e32 v202, v62, v130
	v_fmac_f32_e32 v203, v63, v131
	v_fmac_f32_e32 v200, v32, v136
	v_fmac_f32_e32 v201, v33, v137
	v_fmac_f32_e32 v202, v34, v138
	v_fmac_f32_e32 v203, v35, v139
	v_fma_f32 v204, v172, v36, v180
	v_fma_f32 v205, v173, v37, v181
	v_fma_f32 v206, v174, v38, v182
	v_fma_f32 v207, v175, v39, v183
	v_fmac_f32_e32 v204, v52, v160
	v_fmac_f32_e32 v205, v53, v161
	v_fmac_f32_e32 v206, v54, v162
	v_fmac_f32_e32 v207, v55, v163
	v_fmac_f32_e32 v204, v20, v176
	v_fmac_f32_e32 v205, v21, v177
	v_fmac_f32_e32 v206, v22, v178
	v_fmac_f32_e32 v207, v23, v179
	v_mul_f32_e32 v208, 0xbfb8aa3b, v200
	v_mul_f32_e32 v209, 0xbfb8aa3b, v201
	v_mul_f32_e32 v210, 0xbfb8aa3b, v202
	v_mul_f32_e32 v211, 0xbfb8aa3b, v203
	v_exp_f32_e32 v208, v208
	v_exp_f32_e32 v209, v209
	v_exp_f32_e32 v210, v210
	v_exp_f32_e32 v211, v211
	v_add_f32_e32 v208, 1.0, v208
	v_add_f32_e32 v209, 1.0, v209
	v_add_f32_e32 v210, 1.0, v210
	v_add_f32_e32 v211, 1.0, v211
	v_rcp_f32_e32 v208, v208
	v_rcp_f32_e32 v209, v209
	v_rcp_f32_e32 v210, v210
	v_rcp_f32_e32 v211, v211
	v_mul_f32_e32 v200, v200, v208
	v_mul_f32_e32 v201, v201, v209
	v_mul_f32_e32 v202, v202, v210
	v_mul_f32_e32 v203, v203, v211
	v_mul_f32_e32 v200, v200, v204
	v_mul_f32_e32 v201, v201, v205
	v_mul_f32_e32 v202, v202, v206
	v_mul_f32_e32 v203, v203, v207
	v_cvt_pk_bf16_f32 v246, v200, v201
	v_cvt_pk_bf16_f32 v247, v202, v203
	v_fma_f32 v200, v132, v32, v140
	v_fma_f32 v201, v133, v33, v141
	v_fma_f32 v202, v134, v34, v142
	v_fma_f32 v203, v135, v35, v143
	v_fmac_f32_e32 v200, v48, v128
	v_fmac_f32_e32 v201, v49, v129
	v_fmac_f32_e32 v202, v50, v130
	v_fmac_f32_e32 v203, v51, v131
	v_fmac_f32_e32 v200, v16, v136
	v_fmac_f32_e32 v201, v17, v137
	v_fmac_f32_e32 v202, v18, v138
	v_fmac_f32_e32 v203, v19, v139
	v_fma_f32 v204, v172, v20, v180
	v_fma_f32 v205, v173, v21, v181
	v_fma_f32 v206, v174, v22, v182
	v_fma_f32 v207, v175, v23, v183
	v_fmac_f32_e32 v204, v36, v160
	v_fmac_f32_e32 v205, v37, v161
	v_fmac_f32_e32 v206, v38, v162
	v_fmac_f32_e32 v207, v39, v163
	v_fmac_f32_e32 v204, v4, v176
	v_fmac_f32_e32 v205, v5, v177
	v_fmac_f32_e32 v206, v6, v178
	v_fmac_f32_e32 v207, v7, v179
	v_mul_f32_e32 v208, 0xbfb8aa3b, v200
	v_mul_f32_e32 v209, 0xbfb8aa3b, v201
	v_mul_f32_e32 v210, 0xbfb8aa3b, v202
	v_mul_f32_e32 v211, 0xbfb8aa3b, v203
	v_exp_f32_e32 v208, v208
	v_exp_f32_e32 v209, v209
	v_exp_f32_e32 v210, v210
	v_exp_f32_e32 v211, v211
	v_add_f32_e32 v208, 1.0, v208
	v_add_f32_e32 v209, 1.0, v209
	v_add_f32_e32 v210, 1.0, v210
	v_add_f32_e32 v211, 1.0, v211
	v_rcp_f32_e32 v208, v208
	v_rcp_f32_e32 v209, v209
	v_rcp_f32_e32 v210, v210
	v_rcp_f32_e32 v211, v211
	v_mul_f32_e32 v200, v200, v208
	v_mul_f32_e32 v201, v201, v209
	v_mul_f32_e32 v202, v202, v210
	v_mul_f32_e32 v203, v203, v211
	v_mul_f32_e32 v200, v200, v204
	v_mul_f32_e32 v201, v201, v205
	v_mul_f32_e32 v202, v202, v206
	v_mul_f32_e32 v203, v203, v207
	v_cvt_pk_bf16_f32 v248, v200, v201
	v_cvt_pk_bf16_f32 v249, v202, v203
	v_fma_f32 v200, v132, v16, v140
	v_fma_f32 v201, v133, v17, v141
	v_fma_f32 v202, v134, v18, v142
	v_fma_f32 v203, v135, v19, v143
	v_fmac_f32_e32 v200, v32, v128
	v_fmac_f32_e32 v201, v33, v129
	v_fmac_f32_e32 v202, v34, v130
	v_fmac_f32_e32 v203, v35, v131
	v_fmac_f32_dpp v200, v60, v136 row_shl:1 row_mask:0xf bank_mask:0xf
	v_fmac_f32_dpp v201, v61, v137 row_shl:1 row_mask:0xf bank_mask:0xf
	v_fmac_f32_dpp v202, v62, v138 row_shl:1 row_mask:0xf bank_mask:0xf
	v_fmac_f32_dpp v203, v63, v139 row_shl:1 row_mask:0xf bank_mask:0xf
	v_fmac_f32_e32 v200, v192, v220
	v_fmac_f32_e32 v201, v193, v221
	v_fmac_f32_e32 v202, v194, v222
	v_fmac_f32_e32 v203, v195, v223
	v_fma_f32 v204, v172, v4, v180
	v_fma_f32 v205, v173, v5, v181
	v_fma_f32 v206, v174, v6, v182
	v_fma_f32 v207, v175, v7, v183
	v_fmac_f32_e32 v204, v20, v160
	v_fmac_f32_e32 v205, v21, v161
	v_fmac_f32_e32 v206, v22, v162
	v_fmac_f32_e32 v207, v23, v163
	v_fmac_f32_dpp v204, v52, v176 row_shl:1 row_mask:0xf bank_mask:0xf
	v_fmac_f32_dpp v205, v53, v177 row_shl:1 row_mask:0xf bank_mask:0xf
	v_fmac_f32_dpp v206, v54, v178 row_shl:1 row_mask:0xf bank_mask:0xf
	v_fmac_f32_dpp v207, v55, v179 row_shl:1 row_mask:0xf bank_mask:0xf
	v_fmac_f32_e32 v204, v196, v232
	v_fmac_f32_e32 v205, v197, v233
	v_fmac_f32_e32 v206, v198, v234
	v_fmac_f32_e32 v207, v199, v235
	s_mov_b64 exec, s[54:55]
	v_add_u32_e32 v250, 0x10800, v252
	global_store_dwordx4 v250, v[200:203], s[56:57]
	v_add_u32_e32 v250, 0x13400, v252
	global_store_dwordx4 v250, v[204:207], s[56:57]
	s_mov_b64 exec, -1
	s_nop 4
	v_mul_f32_e32 v208, 0xbfb8aa3b, v200
	v_mul_f32_e32 v209, 0xbfb8aa3b, v201
	v_mul_f32_e32 v210, 0xbfb8aa3b, v202
	v_mul_f32_e32 v211, 0xbfb8aa3b, v203
	v_exp_f32_e32 v208, v208
	v_exp_f32_e32 v209, v209
	v_exp_f32_e32 v210, v210
	v_exp_f32_e32 v211, v211
	v_add_f32_e32 v208, 1.0, v208
	v_add_f32_e32 v209, 1.0, v209
	v_add_f32_e32 v210, 1.0, v210
	v_add_f32_e32 v211, 1.0, v211
	v_rcp_f32_e32 v208, v208
	v_rcp_f32_e32 v209, v209
	v_rcp_f32_e32 v210, v210
	v_rcp_f32_e32 v211, v211
	v_mul_f32_e32 v200, v200, v208
	v_mul_f32_e32 v201, v201, v209
	v_mul_f32_e32 v202, v202, v210
	v_mul_f32_e32 v203, v203, v211
	v_mul_f32_e32 v200, v200, v204
	v_mul_f32_e32 v201, v201, v205
	v_mul_f32_e32 v202, v202, v206
	v_mul_f32_e32 v203, v203, v207
	v_cvt_pk_bf16_f32 v250, v200, v201
	v_cvt_pk_bf16_f32 v251, v202, v203
	ds_read_b128 v[128:131], v229 offset:2064
	ds_read_b128 v[132:135], v229 offset:2576
	ds_read_b128 v[136:139], v229 offset:4112
	ds_read_b128 v[140:143], v229 offset:5136
	ds_read_b128 v[160:163], v229 offset:3088
	ds_read_b128 v[172:175], v229 offset:3600
	ds_read_b128 v[176:179], v229 offset:4624
	ds_read_b128 v[180:183], v229 offset:5648
	v_mov_b32_e32 v124, v236
	v_mov_b32_e32 v125, v237
	v_mov_b32_e32 v116, v238
	v_mov_b32_e32 v117, v239
	v_mov_b32_e32 v96, v240
	v_mov_b32_e32 v97, v241
	v_mov_b32_e32 v80, v242
	v_mov_b32_e32 v81, v243
	v_mov_b32_e32 v60, v244
	v_mov_b32_e32 v61, v245
	v_mov_b32_e32 v48, v246
	v_mov_b32_e32 v49, v247
	v_mov_b32_e32 v32, v248
	v_mov_b32_e32 v33, v249
	v_mov_b32_e32 v16, v250
	v_mov_b32_e32 v17, v251
	ds_read_b128 v[184:187], v231 offset:16
	ds_read_b128 v[188:191], v231 offset:528
	ds_read_b128 v[192:195], v231 offset:2064
	ds_read_b128 v[196:199], v231 offset:2576
	s_waitcnt lgkmcnt(4)
	v_cndmask_b32_e64 v216, 0, v128, s[34:35]
	v_cndmask_b32_e64 v220, 0, v136, s[36:37]
	v_cndmask_b32_e64 v217, 0, v129, s[34:35]
	v_cndmask_b32_e64 v221, 0, v137, s[36:37]
	v_cndmask_b32_e64 v218, 0, v130, s[34:35]
	v_cndmask_b32_e64 v222, 0, v138, s[36:37]
	v_cndmask_b32_e64 v219, 0, v131, s[34:35]
	v_cndmask_b32_e64 v223, 0, v139, s[36:37]
	v_cndmask_b32_e64 v224, 0, v160, s[34:35]
	v_cndmask_b32_e64 v232, 0, v176, s[36:37]
	v_cndmask_b32_e64 v225, 0, v161, s[34:35]
	v_cndmask_b32_e64 v233, 0, v177, s[36:37]
	v_cndmask_b32_e64 v226, 0, v162, s[34:35]
	v_cndmask_b32_e64 v234, 0, v178, s[36:37]
	v_cndmask_b32_e64 v227, 0, v163, s[34:35]
	v_cndmask_b32_e64 v235, 0, v179, s[36:37]
	s_waitcnt lgkmcnt(0)
	s_nop 1
	v_fma_f32 v200, v132, v120, v140
	v_fma_f32 v201, v133, v121, v141
	v_fma_f32 v202, v134, v122, v142
	v_fma_f32 v203, v135, v123, v143
	v_fmac_f32_dpp v200, v72, v128 row_shr:1 row_mask:0xf bank_mask:0xf
	v_fmac_f32_dpp v201, v73, v129 row_shr:1 row_mask:0xf bank_mask:0xf
	v_fmac_f32_dpp v202, v74, v130 row_shr:1 row_mask:0xf bank_mask:0xf
	v_fmac_f32_dpp v203, v75, v131 row_shr:1 row_mask:0xf bank_mask:0xf
	v_fmac_f32_e32 v200, v184, v216
	v_fmac_f32_e32 v201, v185, v217
	v_fmac_f32_e32 v202, v186, v218
	v_fmac_f32_e32 v203, v187, v219
	v_fmac_f32_e32 v200, v112, v136
	v_fmac_f32_e32 v201, v113, v137
	v_fmac_f32_e32 v202, v114, v138
	v_fmac_f32_e32 v203, v115, v139
	v_fma_f32 v204, v172, v104, v180
	v_fma_f32 v205, v173, v105, v181
	v_fma_f32 v206, v174, v106, v182
	v_fma_f32 v207, v175, v107, v183
	v_fmac_f32_dpp v204, v64, v160 row_shr:1 row_mask:0xf bank_mask:0xf
	v_fmac_f32_dpp v205, v65, v161 row_shr:1 row_mask:0xf bank_mask:0xf
	v_fmac_f32_dpp v206, v66, v162 row_shr:1 row_mask:0xf bank_mask:0xf
	v_fmac_f32_dpp v207, v67, v163 row_shr:1 row_mask:0xf bank_mask:0xf
	v_fmac_f32_e32 v204, v188, v224
	v_fmac_f32_e32 v205, v189, v225
	v_fmac_f32_e32 v206, v190, v226
	v_fmac_f32_e32 v207, v191, v227
	v_fmac_f32_e32 v204, v92, v176
	v_fmac_f32_e32 v205, v93, v177
	v_fmac_f32_e32 v206, v94, v178
	v_fmac_f32_e32 v207, v95, v179
	s_mov_b64 exec, s[52:53]
	v_add_u32_e32 v250, 0x5800, v252
	global_store_dwordx4 v250, v[200:203], s[56:57] offset:16
	v_add_u32_e32 v250, 0x8400, v252
	global_store_dwordx4 v250, v[204:207], s[56:57] offset:16
	s_mov_b64 exec, -1
	s_nop 4
	v_mul_f32_e32 v208, 0xbfb8aa3b, v200
	v_mul_f32_e32 v209, 0xbfb8aa3b, v201
	v_mul_f32_e32 v210, 0xbfb8aa3b, v202
	v_mul_f32_e32 v211, 0xbfb8aa3b, v203
	v_exp_f32_e32 v208, v208
	v_exp_f32_e32 v209, v209
	v_exp_f32_e32 v210, v210
	v_exp_f32_e32 v211, v211
	v_add_f32_e32 v208, 1.0, v208
	v_add_f32_e32 v209, 1.0, v209
	v_add_f32_e32 v210, 1.0, v210
	v_add_f32_e32 v211, 1.0, v211
	v_rcp_f32_e32 v208, v208
	v_rcp_f32_e32 v209, v209
	v_rcp_f32_e32 v210, v210
	v_rcp_f32_e32 v211, v211
	v_mul_f32_e32 v200, v200, v208
	v_mul_f32_e32 v201, v201, v209
	v_mul_f32_e32 v202, v202, v210
	v_mul_f32_e32 v203, v203, v211
	v_mul_f32_e32 v200, v200, v204
	v_mul_f32_e32 v201, v201, v205
	v_mul_f32_e32 v202, v202, v206
	v_mul_f32_e32 v203, v203, v207
	v_cvt_pk_bf16_f32 v126, v200, v201
	v_cvt_pk_bf16_f32 v127, v202, v203
	v_fma_f32 v200, v132, v112, v140
	v_fma_f32 v201, v133, v113, v141
	v_fma_f32 v202, v134, v114, v142
	v_fma_f32 v203, v135, v115, v143
	v_fmac_f32_e32 v200, v120, v128
	v_fmac_f32_e32 v201, v121, v129
	v_fmac_f32_e32 v202, v122, v130
	v_fmac_f32_e32 v203, v123, v131
	v_fmac_f32_e32 v200, v88, v136
	v_fmac_f32_e32 v201, v89, v137
	v_fmac_f32_e32 v202, v90, v138
	v_fmac_f32_e32 v203, v91, v139
	v_fma_f32 v204, v172, v92, v180
	v_fma_f32 v205, v173, v93, v181
	v_fma_f32 v206, v174, v94, v182
	v_fma_f32 v207, v175, v95, v183
	v_fmac_f32_e32 v204, v104, v160
	v_fmac_f32_e32 v205, v105, v161
	v_fmac_f32_e32 v206, v106, v162
	v_fmac_f32_e32 v207, v107, v163
	v_fmac_f32_e32 v204, v76, v176
	v_fmac_f32_e32 v205, v77, v177
	v_fmac_f32_e32 v206, v78, v178
	v_fmac_f32_e32 v207, v79, v179
	v_mul_f32_e32 v208, 0xbfb8aa3b, v200
	v_mul_f32_e32 v209, 0xbfb8aa3b, v201
	v_mul_f32_e32 v210, 0xbfb8aa3b, v202
	v_mul_f32_e32 v211, 0xbfb8aa3b, v203
	v_exp_f32_e32 v208, v208
	v_exp_f32_e32 v209, v209
	v_exp_f32_e32 v210, v210
	v_exp_f32_e32 v211, v211
	v_add_f32_e32 v208, 1.0, v208
	v_add_f32_e32 v209, 1.0, v209
	v_add_f32_e32 v210, 1.0, v210
	v_add_f32_e32 v211, 1.0, v211
	v_rcp_f32_e32 v208, v208
	v_rcp_f32_e32 v209, v209
	v_rcp_f32_e32 v210, v210
	v_rcp_f32_e32 v211, v211
	v_mul_f32_e32 v200, v200, v208
	v_mul_f32_e32 v201, v201, v209
	v_mul_f32_e32 v202, v202, v210
	v_mul_f32_e32 v203, v203, v211
	v_mul_f32_e32 v200, v200, v204
	v_mul_f32_e32 v201, v201, v205
	v_mul_f32_e32 v202, v202, v206
	v_mul_f32_e32 v203, v203, v207
	v_cvt_pk_bf16_f32 v118, v200, v201
	v_cvt_pk_bf16_f32 v119, v202, v203
	v_fma_f32 v200, v132, v88, v140
	v_fma_f32 v201, v133, v89, v141
	v_fma_f32 v202, v134, v90, v142
	v_fma_f32 v203, v135, v91, v143
	v_fmac_f32_e32 v200, v112, v128
	v_fmac_f32_e32 v201, v113, v129
	v_fmac_f32_e32 v202, v114, v130
	v_fmac_f32_e32 v203, v115, v131
	v_fmac_f32_e32 v200, v72, v136
	v_fmac_f32_e32 v201, v73, v137
	v_fmac_f32_e32 v202, v74, v138
	v_fmac_f32_e32 v203, v75, v139
	v_fma_f32 v204, v172, v76, v180
	v_fma_f32 v205, v173, v77, v181
	v_fma_f32 v206, v174, v78, v182
	v_fma_f32 v207, v175, v79, v183
	v_fmac_f32_e32 v204, v92, v160
	v_fmac_f32_e32 v205, v93, v161
	v_fmac_f32_e32 v206, v94, v162
	v_fmac_f32_e32 v207, v95, v163
	v_fmac_f32_e32 v204, v64, v176
	v_fmac_f32_e32 v205, v65, v177
	v_fmac_f32_e32 v206, v66, v178
	v_fmac_f32_e32 v207, v67, v179
	v_mul_f32_e32 v208, 0xbfb8aa3b, v200
	v_mul_f32_e32 v209, 0xbfb8aa3b, v201
	v_mul_f32_e32 v210, 0xbfb8aa3b, v202
	v_mul_f32_e32 v211, 0xbfb8aa3b, v203
	v_exp_f32_e32 v208, v208
	v_exp_f32_e32 v209, v209
	v_exp_f32_e32 v210, v210
	v_exp_f32_e32 v211, v211
	v_add_f32_e32 v208, 1.0, v208
	v_add_f32_e32 v209, 1.0, v209
	v_add_f32_e32 v210, 1.0, v210
	v_add_f32_e32 v211, 1.0, v211
	v_rcp_f32_e32 v208, v208
	v_rcp_f32_e32 v209, v209
	v_rcp_f32_e32 v210, v210
	v_rcp_f32_e32 v211, v211
	v_mul_f32_e32 v200, v200, v208
	v_mul_f32_e32 v201, v201, v209
	v_mul_f32_e32 v202, v202, v210
	v_mul_f32_e32 v203, v203, v211
	v_mul_f32_e32 v200, v200, v204
	v_mul_f32_e32 v201, v201, v205
	v_mul_f32_e32 v202, v202, v206
	v_mul_f32_e32 v203, v203, v207
	v_cvt_pk_bf16_f32 v98, v200, v201
	v_cvt_pk_bf16_f32 v99, v202, v203
	v_fma_f32 v200, v132, v72, v140
	v_fma_f32 v201, v133, v73, v141
	v_fma_f32 v202, v134, v74, v142
	v_fma_f32 v203, v135, v75, v143
	v_fmac_f32_e32 v200, v88, v128
	v_fmac_f32_e32 v201, v89, v129
	v_fmac_f32_e32 v202, v90, v130
	v_fmac_f32_e32 v203, v91, v131
	v_fmac_f32_dpp v200, v120, v136 row_shl:1 row_mask:0xf bank_mask:0xf
	v_fmac_f32_dpp v201, v121, v137 row_shl:1 row_mask:0xf bank_mask:0xf
	v_fmac_f32_dpp v202, v122, v138 row_shl:1 row_mask:0xf bank_mask:0xf
	v_fmac_f32_dpp v203, v123, v139 row_shl:1 row_mask:0xf bank_mask:0xf
	v_fmac_f32_e32 v200, v184, v220
	v_fmac_f32_e32 v201, v185, v221
	v_fmac_f32_e32 v202, v186, v222
	v_fmac_f32_e32 v203, v187, v223
	v_fma_f32 v204, v172, v64, v180
	v_fma_f32 v205, v173, v65, v181
	v_fma_f32 v206, v174, v66, v182
	v_fma_f32 v207, v175, v67, v183
	v_fmac_f32_e32 v204, v76, v160
	v_fmac_f32_e32 v205, v77, v161
	v_fmac_f32_e32 v206, v78, v162
	v_fmac_f32_e32 v207, v79, v163
	v_fmac_f32_dpp v204, v104, v176 row_shl:1 row_mask:0xf bank_mask:0xf
	v_fmac_f32_dpp v205, v105, v177 row_shl:1 row_mask:0xf bank_mask:0xf
	v_fmac_f32_dpp v206, v106, v178 row_shl:1 row_mask:0xf bank_mask:0xf
	v_fmac_f32_dpp v207, v107, v179 row_shl:1 row_mask:0xf bank_mask:0xf
	v_fmac_f32_e32 v204, v188, v232
	v_fmac_f32_e32 v205, v189, v233
	v_fmac_f32_e32 v206, v190, v234
	v_fmac_f32_e32 v207, v191, v235
	v_mul_f32_e32 v208, 0xbfb8aa3b, v200
	v_mul_f32_e32 v209, 0xbfb8aa3b, v201
	v_mul_f32_e32 v210, 0xbfb8aa3b, v202
	v_mul_f32_e32 v211, 0xbfb8aa3b, v203
	v_exp_f32_e32 v208, v208
	v_exp_f32_e32 v209, v209
	v_exp_f32_e32 v210, v210
	v_exp_f32_e32 v211, v211
	v_add_f32_e32 v208, 1.0, v208
	v_add_f32_e32 v209, 1.0, v209
	v_add_f32_e32 v210, 1.0, v210
	v_add_f32_e32 v211, 1.0, v211
	v_rcp_f32_e32 v208, v208
	v_rcp_f32_e32 v209, v209
	v_rcp_f32_e32 v210, v210
	v_rcp_f32_e32 v211, v211
	v_mul_f32_e32 v200, v200, v208
	v_mul_f32_e32 v201, v201, v209
	v_mul_f32_e32 v202, v202, v210
	v_mul_f32_e32 v203, v203, v211
	v_mul_f32_e32 v200, v200, v204
	v_mul_f32_e32 v201, v201, v205
	v_mul_f32_e32 v202, v202, v206
	v_mul_f32_e32 v203, v203, v207
	v_cvt_pk_bf16_f32 v82, v200, v201
	v_cvt_pk_bf16_f32 v83, v202, v203
	v_fma_f32 v200, v132, v56, v140
	v_fma_f32 v201, v133, v57, v141
	v_fma_f32 v202, v134, v58, v142
	v_fma_f32 v203, v135, v59, v143
	v_fmac_f32_dpp v200, v8, v128 row_shr:1 row_mask:0xf bank_mask:0xf
	v_fmac_f32_dpp v201, v9, v129 row_shr:1 row_mask:0xf bank_mask:0xf
	v_fmac_f32_dpp v202, v10, v130 row_shr:1 row_mask:0xf bank_mask:0xf
	v_fmac_f32_dpp v203, v11, v131 row_shr:1 row_mask:0xf bank_mask:0xf
	v_fmac_f32_e32 v200, v192, v216
	v_fmac_f32_e32 v201, v193, v217
	v_fmac_f32_e32 v202, v194, v218
	v_fmac_f32_e32 v203, v195, v219
	v_fmac_f32_e32 v200, v40, v136
	v_fmac_f32_e32 v201, v41, v137
	v_fmac_f32_e32 v202, v42, v138
	v_fmac_f32_e32 v203, v43, v139
	v_fma_f32 v204, v172, v44, v180
	v_fma_f32 v205, v173, v45, v181
	v_fma_f32 v206, v174, v46, v182
	v_fma_f32 v207, v175, v47, v183
	v_fmac_f32_dpp v204, v0, v160 row_shr:1 row_mask:0xf bank_mask:0xf
	v_fmac_f32_dpp v205, v1, v161 row_shr:1 row_mask:0xf bank_mask:0xf
	v_fmac_f32_dpp v206, v2, v162 row_shr:1 row_mask:0xf bank_mask:0xf
	v_fmac_f32_dpp v207, v3, v163 row_shr:1 row_mask:0xf bank_mask:0xf
	v_fmac_f32_e32 v204, v196, v224
	v_fmac_f32_e32 v205, v197, v225
	v_fmac_f32_e32 v206, v198, v226
	v_fmac_f32_e32 v207, v199, v227
	v_fmac_f32_e32 v204, v28, v176
	v_fmac_f32_e32 v205, v29, v177
	v_fmac_f32_e32 v206, v30, v178
	v_fmac_f32_e32 v207, v31, v179
	v_mul_f32_e32 v208, 0xbfb8aa3b, v200
	v_mul_f32_e32 v209, 0xbfb8aa3b, v201
	v_mul_f32_e32 v210, 0xbfb8aa3b, v202
	v_mul_f32_e32 v211, 0xbfb8aa3b, v203
	v_exp_f32_e32 v208, v208
	v_exp_f32_e32 v209, v209
	v_exp_f32_e32 v210, v210
	v_exp_f32_e32 v211, v211
	v_add_f32_e32 v208, 1.0, v208
	v_add_f32_e32 v209, 1.0, v209
	v_add_f32_e32 v210, 1.0, v210
	v_add_f32_e32 v211, 1.0, v211
	v_rcp_f32_e32 v208, v208
	v_rcp_f32_e32 v209, v209
	v_rcp_f32_e32 v210, v210
	v_rcp_f32_e32 v211, v211
	v_mul_f32_e32 v200, v200, v208
	v_mul_f32_e32 v201, v201, v209
	v_mul_f32_e32 v202, v202, v210
	v_mul_f32_e32 v203, v203, v211
	v_mul_f32_e32 v200, v200, v204
	v_mul_f32_e32 v201, v201, v205
	v_mul_f32_e32 v202, v202, v206
	v_mul_f32_e32 v203, v203, v207
	v_cvt_pk_bf16_f32 v62, v200, v201
	v_cvt_pk_bf16_f32 v63, v202, v203
	v_fma_f32 v200, v132, v40, v140
	v_fma_f32 v201, v133, v41, v141
	v_fma_f32 v202, v134, v42, v142
	v_fma_f32 v203, v135, v43, v143
	v_fmac_f32_e32 v200, v56, v128
	v_fmac_f32_e32 v201, v57, v129
	v_fmac_f32_e32 v202, v58, v130
	v_fmac_f32_e32 v203, v59, v131
	v_fmac_f32_e32 v200, v24, v136
	v_fmac_f32_e32 v201, v25, v137
	v_fmac_f32_e32 v202, v26, v138
	v_fmac_f32_e32 v203, v27, v139
	v_fma_f32 v204, v172, v28, v180
	v_fma_f32 v205, v173, v29, v181
	v_fma_f32 v206, v174, v30, v182
	v_fma_f32 v207, v175, v31, v183
	v_fmac_f32_e32 v204, v44, v160
	v_fmac_f32_e32 v205, v45, v161
	v_fmac_f32_e32 v206, v46, v162
	v_fmac_f32_e32 v207, v47, v163
	v_fmac_f32_e32 v204, v12, v176
	v_fmac_f32_e32 v205, v13, v177
	v_fmac_f32_e32 v206, v14, v178
	v_fmac_f32_e32 v207, v15, v179
	v_mul_f32_e32 v208, 0xbfb8aa3b, v200
	v_mul_f32_e32 v209, 0xbfb8aa3b, v201
	v_mul_f32_e32 v210, 0xbfb8aa3b, v202
	v_mul_f32_e32 v211, 0xbfb8aa3b, v203
	v_exp_f32_e32 v208, v208
	v_exp_f32_e32 v209, v209
	v_exp_f32_e32 v210, v210
	v_exp_f32_e32 v211, v211
	v_add_f32_e32 v208, 1.0, v208
	v_add_f32_e32 v209, 1.0, v209
	v_add_f32_e32 v210, 1.0, v210
	v_add_f32_e32 v211, 1.0, v211
	v_rcp_f32_e32 v208, v208
	v_rcp_f32_e32 v209, v209
	v_rcp_f32_e32 v210, v210
	v_rcp_f32_e32 v211, v211
	v_mul_f32_e32 v200, v200, v208
	v_mul_f32_e32 v201, v201, v209
	v_mul_f32_e32 v202, v202, v210
	v_mul_f32_e32 v203, v203, v211
	v_mul_f32_e32 v200, v200, v204
	v_mul_f32_e32 v201, v201, v205
	v_mul_f32_e32 v202, v202, v206
	v_mul_f32_e32 v203, v203, v207
	v_cvt_pk_bf16_f32 v50, v200, v201
	v_cvt_pk_bf16_f32 v51, v202, v203
	v_fma_f32 v200, v132, v24, v140
	v_fma_f32 v201, v133, v25, v141
	v_fma_f32 v202, v134, v26, v142
	v_fma_f32 v203, v135, v27, v143
	v_fmac_f32_e32 v200, v40, v128
	v_fmac_f32_e32 v201, v41, v129
	v_fmac_f32_e32 v202, v42, v130
	v_fmac_f32_e32 v203, v43, v131
	v_fmac_f32_e32 v200, v8, v136
	v_fmac_f32_e32 v201, v9, v137
	v_fmac_f32_e32 v202, v10, v138
	v_fmac_f32_e32 v203, v11, v139
	v_fma_f32 v204, v172, v12, v180
	v_fma_f32 v205, v173, v13, v181
	v_fma_f32 v206, v174, v14, v182
	v_fma_f32 v207, v175, v15, v183
	v_fmac_f32_e32 v204, v28, v160
	v_fmac_f32_e32 v205, v29, v161
	v_fmac_f32_e32 v206, v30, v162
	v_fmac_f32_e32 v207, v31, v163
	v_fmac_f32_e32 v204, v0, v176
	v_fmac_f32_e32 v205, v1, v177
	v_fmac_f32_e32 v206, v2, v178
	v_fmac_f32_e32 v207, v3, v179
	v_mul_f32_e32 v208, 0xbfb8aa3b, v200
	v_mul_f32_e32 v209, 0xbfb8aa3b, v201
	v_mul_f32_e32 v210, 0xbfb8aa3b, v202
	v_mul_f32_e32 v211, 0xbfb8aa3b, v203
	v_exp_f32_e32 v208, v208
	v_exp_f32_e32 v209, v209
	v_exp_f32_e32 v210, v210
	v_exp_f32_e32 v211, v211
	v_add_f32_e32 v208, 1.0, v208
	v_add_f32_e32 v209, 1.0, v209
	v_add_f32_e32 v210, 1.0, v210
	v_add_f32_e32 v211, 1.0, v211
	v_rcp_f32_e32 v208, v208
	v_rcp_f32_e32 v209, v209
	v_rcp_f32_e32 v210, v210
	v_rcp_f32_e32 v211, v211
	v_mul_f32_e32 v200, v200, v208
	v_mul_f32_e32 v201, v201, v209
	v_mul_f32_e32 v202, v202, v210
	v_mul_f32_e32 v203, v203, v211
	v_mul_f32_e32 v200, v200, v204
	v_mul_f32_e32 v201, v201, v205
	v_mul_f32_e32 v202, v202, v206
	v_mul_f32_e32 v203, v203, v207
	v_cvt_pk_bf16_f32 v34, v200, v201
	v_cvt_pk_bf16_f32 v35, v202, v203
	v_fma_f32 v200, v132, v8, v140
	v_fma_f32 v201, v133, v9, v141
	v_fma_f32 v202, v134, v10, v142
	v_fma_f32 v203, v135, v11, v143
	v_fmac_f32_e32 v200, v24, v128
	v_fmac_f32_e32 v201, v25, v129
	v_fmac_f32_e32 v202, v26, v130
	v_fmac_f32_e32 v203, v27, v131
	v_fmac_f32_dpp v200, v56, v136 row_shl:1 row_mask:0xf bank_mask:0xf
	v_fmac_f32_dpp v201, v57, v137 row_shl:1 row_mask:0xf bank_mask:0xf
	v_fmac_f32_dpp v202, v58, v138 row_shl:1 row_mask:0xf bank_mask:0xf
	v_fmac_f32_dpp v203, v59, v139 row_shl:1 row_mask:0xf bank_mask:0xf
	v_fmac_f32_e32 v200, v192, v220
	v_fmac_f32_e32 v201, v193, v221
	v_fmac_f32_e32 v202, v194, v222
	v_fmac_f32_e32 v203, v195, v223
	v_fma_f32 v204, v172, v0, v180
	v_fma_f32 v205, v173, v1, v181
	v_fma_f32 v206, v174, v2, v182
	v_fma_f32 v207, v175, v3, v183
	v_fmac_f32_e32 v204, v12, v160
	v_fmac_f32_e32 v205, v13, v161
	v_fmac_f32_e32 v206, v14, v162
	v_fmac_f32_e32 v207, v15, v163
	v_fmac_f32_dpp v204, v44, v176 row_shl:1 row_mask:0xf bank_mask:0xf
	v_fmac_f32_dpp v205, v45, v177 row_shl:1 row_mask:0xf bank_mask:0xf
	v_fmac_f32_dpp v206, v46, v178 row_shl:1 row_mask:0xf bank_mask:0xf
	v_fmac_f32_dpp v207, v47, v179 row_shl:1 row_mask:0xf bank_mask:0xf
	v_fmac_f32_e32 v204, v196, v232
	v_fmac_f32_e32 v205, v197, v233
	v_fmac_f32_e32 v206, v198, v234
	v_fmac_f32_e32 v207, v199, v235
	s_mov_b64 exec, s[54:55]
	v_add_u32_e32 v250, 0x10800, v252
	global_store_dwordx4 v250, v[200:203], s[56:57] offset:16
	v_add_u32_e32 v250, 0x13400, v252
	global_store_dwordx4 v250, v[204:207], s[56:57] offset:16
	s_mov_b64 exec, -1
	s_nop 4
	v_mul_f32_e32 v208, 0xbfb8aa3b, v200
	v_mul_f32_e32 v209, 0xbfb8aa3b, v201
	v_mul_f32_e32 v210, 0xbfb8aa3b, v202
	v_mul_f32_e32 v211, 0xbfb8aa3b, v203
	v_exp_f32_e32 v208, v208
	v_exp_f32_e32 v209, v209
	v_exp_f32_e32 v210, v210
	v_exp_f32_e32 v211, v211
	v_add_f32_e32 v208, 1.0, v208
	v_add_f32_e32 v209, 1.0, v209
	v_add_f32_e32 v210, 1.0, v210
	v_add_f32_e32 v211, 1.0, v211
	v_rcp_f32_e32 v208, v208
	v_rcp_f32_e32 v209, v209
	v_rcp_f32_e32 v210, v210
	v_rcp_f32_e32 v211, v211
	v_mul_f32_e32 v200, v200, v208
	v_mul_f32_e32 v201, v201, v209
	v_mul_f32_e32 v202, v202, v210
	v_mul_f32_e32 v203, v203, v211
	v_mul_f32_e32 v200, v200, v204
	v_mul_f32_e32 v201, v201, v205
	v_mul_f32_e32 v202, v202, v206
	v_mul_f32_e32 v203, v203, v207
	v_cvt_pk_bf16_f32 v18, v200, v201
	v_cvt_pk_bf16_f32 v19, v202, v203
	global_store_dwordx4 v171, v[124:127], s[30:31]
	v_add_u32_e32 v250, 0x1600, v171
	global_store_dwordx4 v250, v[116:119], s[30:31]
	s_nop 0
	v_add_u32_e32 v250, 0x2c00, v171
	global_store_dwordx4 v250, v[96:99], s[30:31]
	s_nop 0
	v_add_u32_e32 v250, 0x4200, v171
	global_store_dwordx4 v250, v[80:83], s[30:31]
	s_nop 0
	v_add_u32_e32 v250, 0xb0000, v171
	global_store_dwordx4 v250, v[60:63], s[30:31]
	s_nop 0
	v_add_u32_e32 v250, 0xb1600, v171
	global_store_dwordx4 v250, v[48:51], s[30:31]
	s_nop 0
	v_add_u32_e32 v250, 0xb2c00, v171
	global_store_dwordx4 v250, v[32:35], s[30:31]
	s_nop 0
	v_add_u32_e32 v250, 0xb4200, v171
	global_store_dwordx4 v250, v[16:19], s[30:31]
	s_nop 0
	s_and_b64 s[34:35], s[4:5], exec
	s_cbranch_scc0 .LepC_nonext
	s_xor_b32 s101, s101, 1
	s_or_b32 s101, s101, 2
	s_and_b32 s32, s101, 1
	s_mulk_i32 s32, 0x1800
	s_add_i32 s32, s32, 0x22c00
	v_readfirstlane_b32 s79, v230
	s_cmp_lt_u32 s79, 64
	s_cbranch_scc0 .LepC_nfe
	s_add_i32 s30, s24, 0
	s_ashr_i32 s30, s30, 2
	s_add_i32 s30, s30, 1
	s_cmp_gt_i32 s24, -1
	s_cselect_b32 s30, s30, 0
	s_mul_hi_i32 s31, s30, 0x5800
	s_mulk_i32 s30, 0x5800
	s_add_u32 s30, s33, s30
	s_addc_u32 s31, s50, s31
	v_readlane_b32 s34, v254, 5
	v_readlane_b32 s35, v254, 6
	v_readlane_b32 s36, v254, 7
	v_readlane_b32 s37, v254, 8
	s_nop 0
	s_add_u32 s34, s34, 0x10800
	s_addc_u32 s35, s35, 0
	s_add_u32 s36, s36, 0x5800
	s_addc_u32 s37, s37, 0
	v_and_b32_e32 v238, 63, v230
	v_lshrrev_b32_e32 v239, 5, v238
	v_and_b32_e32 v240, 31, v238
	v_lshlrev_b32_e32 v240, 4, v240
	s_lshl_b32 s79, s22, 9
	v_add_u32_e32 v240, s79, v240
	v_mul_u32_u24_e32 v241, 0x2c00, v239
	v_mul_u32_u24_e32 v242, 0x5800, v239
	v_add_u32_e32 v241, v241, v240
	v_add_u32_e32 v242, v242, v240
	v_lshlrev_b32_e32 v243, 4, v238
	s_lshl_b32 s79, s24, 10
	v_add_u32_e32 v243, s79, v243
	s_mov_b32 m0, s32
	s_nop 0
	global_load_lds_dwordx4 v243, s[10:11]
	s_add_i32 m0, s32, 1024
	s_nop 0
	global_load_lds_dwordx4 v241, s[30:31]
	s_add_i32 m0, s32, 2048
	s_nop 0
	global_load_lds_dwordx4 v242, s[34:35]
	v_add_u32_e32 v243, 0x2c00, v242
	s_add_i32 m0, s32, 3072
	s_nop 0
	global_load_lds_dwordx4 v243, s[34:35]
	v_add_u32_e32 v243, 0xb000, v241
	s_add_i32 m0, s32, 4096
	s_nop 0
	global_load_lds_dwordx4 v243, s[34:35]
	s_add_i32 m0, s32, 5120
	s_nop 0
	global_load_lds_dwordx4 v241, s[36:37]
.LepC_nfe:
.LepC_nonext:
	s_mov_b64 s[6:7], -1
	s_and_b64 vcc, exec, s[4:5]
	s_cbranch_vccz .LBB0_1873
	s_andn2_b64 vcc, exec, s[8:9]
	s_cbranch_vccnz .LBB0_1872
	s_barrier
	s_branch .LBB0_1872

	.amdhsa_kernel _Z6mk_fwd6Params
		.amdhsa_group_segment_fixed_size 22528
		.amdhsa_private_segment_fixed_size 0
		.amdhsa_kernarg_size 512
		.amdhsa_user_sgpr_count 2
		.amdhsa_user_sgpr_dispatch_ptr 0
		.amdhsa_user_sgpr_queue_ptr 0
		.amdhsa_user_sgpr_kernarg_segment_ptr 1
		.amdhsa_user_sgpr_dispatch_id 0
		.amdhsa_user_sgpr_kernarg_preload_length 0
		.amdhsa_user_sgpr_kernarg_preload_offset 0
		.amdhsa_user_sgpr_private_segment_size 0
		.amdhsa_uses_dynamic_stack 0
		.amdhsa_enable_private_segment 0
		.amdhsa_system_sgpr_workgroup_id_x 1
		.amdhsa_system_sgpr_workgroup_id_y 0
		.amdhsa_system_sgpr_workgroup_id_z 0
		.amdhsa_system_sgpr_workgroup_info 0
		.amdhsa_system_vgpr_workitem_id 2
		.amdhsa_next_free_vgpr 256
		.amdhsa_next_free_sgpr 102
		.amdhsa_accum_offset 256
		.amdhsa_reserve_vcc 1
		.amdhsa_float_round_mode_32 0
		.amdhsa_float_round_mode_16_64 0
		.amdhsa_float_denorm_mode_32 3
		.amdhsa_float_denorm_mode_16_64 3
		.amdhsa_dx10_clamp 1
		.amdhsa_ieee_mode 1
		.amdhsa_fp16_overflow 0
		.amdhsa_tg_split 0
		.amdhsa_exception_fp_ieee_invalid_op 0
		.amdhsa_exception_fp_denorm_src 0
		.amdhsa_exception_fp_ieee_div_zero 0
		.amdhsa_exception_fp_ieee_overflow 0
		.amdhsa_exception_fp_ieee_underflow 0
		.amdhsa_exception_fp_ieee_inexact 0
		.amdhsa_exception_int_div_zero 0
	.end_amdhsa_kernel

amdhsa.kernels:
  - .agpr_count:     0
    .args:
      - .offset:         0
        .size:           256
        .value_kind:     by_value
      - .offset:         256
        .size:           4
        .value_kind:     hidden_block_count_x
      - .offset:         260
        .size:           4
        .value_kind:     hidden_block_count_y
      - .offset:         264
        .size:           4
        .value_kind:     hidden_block_count_z
      - .offset:         268
        .size:           2
        .value_kind:     hidden_group_size_x
      - .offset:         270
        .size:           2
        .value_kind:     hidden_group_size_y
      - .offset:         272
        .size:           2
        .value_kind:     hidden_group_size_z
      - .offset:         274
        .size:           2
        .value_kind:     hidden_remainder_x
      - .offset:         276
        .size:           2
        .value_kind:     hidden_remainder_y
      - .offset:         278
        .size:           2
        .value_kind:     hidden_remainder_z
      - .offset:         296
        .size:           8
        .value_kind:     hidden_global_offset_x
      - .offset:         304
        .size:           8
        .value_kind:     hidden_global_offset_y
      - .offset:         312
        .size:           8
        .value_kind:     hidden_global_offset_z
      - .offset:         320
        .size:           2
        .value_kind:     hidden_grid_dims
      - .offset:         344
        .size:           8
        .value_kind:     hidden_multigrid_sync_arg
      - .offset:         376
        .size:           4
        .value_kind:     hidden_dynamic_lds_size
    .group_segment_fixed_size: 22528
    .kernarg_segment_align: 8
    .kernarg_segment_size: 512
    .language:       OpenCL C
    .language_version:
      - 2
      - 0
    .max_flat_workgroup_size: 512
    .name:           _Z6mk_fwd6Params
    .private_segment_fixed_size: 0
    .sgpr_count:     108
    .sgpr_spill_count: 80
    .symbol:         _Z6mk_fwd6Params.kd
    .uniform_work_group_size: 1
    .uses_dynamic_stack: false
    .vgpr_count:     256
    .vgpr_spill_count: 0
    .wavefront_size: 64
